# gemm K-loops: counter / pointer-advance / exit-test SALU moved from behind the last MFMA block to the end of the preceding load segment (back-edge work out of the compute segment)
# baseline (speedup 1.0000x reference)
; #define PG8_STAGE(bufoff, gbase, voff) do { _Pragma("unroll") for (int _i = 0; _i < 2; ++_i) \
;         __builtin_amdgcn_global_load_lds((const unsigned*)((const char*)(gbase) + (voff)[_i]), (PG8_LAS unsigned*)(lds + (bufoff) + ldsw + _i * 8192), 16, 0, 0); } while (0)
; #define PG8_LDA(dst, b, h) do { _Pragma("unroll") for (int m = 0; m < 4; ++m) _Pragma("unroll") for (int k = 0; k < 2; ++k) dst[m][k] = *(const PG8_LAS bf16x8*)(lds + PG8_SA(b, h) + aoff + m * 2048 + k * 1024); } while (0)
; #define PG8_LDB(dst, b, h) do { _Pragma("unroll") for (int n = 0; n < 2; ++n) _Pragma("unroll") for (int k = 0; k < 2; ++k) dst[n][k] = *(const PG8_LAS bf16x8*)(lds + PG8_SB(b, h) + boff + n * 2048 + k * 1024); } while (0)
; #define PG8_WAIT_L(n) asm volatile("s_waitcnt lgkmcnt(" #n ")" ::: "memory")
; #define PG8_BAR __builtin_amdgcn_s_barrier()
; #define PG8_SCHED __builtin_amdgcn_sched_barrier(0)
; template <class Epi, class Sched>
; __device__ __forceinline__ void gemm_phase(PG8_LAS unsigned char* lds, const Gemm g, const Sched& S, const Epi& E) {
;     ...
;         const bool has_next = S.next(ui + 1, nxt);
;         const char* nA = has_next ? (const char*)g.A + (size_t)nxt.pm * tstepA + (size_t)nxt.kc * cstep : cA; const char* nB = has_next ? (const char*)g.Bt + (size_t)nxt.pn * tstep + (size_t)nxt.kc * cstep : cB;
;         for (int t = 0; t < nt; t += 2) {
;             const bool last = (t == nt - 2);
;             const char* a1 = cA + (size_t)(t + 1) * kstep;
;             const char* a2 = last ? nA : cA + (size_t)(t + 2) * kstep; const char* b2 = last ? nB : cB + (size_t)(t + 2) * kstep;
;             const char* a3 = a2 + kstep; const char* b3 = b2 + kstep;
;             if (last && has_next) S.a_ready(nxt);
;             PG8_LDB(B0, 0, 0); PG8_SCHED; PG8_LDA(At, 0, 0); PG8_STAGE(PG8_SA(1, 1), a1 + hstep, voffA);
;             PG8_WAIT_L(8); PG8_BAR; PG8_WAIT_L(0); PG8_MMA(0, 0, At, B0); PG8_BAR; PG8_SCHED;
;             PG8_LDB(B1, 0, 1); PG8_STAGE(PG8_SB(0, 0), b2, voffB);
;             PG8_BAR; PG8_WAIT_L(0); PG8_MMA(0, 1, At, B1); PG8_BAR;
;             PG8_LDA(At, 0, 1); PG8_STAGE(PG8_SA(0, 0), a2, voffA);
;             PG8_BAR; PG8_WAIT_L(0); PG8_MMA(1, 0, At, B0); PG8_BAR; PG8_SCHED;
.LBB0_267:
	s_add_u32 s16, s16, 0x80
	s_addc_u32 s17, s17, 0
	s_add_u32 s24, s20, 0x100
	s_addc_u32 s25, s21, 0
	s_mov_b32 s20, 0
	s_add_i32 s42, s20, 2
	s_add_u32 s22, s16, 0x80
	s_addc_u32 s21, s17, 0
	s_add_i32 s43, 0, 0x10000
	v_add_u32_e32 v142, s43, v170
	ds_read_b128 v[130:133], v142
	ds_read_b128 v[134:137], v142 offset:1024
	ds_read_b128 v[138:141], v142 offset:2048
	ds_read_b128 v[142:145], v142 offset:3072
	s_cmp_eq_u32 s66, s20
	s_cselect_b32 s20, s2, s22
	s_cselect_b32 s21, s3, s21
	s_cselect_b32 s23, s13, s25
	s_cselect_b32 s22, s12, s24
	v_lshl_add_u64 v[168:169], s[16:17], 0, v[164:165]
	s_add_i32 m0, s36, 0xc000
	ds_read_b128 v[176:179], v172
	ds_read_b128 v[180:183], v172 offset:1024
	ds_read_b128 v[184:187], v172 offset:2048
	ds_read_b128 v[188:191], v172 offset:3072
	ds_read_b128 v[192:195], v172 offset:4096
	ds_read_b128 v[196:199], v172 offset:5120
	ds_read_b128 v[200:203], v172 offset:6144
	ds_read_b128 v[204:207], v172 offset:7168
	global_load_lds_dwordx4 v[168:169], off
	v_lshl_add_u64 v[168:169], s[16:17], 0, v[166:167]
	s_add_i32 m0, s36, 0xe000
	s_nop 0
	global_load_lds_dwordx4 v[168:169], off
	s_waitcnt lgkmcnt(8)
	s_barrier
	s_waitcnt lgkmcnt(7)
	v_mfma_f32_16x16x32_bf16 v[126:129], v[130:133], v[176:179], 0
	v_mfma_f32_16x16x32_bf16 v[122:125], v[138:141], v[176:179], 0
	s_waitcnt lgkmcnt(5)
	v_mfma_f32_16x16x32_bf16 v[114:117], v[130:133], v[184:187], 0
	v_mfma_f32_16x16x32_bf16 v[110:113], v[138:141], v[184:187], 0
	s_waitcnt lgkmcnt(3)
	v_mfma_f32_16x16x32_bf16 v[98:101], v[130:133], v[192:195], 0
	v_mfma_f32_16x16x32_bf16 v[94:97], v[138:141], v[192:195], 0
	s_waitcnt lgkmcnt(1)
	v_mfma_f32_16x16x32_bf16 v[82:85], v[130:133], v[200:203], 0
	v_mfma_f32_16x16x32_bf16 v[78:81], v[138:141], v[200:203], 0
	v_mfma_f32_16x16x32_bf16 v[126:129], v[134:137], v[180:183], v[126:129]
	v_mfma_f32_16x16x32_bf16 v[122:125], v[142:145], v[180:183], v[122:125]
	v_mfma_f32_16x16x32_bf16 v[114:117], v[134:137], v[188:191], v[114:117]
	v_mfma_f32_16x16x32_bf16 v[110:113], v[142:145], v[188:191], v[110:113]
	v_mfma_f32_16x16x32_bf16 v[98:101], v[134:137], v[196:199], v[98:101]
	v_mfma_f32_16x16x32_bf16 v[94:97], v[142:145], v[196:199], v[94:97]
	s_waitcnt lgkmcnt(0)
	v_mfma_f32_16x16x32_bf16 v[82:85], v[134:137], v[204:207], v[82:85]
	v_mfma_f32_16x16x32_bf16 v[78:81], v[142:145], v[204:207], v[78:81]
	s_barrier
	s_add_i32 s44, 0, 0x14000
	v_add_u32_e32 v168, s44, v170
	s_add_i32 s43, s43, s35
	ds_read_b128 v[208:211], v168
	ds_read_b128 v[212:215], v168 offset:1024
	ds_read_b128 v[216:219], v168 offset:2048
	ds_read_b128 v[234:237], v168 offset:3072
	v_lshl_add_u64 v[168:169], s[22:23], 0, v[48:49]
	s_mov_b32 m0, s43
	v_lshl_add_u64 v[224:225], s[22:23], 0, v[146:147]
	global_load_lds_dwordx4 v[168:169], off
	s_add_i32 m0, s43, 0x2000
	s_nop 0
	global_load_lds_dwordx4 v[224:225], off
	s_barrier
	s_waitcnt lgkmcnt(3)
	v_mfma_f32_16x16x32_bf16 v[118:121], v[208:211], v[176:179], 0
	s_waitcnt lgkmcnt(1)
	v_mfma_f32_16x16x32_bf16 v[106:109], v[216:219], v[176:179], 0
	v_mfma_f32_16x16x32_bf16 v[102:105], v[208:211], v[184:187], 0
	v_mfma_f32_16x16x32_bf16 v[90:93], v[216:219], v[184:187], 0
	v_mfma_f32_16x16x32_bf16 v[86:89], v[208:211], v[192:195], 0
	v_mfma_f32_16x16x32_bf16 v[74:77], v[216:219], v[192:195], 0
	v_mfma_f32_16x16x32_bf16 v[70:73], v[208:211], v[200:203], 0
	v_mfma_f32_16x16x32_bf16 v[66:69], v[216:219], v[200:203], 0
	v_mfma_f32_16x16x32_bf16 v[118:121], v[212:215], v[180:183], v[118:121]
	s_waitcnt lgkmcnt(0)
	v_mfma_f32_16x16x32_bf16 v[106:109], v[234:237], v[180:183], v[106:109]
	v_mfma_f32_16x16x32_bf16 v[102:105], v[212:215], v[188:191], v[102:105]
	v_mfma_f32_16x16x32_bf16 v[90:93], v[234:237], v[188:191], v[90:93]
	v_mfma_f32_16x16x32_bf16 v[86:89], v[212:215], v[196:199], v[86:89]
	v_mfma_f32_16x16x32_bf16 v[74:77], v[234:237], v[196:199], v[74:77]
	v_mfma_f32_16x16x32_bf16 v[70:73], v[212:215], v[204:207], v[70:73]
	v_mfma_f32_16x16x32_bf16 v[66:69], v[234:237], v[204:207], v[66:69]
	s_mov_b32 m0, s36
	v_lshl_add_u64 v[228:229], s[20:21], 0, v[48:49]
	s_barrier
	ds_read_b128 v[176:179], v172 offset:16384
	ds_read_b128 v[180:183], v172 offset:17408
	ds_read_b128 v[184:187], v172 offset:18432
	ds_read_b128 v[188:191], v172 offset:19456
	ds_read_b128 v[192:195], v172 offset:20480
	ds_read_b128 v[196:199], v172 offset:21504
	ds_read_b128 v[200:203], v172 offset:22528
	ds_read_b128 v[204:207], v172 offset:23552
	global_load_lds_dwordx4 v[228:229], off
	v_lshl_add_u64 v[238:239], s[20:21], 0, v[146:147]
	s_mov_b32 m0, s37
	s_nop 0
	global_load_lds_dwordx4 v[238:239], off
	s_barrier
	s_waitcnt lgkmcnt(7)
	v_mfma_f32_16x16x32_bf16 v[62:65], v[130:133], v[176:179], 0
	v_mfma_f32_16x16x32_bf16 v[58:61], v[138:141], v[176:179], 0
	s_waitcnt lgkmcnt(5)
	v_mfma_f32_16x16x32_bf16 v[50:53], v[130:133], v[184:187], 0
	v_mfma_f32_16x16x32_bf16 v[44:47], v[138:141], v[184:187], 0
	s_waitcnt lgkmcnt(3)
	v_mfma_f32_16x16x32_bf16 v[32:35], v[130:133], v[192:195], 0
	v_mfma_f32_16x16x32_bf16 v[28:31], v[138:141], v[192:195], 0
	s_waitcnt lgkmcnt(1)
	v_mfma_f32_16x16x32_bf16 v[16:19], v[130:133], v[200:203], 0
	v_mfma_f32_16x16x32_bf16 v[12:15], v[138:141], v[200:203], 0
	v_mfma_f32_16x16x32_bf16 v[62:65], v[134:137], v[180:183], v[62:65]
	v_mfma_f32_16x16x32_bf16 v[58:61], v[142:145], v[180:183], v[58:61]
	v_mfma_f32_16x16x32_bf16 v[50:53], v[134:137], v[188:191], v[50:53]
	v_mfma_f32_16x16x32_bf16 v[44:47], v[142:145], v[188:191], v[44:47]
	v_mfma_f32_16x16x32_bf16 v[32:35], v[134:137], v[196:199], v[32:35]
	v_mfma_f32_16x16x32_bf16 v[28:31], v[142:145], v[196:199], v[28:31]
	s_waitcnt lgkmcnt(0)
	v_mfma_f32_16x16x32_bf16 v[16:19], v[134:137], v[204:207], v[16:19]
	v_mfma_f32_16x16x32_bf16 v[12:15], v[142:145], v[204:207], v[12:15]
	s_barrier
; #define PG8_STAGE(bufoff, gbase, voff) do { _Pragma("unroll") for (int _i = 0; _i < 2; ++_i) \
;         __builtin_amdgcn_global_load_lds((const unsigned*)((const char*)(gbase) + (voff)[_i]), (PG8_LAS unsigned*)(lds + (bufoff) + ldsw + _i * 8192), 16, 0, 0); } while (0)
; #define PG8_LDA(dst, b, h) do { _Pragma("unroll") for (int m = 0; m < 4; ++m) _Pragma("unroll") for (int k = 0; k < 2; ++k) dst[m][k] = *(const PG8_LAS bf16x8*)(lds + PG8_SA(b, h) + aoff + m * 2048 + k * 1024); } while (0)
; #define PG8_LDB(dst, b, h) do { _Pragma("unroll") for (int n = 0; n < 2; ++n) _Pragma("unroll") for (int k = 0; k < 2; ++k) dst[n][k] = *(const PG8_LAS bf16x8*)(lds + PG8_SB(b, h) + boff + n * 2048 + k * 1024); } while (0)
; #define PG8_MMA(ai, bj, At, Bt) do { __builtin_amdgcn_s_setprio(1); _Pragma("unroll") for (int m = 0; m < 4; ++m) _Pragma("unroll") for (int n = 0; n < 2; ++n) _Pragma("unroll") for (int k = 0; k < 2; ++k) \
;         acc[ai][bj][m][n] = __builtin_amdgcn_mfma_f32_16x16x32_bf16(Bt[n][k], At[m][k], acc[ai][bj][m][n], 0, 0, 0); __builtin_amdgcn_s_setprio(0); } while (0)
; #define PG8_WAIT_V(n) asm volatile("s_waitcnt vmcnt(" #n ")" ::: "memory")
; #define PG8_WAIT_L(n) asm volatile("s_waitcnt lgkmcnt(" #n ")" ::: "memory")
; #define PG8_BAR __builtin_amdgcn_s_barrier()
; #define PG8_SCHED __builtin_amdgcn_sched_barrier(0)
; template <class Epi, class Sched>
; __device__ __forceinline__ void gemm_phase(PG8_LAS unsigned char* lds, const Gemm g, const Sched& S, const Epi& E) {
;     ...
;             PG8_STAGE(PG8_SB(0, 1), b2 + hstep, voffB);
;             PG8_WAIT_V(6); PG8_BAR; PG8_MMA(1, 1, At, B1); PG8_BAR;
;             PG8_LDB(B0, 1, 0); PG8_SCHED; PG8_LDA(At, 1, 0); PG8_STAGE(PG8_SA(0, 1), a2 + hstep, voffA);
;             PG8_WAIT_L(8); PG8_BAR; PG8_WAIT_L(0); PG8_MMA(0, 0, At, B0); PG8_BAR; PG8_SCHED;
;             PG8_LDB(B1, 1, 1); PG8_STAGE(PG8_SB(1, 0), b3, voffB);
;             PG8_BAR; PG8_WAIT_L(0); PG8_MMA(0, 1, At, B1); PG8_BAR;
;             PG8_LDA(At, 1, 1); PG8_STAGE(PG8_SA(1, 0), a3, voffA);
;             PG8_BAR; PG8_WAIT_L(0); PG8_MMA(1, 0, At, B0); PG8_BAR; PG8_SCHED;
	s_add_u32 s22, s22, s10
	s_addc_u32 s23, s23, 0
	s_add_i32 s43, s44, s35
	v_lshl_add_u64 v[240:241], s[22:23], 0, v[48:49]
	s_mov_b32 m0, s43
	v_lshl_add_u64 v[242:243], s[22:23], 0, v[146:147]
	global_load_lds_dwordx4 v[240:241], off
	s_add_i32 m0, s43, 0x2000
	s_nop 0
	global_load_lds_dwordx4 v[242:243], off
	s_waitcnt vmcnt(6)
	s_barrier
	v_mfma_f32_16x16x32_bf16 v[54:57], v[208:211], v[176:179], 0
	v_mfma_f32_16x16x32_bf16 v[40:43], v[216:219], v[176:179], 0
	v_mfma_f32_16x16x32_bf16 v[36:39], v[208:211], v[184:187], 0
	v_mfma_f32_16x16x32_bf16 v[24:27], v[216:219], v[184:187], 0
	v_mfma_f32_16x16x32_bf16 v[20:23], v[208:211], v[192:195], 0
	v_mfma_f32_16x16x32_bf16 v[8:11], v[216:219], v[192:195], 0
	v_mfma_f32_16x16x32_bf16 v[4:7], v[208:211], v[200:203], 0
	v_mfma_f32_16x16x32_bf16 v[0:3], v[216:219], v[200:203], 0
	v_mfma_f32_16x16x32_bf16 v[54:57], v[212:215], v[180:183], v[54:57]
	v_mfma_f32_16x16x32_bf16 v[40:43], v[234:237], v[180:183], v[40:43]
	v_mfma_f32_16x16x32_bf16 v[36:39], v[212:215], v[188:191], v[36:39]
	v_mfma_f32_16x16x32_bf16 v[24:27], v[234:237], v[188:191], v[24:27]
	v_mfma_f32_16x16x32_bf16 v[20:23], v[212:215], v[196:199], v[20:23]
	v_mfma_f32_16x16x32_bf16 v[8:11], v[234:237], v[196:199], v[8:11]
	v_mfma_f32_16x16x32_bf16 v[4:7], v[212:215], v[204:207], v[4:7]
	v_mfma_f32_16x16x32_bf16 v[0:3], v[234:237], v[204:207], v[0:3]
	s_add_i32 s22, 0, 0x18000
	v_add_u32_e32 v142, s22, v170
	s_barrier
	ds_read_b128 v[130:133], v142
	ds_read_b128 v[134:137], v142 offset:1024
	ds_read_b128 v[138:141], v142 offset:2048
	ds_read_b128 v[142:145], v142 offset:3072
	s_add_u32 s20, s20, s10
	s_addc_u32 s21, s21, 0
	s_mov_b32 m0, s38
	v_lshl_add_u64 v[208:209], s[20:21], 0, v[48:49]
	ds_read_b128 v[176:179], v172 offset:32768
	ds_read_b128 v[180:183], v172 offset:33792
	ds_read_b128 v[184:187], v172 offset:34816
	ds_read_b128 v[188:191], v172 offset:35840
	ds_read_b128 v[192:195], v172 offset:36864
	ds_read_b128 v[196:199], v172 offset:37888
	ds_read_b128 v[200:203], v172 offset:38912
	ds_read_b128 v[204:207], v172 offset:39936
	global_load_lds_dwordx4 v[208:209], off
	v_lshl_add_u64 v[208:209], s[20:21], 0, v[146:147]
	s_mov_b32 m0, s39
	s_nop 0
	global_load_lds_dwordx4 v[208:209], off
	s_waitcnt lgkmcnt(8)
	s_barrier
	s_waitcnt lgkmcnt(7)
	v_mfma_f32_16x16x32_bf16 v[126:129], v[130:133], v[176:179], v[126:129]
	v_mfma_f32_16x16x32_bf16 v[122:125], v[138:141], v[176:179], v[122:125]
	s_waitcnt lgkmcnt(5)
	v_mfma_f32_16x16x32_bf16 v[114:117], v[130:133], v[184:187], v[114:117]
	v_mfma_f32_16x16x32_bf16 v[110:113], v[138:141], v[184:187], v[110:113]
	s_waitcnt lgkmcnt(3)
	v_mfma_f32_16x16x32_bf16 v[98:101], v[130:133], v[192:195], v[98:101]
	v_mfma_f32_16x16x32_bf16 v[94:97], v[138:141], v[192:195], v[94:97]
	s_waitcnt lgkmcnt(1)
	v_mfma_f32_16x16x32_bf16 v[82:85], v[130:133], v[200:203], v[82:85]
	v_mfma_f32_16x16x32_bf16 v[78:81], v[138:141], v[200:203], v[78:81]
	v_mfma_f32_16x16x32_bf16 v[126:129], v[134:137], v[180:183], v[126:129]
	v_mfma_f32_16x16x32_bf16 v[122:125], v[142:145], v[180:183], v[122:125]
	v_mfma_f32_16x16x32_bf16 v[114:117], v[134:137], v[188:191], v[114:117]
	v_mfma_f32_16x16x32_bf16 v[110:113], v[142:145], v[188:191], v[110:113]
	v_mfma_f32_16x16x32_bf16 v[98:101], v[134:137], v[196:199], v[98:101]
	v_mfma_f32_16x16x32_bf16 v[94:97], v[142:145], v[196:199], v[94:97]
	s_waitcnt lgkmcnt(0)
	v_mfma_f32_16x16x32_bf16 v[82:85], v[134:137], v[204:207], v[82:85]
	v_mfma_f32_16x16x32_bf16 v[78:81], v[142:145], v[204:207], v[78:81]
	s_barrier
	s_add_i32 s20, 0, 0x1c000
	s_add_i32 s21, s22, s35
	v_add_u32_e32 v173, s20, v170
	v_lshl_add_u64 v[168:169], v[168:169], 0, s[0:1]
	s_mov_b32 m0, s21
	ds_read_b128 v[208:211], v173
	ds_read_b128 v[212:215], v173 offset:1024
	ds_read_b128 v[216:219], v173 offset:2048
	ds_read_b128 v[234:237], v173 offset:3072
	global_load_lds_dwordx4 v[168:169], off
	v_lshl_add_u64 v[168:169], v[224:225], 0, s[0:1]
	s_add_i32 m0, s21, 0x2000
	s_nop 0
	global_load_lds_dwordx4 v[168:169], off
	s_barrier
	s_waitcnt lgkmcnt(3)
	v_mfma_f32_16x16x32_bf16 v[118:121], v[208:211], v[176:179], v[118:121]
	s_waitcnt lgkmcnt(1)
	v_mfma_f32_16x16x32_bf16 v[106:109], v[216:219], v[176:179], v[106:109]
	v_mfma_f32_16x16x32_bf16 v[102:105], v[208:211], v[184:187], v[102:105]
	v_mfma_f32_16x16x32_bf16 v[90:93], v[216:219], v[184:187], v[90:93]
	v_mfma_f32_16x16x32_bf16 v[86:89], v[208:211], v[192:195], v[86:89]
	v_mfma_f32_16x16x32_bf16 v[74:77], v[216:219], v[192:195], v[74:77]
	v_mfma_f32_16x16x32_bf16 v[70:73], v[208:211], v[200:203], v[70:73]
	v_mfma_f32_16x16x32_bf16 v[66:69], v[216:219], v[200:203], v[66:69]
	v_mfma_f32_16x16x32_bf16 v[118:121], v[212:215], v[180:183], v[118:121]
	s_waitcnt lgkmcnt(0)
	v_mfma_f32_16x16x32_bf16 v[106:109], v[234:237], v[180:183], v[106:109]
	v_mfma_f32_16x16x32_bf16 v[102:105], v[212:215], v[188:191], v[102:105]
	v_mfma_f32_16x16x32_bf16 v[90:93], v[234:237], v[188:191], v[90:93]
	v_mfma_f32_16x16x32_bf16 v[86:89], v[212:215], v[196:199], v[86:89]
	v_mfma_f32_16x16x32_bf16 v[74:77], v[234:237], v[196:199], v[74:77]
	v_mfma_f32_16x16x32_bf16 v[70:73], v[212:215], v[204:207], v[70:73]
	v_mfma_f32_16x16x32_bf16 v[66:69], v[234:237], v[204:207], v[66:69]
	s_mov_b32 m0, s64
	v_lshl_add_u64 v[168:169], v[228:229], 0, s[0:1]
	s_barrier
	ds_read_b128 v[176:179], v172 offset:49152
	ds_read_b128 v[180:183], v172 offset:50176
	ds_read_b128 v[184:187], v172 offset:51200
	ds_read_b128 v[188:191], v172 offset:52224
	ds_read_b128 v[192:195], v172 offset:53248
	ds_read_b128 v[196:199], v172 offset:54272
	ds_read_b128 v[200:203], v172 offset:55296
	ds_read_b128 v[204:207], v172 offset:56320
	global_load_lds_dwordx4 v[168:169], off
	v_lshl_add_u64 v[168:169], v[238:239], 0, s[0:1]
	s_mov_b32 m0, s65
	s_nop 0
	global_load_lds_dwordx4 v[168:169], off
	s_barrier
; #define PG8_STAGE(bufoff, gbase, voff) do { _Pragma("unroll") for (int _i = 0; _i < 2; ++_i) \
;         __builtin_amdgcn_global_load_lds((const unsigned*)((const char*)(gbase) + (voff)[_i]), (PG8_LAS unsigned*)(lds + (bufoff) + ldsw + _i * 8192), 16, 0, 0); } while (0)
; #define PG8_LDA(dst, b, h) do { _Pragma("unroll") for (int m = 0; m < 4; ++m) _Pragma("unroll") for (int k = 0; k < 2; ++k) dst[m][k] = *(const PG8_LAS bf16x8*)(lds + PG8_SA(b, h) + aoff + m * 2048 + k * 1024); } while (0)
; #define PG8_WAIT_V(n) asm volatile("s_waitcnt vmcnt(" #n ")" ::: "memory")
; template <class Epi, class Sched>
; __device__ __forceinline__ void gemm_phase(PG8_LAS unsigned char* lds, const Gemm g, const Sched& S, const Epi& E) {
;     ...
;         for (int t = 0; t < nt; t += 2) {
;             const bool last = (t == nt - 2);
;             const char* a1 = cA + (size_t)(t + 1) * kstep;
;             const char* a2 = last ? nA : cA + (size_t)(t + 2) * kstep; const char* b2 = last ? nB : cB + (size_t)(t + 2) * kstep;
;             const char* a3 = a2 + kstep; const char* b3 = b2 + kstep;
;             if (last && has_next) S.a_ready(nxt);
;             PG8_LDB(B0, 0, 0); PG8_SCHED; PG8_LDA(At, 0, 0); PG8_STAGE(PG8_SA(1, 1), a1 + hstep, voffA);
;             PG8_WAIT_L(8); PG8_BAR; PG8_WAIT_L(0); PG8_MMA(0, 0, At, B0); PG8_BAR; PG8_SCHED;
;             PG8_LDB(B1, 0, 1); PG8_STAGE(PG8_SB(0, 0), b2, voffB);
;             PG8_BAR; PG8_WAIT_L(0); PG8_MMA(0, 1, At, B1); PG8_BAR;
;             PG8_LDA(At, 0, 1); PG8_STAGE(PG8_SA(0, 0), a2, voffA);
;             PG8_BAR; PG8_WAIT_L(0); PG8_MMA(1, 0, At, B0); PG8_BAR; PG8_SCHED;
;             PG8_STAGE(PG8_SB(0, 1), b2 + hstep, voffB);
;             PG8_WAIT_V(6); PG8_BAR; PG8_MMA(1, 1, At, B1); PG8_BAR;
;             PG8_LDB(B0, 1, 0); PG8_SCHED; PG8_LDA(At, 1, 0); PG8_STAGE(PG8_SA(0, 1), a2 + hstep, voffA);
;             PG8_WAIT_L(8); PG8_BAR; PG8_WAIT_L(0); PG8_MMA(0, 0, At, B0); PG8_BAR; PG8_SCHED;
;             PG8_LDB(B1, 1, 1); PG8_STAGE(PG8_SB(1, 0), b3, voffB);
;             PG8_BAR; PG8_WAIT_L(0); PG8_MMA(0, 1, At, B1); PG8_BAR;
;             PG8_LDA(At, 1, 1); PG8_STAGE(PG8_SA(1, 0), a3, voffA);
;             PG8_BAR; PG8_WAIT_L(0); PG8_MMA(1, 0, At, B0); PG8_BAR; PG8_SCHED;
;             PG8_STAGE(PG8_SB(1, 1), b3 + hstep, voffB);
;             PG8_WAIT_V(6); PG8_BAR; PG8_MMA(1, 1, At, B1); PG8_BAR;
	s_waitcnt lgkmcnt(7)
	v_mfma_f32_16x16x32_bf16 v[62:65], v[130:133], v[176:179], v[62:65]
	v_mfma_f32_16x16x32_bf16 v[58:61], v[138:141], v[176:179], v[58:61]
	s_waitcnt lgkmcnt(5)
	v_mfma_f32_16x16x32_bf16 v[50:53], v[130:133], v[184:187], v[50:53]
	v_mfma_f32_16x16x32_bf16 v[44:47], v[138:141], v[184:187], v[44:47]
	s_waitcnt lgkmcnt(3)
	v_mfma_f32_16x16x32_bf16 v[32:35], v[130:133], v[192:195], v[32:35]
	v_mfma_f32_16x16x32_bf16 v[28:31], v[138:141], v[192:195], v[28:31]
	s_waitcnt lgkmcnt(1)
	v_mfma_f32_16x16x32_bf16 v[16:19], v[130:133], v[200:203], v[16:19]
	v_mfma_f32_16x16x32_bf16 v[12:15], v[138:141], v[200:203], v[12:15]
	v_mfma_f32_16x16x32_bf16 v[62:65], v[134:137], v[180:183], v[62:65]
	v_mfma_f32_16x16x32_bf16 v[58:61], v[142:145], v[180:183], v[58:61]
	v_mfma_f32_16x16x32_bf16 v[50:53], v[134:137], v[188:191], v[50:53]
	v_mfma_f32_16x16x32_bf16 v[44:47], v[142:145], v[188:191], v[44:47]
	v_mfma_f32_16x16x32_bf16 v[32:35], v[134:137], v[196:199], v[32:35]
	v_mfma_f32_16x16x32_bf16 v[28:31], v[142:145], v[196:199], v[28:31]
	s_waitcnt lgkmcnt(0)
	v_mfma_f32_16x16x32_bf16 v[16:19], v[134:137], v[204:207], v[16:19]
	v_mfma_f32_16x16x32_bf16 v[12:15], v[142:145], v[204:207], v[12:15]
	s_barrier
	s_add_i32 s20, s20, s35
	v_lshl_add_u64 v[130:131], v[240:241], 0, s[0:1]
	s_mov_b32 m0, s20
	s_nop 0
	global_load_lds_dwordx4 v[130:131], off
	v_lshl_add_u64 v[130:131], v[242:243], 0, s[0:1]
	s_add_i32 m0, s20, 0x2000
	s_nop 0
	global_load_lds_dwordx4 v[130:131], off
	s_add_u32 s16, s16, 0x100
	s_addc_u32 s17, s17, 0
	s_add_u32 s24, s24, 0x100
	s_addc_u32 s25, s25, 0
	s_cmp_ge_u32 s42, s54
	s_mov_b32 s20, s42
	s_waitcnt vmcnt(6)
	s_barrier
	v_mfma_f32_16x16x32_bf16 v[54:57], v[208:211], v[176:179], v[54:57]
	v_mfma_f32_16x16x32_bf16 v[40:43], v[216:219], v[176:179], v[40:43]
	v_mfma_f32_16x16x32_bf16 v[36:39], v[208:211], v[184:187], v[36:39]
	v_mfma_f32_16x16x32_bf16 v[24:27], v[216:219], v[184:187], v[24:27]
	v_mfma_f32_16x16x32_bf16 v[20:23], v[208:211], v[192:195], v[20:23]
	v_mfma_f32_16x16x32_bf16 v[8:11], v[216:219], v[192:195], v[8:11]
	v_mfma_f32_16x16x32_bf16 v[4:7], v[208:211], v[200:203], v[4:7]
	v_mfma_f32_16x16x32_bf16 v[0:3], v[216:219], v[200:203], v[0:3]
	v_mfma_f32_16x16x32_bf16 v[54:57], v[212:215], v[180:183], v[54:57]
	v_mfma_f32_16x16x32_bf16 v[40:43], v[234:237], v[180:183], v[40:43]
	v_mfma_f32_16x16x32_bf16 v[36:39], v[212:215], v[188:191], v[36:39]
	v_mfma_f32_16x16x32_bf16 v[24:27], v[234:237], v[188:191], v[24:27]
	v_mfma_f32_16x16x32_bf16 v[20:23], v[212:215], v[196:199], v[20:23]
	v_mfma_f32_16x16x32_bf16 v[8:11], v[234:237], v[196:199], v[8:11]
	v_mfma_f32_16x16x32_bf16 v[4:7], v[212:215], v[204:207], v[4:7]
	v_mfma_f32_16x16x32_bf16 v[0:3], v[234:237], v[204:207], v[0:3]
	s_barrier
	s_cbranch_scc1 .Lkpeel_exit_268
.LBB0_268:
	s_add_i32 s42, s20, 2
	s_add_u32 s22, s16, 0x80
	s_addc_u32 s21, s17, 0
	s_add_i32 s43, 0, 0x10000
	v_add_u32_e32 v142, s43, v170
	ds_read_b128 v[130:133], v142
	ds_read_b128 v[134:137], v142 offset:1024
	ds_read_b128 v[138:141], v142 offset:2048
	ds_read_b128 v[142:145], v142 offset:3072
	s_cmp_eq_u32 s66, s20
	s_cselect_b32 s20, s2, s22
	s_cselect_b32 s21, s3, s21
	s_cselect_b32 s23, s13, s25
	s_cselect_b32 s22, s12, s24
	v_lshl_add_u64 v[168:169], s[16:17], 0, v[164:165]
	s_add_i32 m0, s36, 0xc000
	ds_read_b128 v[176:179], v172
	ds_read_b128 v[180:183], v172 offset:1024
	ds_read_b128 v[184:187], v172 offset:2048
	ds_read_b128 v[188:191], v172 offset:3072
	ds_read_b128 v[192:195], v172 offset:4096
	ds_read_b128 v[196:199], v172 offset:5120
	ds_read_b128 v[200:203], v172 offset:6144
	ds_read_b128 v[204:207], v172 offset:7168
	global_load_lds_dwordx4 v[168:169], off
	v_lshl_add_u64 v[168:169], s[16:17], 0, v[166:167]
	s_add_i32 m0, s36, 0xe000
	s_nop 0
	global_load_lds_dwordx4 v[168:169], off
	s_waitcnt lgkmcnt(8)
	s_barrier
	s_waitcnt lgkmcnt(7)
	v_mfma_f32_16x16x32_bf16 v[126:129], v[130:133], v[176:179], v[126:129]
	v_mfma_f32_16x16x32_bf16 v[122:125], v[138:141], v[176:179], v[122:125]
	s_waitcnt lgkmcnt(5)
	v_mfma_f32_16x16x32_bf16 v[114:117], v[130:133], v[184:187], v[114:117]
	v_mfma_f32_16x16x32_bf16 v[110:113], v[138:141], v[184:187], v[110:113]
	s_waitcnt lgkmcnt(3)
	v_mfma_f32_16x16x32_bf16 v[98:101], v[130:133], v[192:195], v[98:101]
	v_mfma_f32_16x16x32_bf16 v[94:97], v[138:141], v[192:195], v[94:97]
	s_waitcnt lgkmcnt(1)
	v_mfma_f32_16x16x32_bf16 v[82:85], v[130:133], v[200:203], v[82:85]
	v_mfma_f32_16x16x32_bf16 v[78:81], v[138:141], v[200:203], v[78:81]
	v_mfma_f32_16x16x32_bf16 v[126:129], v[134:137], v[180:183], v[126:129]
	v_mfma_f32_16x16x32_bf16 v[122:125], v[142:145], v[180:183], v[122:125]
	v_mfma_f32_16x16x32_bf16 v[114:117], v[134:137], v[188:191], v[114:117]
	v_mfma_f32_16x16x32_bf16 v[110:113], v[142:145], v[188:191], v[110:113]
	v_mfma_f32_16x16x32_bf16 v[98:101], v[134:137], v[196:199], v[98:101]
	v_mfma_f32_16x16x32_bf16 v[94:97], v[142:145], v[196:199], v[94:97]
	s_waitcnt lgkmcnt(0)
	v_mfma_f32_16x16x32_bf16 v[82:85], v[134:137], v[204:207], v[82:85]
	v_mfma_f32_16x16x32_bf16 v[78:81], v[142:145], v[204:207], v[78:81]
	s_barrier
	s_add_i32 s44, 0, 0x14000
	v_add_u32_e32 v168, s44, v170
	s_add_i32 s43, s43, s35
	ds_read_b128 v[208:211], v168
	ds_read_b128 v[212:215], v168 offset:1024
	ds_read_b128 v[216:219], v168 offset:2048
	ds_read_b128 v[234:237], v168 offset:3072
	v_lshl_add_u64 v[168:169], s[22:23], 0, v[48:49]
	s_mov_b32 m0, s43
	v_lshl_add_u64 v[224:225], s[22:23], 0, v[146:147]
	global_load_lds_dwordx4 v[168:169], off
	s_add_i32 m0, s43, 0x2000
	s_nop 0
	global_load_lds_dwordx4 v[224:225], off
	s_barrier
; #define PG8_STAGE(bufoff, gbase, voff) do { _Pragma("unroll") for (int _i = 0; _i < 2; ++_i) \
;         __builtin_amdgcn_global_load_lds((const unsigned*)((const char*)(gbase) + (voff)[_i]), (PG8_LAS unsigned*)(lds + (bufoff) + ldsw + _i * 8192), 16, 0, 0); } while (0)
; #define PG8_LDA(dst, b, h) do { _Pragma("unroll") for (int m = 0; m < 4; ++m) _Pragma("unroll") for (int k = 0; k < 2; ++k) dst[m][k] = *(const PG8_LAS bf16x8*)(lds + PG8_SA(b, h) + aoff + m * 2048 + k * 1024); } while (0)
; #define PG8_LDB(dst, b, h) do { _Pragma("unroll") for (int n = 0; n < 2; ++n) _Pragma("unroll") for (int k = 0; k < 2; ++k) dst[n][k] = *(const PG8_LAS bf16x8*)(lds + PG8_SB(b, h) + boff + n * 2048 + k * 1024); } while (0)
; #define PG8_MMA(ai, bj, At, Bt) do { __builtin_amdgcn_s_setprio(1); _Pragma("unroll") for (int m = 0; m < 4; ++m) _Pragma("unroll") for (int n = 0; n < 2; ++n) _Pragma("unroll") for (int k = 0; k < 2; ++k) \
;         acc[ai][bj][m][n] = __builtin_amdgcn_mfma_f32_16x16x32_bf16(Bt[n][k], At[m][k], acc[ai][bj][m][n], 0, 0, 0); __builtin_amdgcn_s_setprio(0); } while (0)
; #define PG8_WAIT_V(n) asm volatile("s_waitcnt vmcnt(" #n ")" ::: "memory")
; #define PG8_WAIT_L(n) asm volatile("s_waitcnt lgkmcnt(" #n ")" ::: "memory")
; #define PG8_BAR __builtin_amdgcn_s_barrier()
; #define PG8_SCHED __builtin_amdgcn_sched_barrier(0)
; template <class Epi, class Sched>
; __device__ __forceinline__ void gemm_phase(PG8_LAS unsigned char* lds, const Gemm g, const Sched& S, const Epi& E) {
;     ...
;             PG8_LDB(B1, 0, 1); PG8_STAGE(PG8_SB(0, 0), b2, voffB);
;             PG8_BAR; PG8_WAIT_L(0); PG8_MMA(0, 1, At, B1); PG8_BAR;
;             PG8_LDA(At, 0, 1); PG8_STAGE(PG8_SA(0, 0), a2, voffA);
;             PG8_BAR; PG8_WAIT_L(0); PG8_MMA(1, 0, At, B0); PG8_BAR; PG8_SCHED;
;             PG8_STAGE(PG8_SB(0, 1), b2 + hstep, voffB);
;             PG8_WAIT_V(6); PG8_BAR; PG8_MMA(1, 1, At, B1); PG8_BAR;
;             PG8_LDB(B0, 1, 0); PG8_SCHED; PG8_LDA(At, 1, 0); PG8_STAGE(PG8_SA(0, 1), a2 + hstep, voffA);
;             PG8_WAIT_L(8); PG8_BAR; PG8_WAIT_L(0); PG8_MMA(0, 0, At, B0); PG8_BAR; PG8_SCHED;
	s_waitcnt lgkmcnt(3)
	v_mfma_f32_16x16x32_bf16 v[118:121], v[208:211], v[176:179], v[118:121]
	s_waitcnt lgkmcnt(1)
	v_mfma_f32_16x16x32_bf16 v[106:109], v[216:219], v[176:179], v[106:109]
	v_mfma_f32_16x16x32_bf16 v[102:105], v[208:211], v[184:187], v[102:105]
	v_mfma_f32_16x16x32_bf16 v[90:93], v[216:219], v[184:187], v[90:93]
	v_mfma_f32_16x16x32_bf16 v[86:89], v[208:211], v[192:195], v[86:89]
	v_mfma_f32_16x16x32_bf16 v[74:77], v[216:219], v[192:195], v[74:77]
	v_mfma_f32_16x16x32_bf16 v[70:73], v[208:211], v[200:203], v[70:73]
	v_mfma_f32_16x16x32_bf16 v[66:69], v[216:219], v[200:203], v[66:69]
	v_mfma_f32_16x16x32_bf16 v[118:121], v[212:215], v[180:183], v[118:121]
	s_waitcnt lgkmcnt(0)
	v_mfma_f32_16x16x32_bf16 v[106:109], v[234:237], v[180:183], v[106:109]
	v_mfma_f32_16x16x32_bf16 v[102:105], v[212:215], v[188:191], v[102:105]
	v_mfma_f32_16x16x32_bf16 v[90:93], v[234:237], v[188:191], v[90:93]
	v_mfma_f32_16x16x32_bf16 v[86:89], v[212:215], v[196:199], v[86:89]
	v_mfma_f32_16x16x32_bf16 v[74:77], v[234:237], v[196:199], v[74:77]
	v_mfma_f32_16x16x32_bf16 v[70:73], v[212:215], v[204:207], v[70:73]
	v_mfma_f32_16x16x32_bf16 v[66:69], v[234:237], v[204:207], v[66:69]
	s_mov_b32 m0, s36
	v_lshl_add_u64 v[228:229], s[20:21], 0, v[48:49]
	s_barrier
	ds_read_b128 v[176:179], v172 offset:16384
	ds_read_b128 v[180:183], v172 offset:17408
	ds_read_b128 v[184:187], v172 offset:18432
	ds_read_b128 v[188:191], v172 offset:19456
	ds_read_b128 v[192:195], v172 offset:20480
	ds_read_b128 v[196:199], v172 offset:21504
	ds_read_b128 v[200:203], v172 offset:22528
	ds_read_b128 v[204:207], v172 offset:23552
	global_load_lds_dwordx4 v[228:229], off
	v_lshl_add_u64 v[238:239], s[20:21], 0, v[146:147]
	s_mov_b32 m0, s37
	s_nop 0
	global_load_lds_dwordx4 v[238:239], off
	s_barrier
	s_waitcnt lgkmcnt(7)
	v_mfma_f32_16x16x32_bf16 v[62:65], v[130:133], v[176:179], v[62:65]
	v_mfma_f32_16x16x32_bf16 v[58:61], v[138:141], v[176:179], v[58:61]
	s_waitcnt lgkmcnt(5)
	v_mfma_f32_16x16x32_bf16 v[50:53], v[130:133], v[184:187], v[50:53]
	v_mfma_f32_16x16x32_bf16 v[44:47], v[138:141], v[184:187], v[44:47]
	s_waitcnt lgkmcnt(3)
	v_mfma_f32_16x16x32_bf16 v[32:35], v[130:133], v[192:195], v[32:35]
	v_mfma_f32_16x16x32_bf16 v[28:31], v[138:141], v[192:195], v[28:31]
	s_waitcnt lgkmcnt(1)
	v_mfma_f32_16x16x32_bf16 v[16:19], v[130:133], v[200:203], v[16:19]
	v_mfma_f32_16x16x32_bf16 v[12:15], v[138:141], v[200:203], v[12:15]
	v_mfma_f32_16x16x32_bf16 v[62:65], v[134:137], v[180:183], v[62:65]
	v_mfma_f32_16x16x32_bf16 v[58:61], v[142:145], v[180:183], v[58:61]
	v_mfma_f32_16x16x32_bf16 v[50:53], v[134:137], v[188:191], v[50:53]
	v_mfma_f32_16x16x32_bf16 v[44:47], v[142:145], v[188:191], v[44:47]
	v_mfma_f32_16x16x32_bf16 v[32:35], v[134:137], v[196:199], v[32:35]
	v_mfma_f32_16x16x32_bf16 v[28:31], v[142:145], v[196:199], v[28:31]
	s_waitcnt lgkmcnt(0)
	v_mfma_f32_16x16x32_bf16 v[16:19], v[134:137], v[204:207], v[16:19]
	v_mfma_f32_16x16x32_bf16 v[12:15], v[142:145], v[204:207], v[12:15]
	s_barrier
	s_add_u32 s22, s22, s10
	s_addc_u32 s23, s23, 0
	s_add_i32 s43, s44, s35
	v_lshl_add_u64 v[240:241], s[22:23], 0, v[48:49]
	s_mov_b32 m0, s43
	v_lshl_add_u64 v[242:243], s[22:23], 0, v[146:147]
	global_load_lds_dwordx4 v[240:241], off
	s_add_i32 m0, s43, 0x2000
	s_nop 0
	global_load_lds_dwordx4 v[242:243], off
	s_waitcnt vmcnt(6)
	s_barrier
	v_mfma_f32_16x16x32_bf16 v[54:57], v[208:211], v[176:179], v[54:57]
	v_mfma_f32_16x16x32_bf16 v[40:43], v[216:219], v[176:179], v[40:43]
	v_mfma_f32_16x16x32_bf16 v[36:39], v[208:211], v[184:187], v[36:39]
	v_mfma_f32_16x16x32_bf16 v[24:27], v[216:219], v[184:187], v[24:27]
	v_mfma_f32_16x16x32_bf16 v[20:23], v[208:211], v[192:195], v[20:23]
	v_mfma_f32_16x16x32_bf16 v[8:11], v[216:219], v[192:195], v[8:11]
	v_mfma_f32_16x16x32_bf16 v[4:7], v[208:211], v[200:203], v[4:7]
	v_mfma_f32_16x16x32_bf16 v[0:3], v[216:219], v[200:203], v[0:3]
	v_mfma_f32_16x16x32_bf16 v[54:57], v[212:215], v[180:183], v[54:57]
	v_mfma_f32_16x16x32_bf16 v[40:43], v[234:237], v[180:183], v[40:43]
	v_mfma_f32_16x16x32_bf16 v[36:39], v[212:215], v[188:191], v[36:39]
	v_mfma_f32_16x16x32_bf16 v[24:27], v[234:237], v[188:191], v[24:27]
	v_mfma_f32_16x16x32_bf16 v[20:23], v[212:215], v[196:199], v[20:23]
	v_mfma_f32_16x16x32_bf16 v[8:11], v[234:237], v[196:199], v[8:11]
	v_mfma_f32_16x16x32_bf16 v[4:7], v[212:215], v[204:207], v[4:7]
	v_mfma_f32_16x16x32_bf16 v[0:3], v[234:237], v[204:207], v[0:3]
	s_add_i32 s22, 0, 0x18000
	v_add_u32_e32 v142, s22, v170
	s_barrier
	ds_read_b128 v[130:133], v142
	ds_read_b128 v[134:137], v142 offset:1024
	ds_read_b128 v[138:141], v142 offset:2048
	ds_read_b128 v[142:145], v142 offset:3072
	s_add_u32 s20, s20, s10
	s_addc_u32 s21, s21, 0
	s_mov_b32 m0, s38
	v_lshl_add_u64 v[208:209], s[20:21], 0, v[48:49]
	ds_read_b128 v[176:179], v172 offset:32768
	ds_read_b128 v[180:183], v172 offset:33792
	ds_read_b128 v[184:187], v172 offset:34816
	ds_read_b128 v[188:191], v172 offset:35840
	ds_read_b128 v[192:195], v172 offset:36864
	ds_read_b128 v[196:199], v172 offset:37888
	ds_read_b128 v[200:203], v172 offset:38912
	ds_read_b128 v[204:207], v172 offset:39936
	global_load_lds_dwordx4 v[208:209], off
	v_lshl_add_u64 v[208:209], s[20:21], 0, v[146:147]
	s_mov_b32 m0, s39
	s_nop 0
	global_load_lds_dwordx4 v[208:209], off
	s_waitcnt lgkmcnt(8)
	s_barrier
; #define PG8_STAGE(bufoff, gbase, voff) do { _Pragma("unroll") for (int _i = 0; _i < 2; ++_i) \
;         __builtin_amdgcn_global_load_lds((const unsigned*)((const char*)(gbase) + (voff)[_i]), (PG8_LAS unsigned*)(lds + (bufoff) + ldsw + _i * 8192), 16, 0, 0); } while (0)
; #define PG8_LDA(dst, b, h) do { _Pragma("unroll") for (int m = 0; m < 4; ++m) _Pragma("unroll") for (int k = 0; k < 2; ++k) dst[m][k] = *(const PG8_LAS bf16x8*)(lds + PG8_SA(b, h) + aoff + m * 2048 + k * 1024); } while (0)
; #define PG8_LDB(dst, b, h) do { _Pragma("unroll") for (int n = 0; n < 2; ++n) _Pragma("unroll") for (int k = 0; k < 2; ++k) dst[n][k] = *(const PG8_LAS bf16x8*)(lds + PG8_SB(b, h) + boff + n * 2048 + k * 1024); } while (0)
; #define PG8_MMA(ai, bj, At, Bt) do { __builtin_amdgcn_s_setprio(1); _Pragma("unroll") for (int m = 0; m < 4; ++m) _Pragma("unroll") for (int n = 0; n < 2; ++n) _Pragma("unroll") for (int k = 0; k < 2; ++k) \
;         acc[ai][bj][m][n] = __builtin_amdgcn_mfma_f32_16x16x32_bf16(Bt[n][k], At[m][k], acc[ai][bj][m][n], 0, 0, 0); __builtin_amdgcn_s_setprio(0); } while (0)
; #define PG8_WAIT_V(n) asm volatile("s_waitcnt vmcnt(" #n ")" ::: "memory")
; #define PG8_WAIT_L(n) asm volatile("s_waitcnt lgkmcnt(" #n ")" ::: "memory")
; #define PG8_BAR __builtin_amdgcn_s_barrier()
; #define PG8_SCHED __builtin_amdgcn_sched_barrier(0)
; template <class Epi, class Sched>
; __device__ __forceinline__ void gemm_phase(PG8_LAS unsigned char* lds, const Gemm g, const Sched& S, const Epi& E) {
;     ...
;             PG8_WAIT_L(8); PG8_BAR; PG8_WAIT_L(0); PG8_MMA(0, 0, At, B0); PG8_BAR; PG8_SCHED;
;             PG8_LDB(B1, 1, 1); PG8_STAGE(PG8_SB(1, 0), b3, voffB);
;             PG8_BAR; PG8_WAIT_L(0); PG8_MMA(0, 1, At, B1); PG8_BAR;
;             PG8_LDA(At, 1, 1); PG8_STAGE(PG8_SA(1, 0), a3, voffA);
;             PG8_BAR; PG8_WAIT_L(0); PG8_MMA(1, 0, At, B0); PG8_BAR; PG8_SCHED;
;             PG8_STAGE(PG8_SB(1, 1), b3 + hstep, voffB);
;             PG8_WAIT_V(6); PG8_BAR; PG8_MMA(1, 1, At, B1); PG8_BAR;
	s_waitcnt lgkmcnt(7)
	v_mfma_f32_16x16x32_bf16 v[126:129], v[130:133], v[176:179], v[126:129]
	v_mfma_f32_16x16x32_bf16 v[122:125], v[138:141], v[176:179], v[122:125]
	s_waitcnt lgkmcnt(5)
	v_mfma_f32_16x16x32_bf16 v[114:117], v[130:133], v[184:187], v[114:117]
	v_mfma_f32_16x16x32_bf16 v[110:113], v[138:141], v[184:187], v[110:113]
	s_waitcnt lgkmcnt(3)
	v_mfma_f32_16x16x32_bf16 v[98:101], v[130:133], v[192:195], v[98:101]
	v_mfma_f32_16x16x32_bf16 v[94:97], v[138:141], v[192:195], v[94:97]
	s_waitcnt lgkmcnt(1)
	v_mfma_f32_16x16x32_bf16 v[82:85], v[130:133], v[200:203], v[82:85]
	v_mfma_f32_16x16x32_bf16 v[78:81], v[138:141], v[200:203], v[78:81]
	v_mfma_f32_16x16x32_bf16 v[126:129], v[134:137], v[180:183], v[126:129]
	v_mfma_f32_16x16x32_bf16 v[122:125], v[142:145], v[180:183], v[122:125]
	v_mfma_f32_16x16x32_bf16 v[114:117], v[134:137], v[188:191], v[114:117]
	v_mfma_f32_16x16x32_bf16 v[110:113], v[142:145], v[188:191], v[110:113]
	v_mfma_f32_16x16x32_bf16 v[98:101], v[134:137], v[196:199], v[98:101]
	v_mfma_f32_16x16x32_bf16 v[94:97], v[142:145], v[196:199], v[94:97]
	s_waitcnt lgkmcnt(0)
	v_mfma_f32_16x16x32_bf16 v[82:85], v[134:137], v[204:207], v[82:85]
	v_mfma_f32_16x16x32_bf16 v[78:81], v[142:145], v[204:207], v[78:81]
	s_barrier
	s_add_i32 s20, 0, 0x1c000
	s_add_i32 s21, s22, s35
	v_add_u32_e32 v173, s20, v170
	v_lshl_add_u64 v[168:169], v[168:169], 0, s[0:1]
	s_mov_b32 m0, s21
	ds_read_b128 v[208:211], v173
	ds_read_b128 v[212:215], v173 offset:1024
	ds_read_b128 v[216:219], v173 offset:2048
	ds_read_b128 v[234:237], v173 offset:3072
	global_load_lds_dwordx4 v[168:169], off
	v_lshl_add_u64 v[168:169], v[224:225], 0, s[0:1]
	s_add_i32 m0, s21, 0x2000
	s_nop 0
	global_load_lds_dwordx4 v[168:169], off
	s_barrier
	s_waitcnt lgkmcnt(3)
	v_mfma_f32_16x16x32_bf16 v[118:121], v[208:211], v[176:179], v[118:121]
	s_waitcnt lgkmcnt(1)
	v_mfma_f32_16x16x32_bf16 v[106:109], v[216:219], v[176:179], v[106:109]
	v_mfma_f32_16x16x32_bf16 v[102:105], v[208:211], v[184:187], v[102:105]
	v_mfma_f32_16x16x32_bf16 v[90:93], v[216:219], v[184:187], v[90:93]
	v_mfma_f32_16x16x32_bf16 v[86:89], v[208:211], v[192:195], v[86:89]
	v_mfma_f32_16x16x32_bf16 v[74:77], v[216:219], v[192:195], v[74:77]
	v_mfma_f32_16x16x32_bf16 v[70:73], v[208:211], v[200:203], v[70:73]
	v_mfma_f32_16x16x32_bf16 v[66:69], v[216:219], v[200:203], v[66:69]
	v_mfma_f32_16x16x32_bf16 v[118:121], v[212:215], v[180:183], v[118:121]
	s_waitcnt lgkmcnt(0)
	v_mfma_f32_16x16x32_bf16 v[106:109], v[234:237], v[180:183], v[106:109]
	v_mfma_f32_16x16x32_bf16 v[102:105], v[212:215], v[188:191], v[102:105]
	v_mfma_f32_16x16x32_bf16 v[90:93], v[234:237], v[188:191], v[90:93]
	v_mfma_f32_16x16x32_bf16 v[86:89], v[212:215], v[196:199], v[86:89]
	v_mfma_f32_16x16x32_bf16 v[74:77], v[234:237], v[196:199], v[74:77]
	v_mfma_f32_16x16x32_bf16 v[70:73], v[212:215], v[204:207], v[70:73]
	v_mfma_f32_16x16x32_bf16 v[66:69], v[234:237], v[204:207], v[66:69]
	s_mov_b32 m0, s64
	v_lshl_add_u64 v[168:169], v[228:229], 0, s[0:1]
	s_barrier
	ds_read_b128 v[176:179], v172 offset:49152
	ds_read_b128 v[180:183], v172 offset:50176
	ds_read_b128 v[184:187], v172 offset:51200
	ds_read_b128 v[188:191], v172 offset:52224
	ds_read_b128 v[192:195], v172 offset:53248
	ds_read_b128 v[196:199], v172 offset:54272
	ds_read_b128 v[200:203], v172 offset:55296
	ds_read_b128 v[204:207], v172 offset:56320
	global_load_lds_dwordx4 v[168:169], off
	v_lshl_add_u64 v[168:169], v[238:239], 0, s[0:1]
	s_mov_b32 m0, s65
	s_nop 0
	global_load_lds_dwordx4 v[168:169], off
	s_barrier
	s_waitcnt lgkmcnt(7)
	v_mfma_f32_16x16x32_bf16 v[62:65], v[130:133], v[176:179], v[62:65]
	v_mfma_f32_16x16x32_bf16 v[58:61], v[138:141], v[176:179], v[58:61]
	s_waitcnt lgkmcnt(5)
	v_mfma_f32_16x16x32_bf16 v[50:53], v[130:133], v[184:187], v[50:53]
	v_mfma_f32_16x16x32_bf16 v[44:47], v[138:141], v[184:187], v[44:47]
	s_waitcnt lgkmcnt(3)
	v_mfma_f32_16x16x32_bf16 v[32:35], v[130:133], v[192:195], v[32:35]
	v_mfma_f32_16x16x32_bf16 v[28:31], v[138:141], v[192:195], v[28:31]
	s_waitcnt lgkmcnt(1)
	v_mfma_f32_16x16x32_bf16 v[16:19], v[130:133], v[200:203], v[16:19]
	v_mfma_f32_16x16x32_bf16 v[12:15], v[138:141], v[200:203], v[12:15]
	v_mfma_f32_16x16x32_bf16 v[62:65], v[134:137], v[180:183], v[62:65]
	v_mfma_f32_16x16x32_bf16 v[58:61], v[142:145], v[180:183], v[58:61]
	v_mfma_f32_16x16x32_bf16 v[50:53], v[134:137], v[188:191], v[50:53]
	v_mfma_f32_16x16x32_bf16 v[44:47], v[142:145], v[188:191], v[44:47]
	v_mfma_f32_16x16x32_bf16 v[32:35], v[134:137], v[196:199], v[32:35]
	v_mfma_f32_16x16x32_bf16 v[28:31], v[142:145], v[196:199], v[28:31]
	s_waitcnt lgkmcnt(0)
	v_mfma_f32_16x16x32_bf16 v[16:19], v[134:137], v[204:207], v[16:19]
	v_mfma_f32_16x16x32_bf16 v[12:15], v[142:145], v[204:207], v[12:15]
	s_barrier
	s_add_i32 s20, s20, s35
	v_lshl_add_u64 v[130:131], v[240:241], 0, s[0:1]
	s_mov_b32 m0, s20
	s_nop 0
	global_load_lds_dwordx4 v[130:131], off
	v_lshl_add_u64 v[130:131], v[242:243], 0, s[0:1]
	s_add_i32 m0, s20, 0x2000
	s_nop 0
	global_load_lds_dwordx4 v[130:131], off
	s_add_u32 s16, s16, 0x100
	s_addc_u32 s17, s17, 0
	s_add_u32 s24, s24, 0x100
	s_addc_u32 s25, s25, 0
	s_cmp_ge_u32 s42, s54
	s_mov_b32 s20, s42
	s_waitcnt vmcnt(6)
	s_barrier
	v_mfma_f32_16x16x32_bf16 v[54:57], v[208:211], v[176:179], v[54:57]
	v_mfma_f32_16x16x32_bf16 v[40:43], v[216:219], v[176:179], v[40:43]
	v_mfma_f32_16x16x32_bf16 v[36:39], v[208:211], v[184:187], v[36:39]
	v_mfma_f32_16x16x32_bf16 v[24:27], v[216:219], v[184:187], v[24:27]
	v_mfma_f32_16x16x32_bf16 v[20:23], v[208:211], v[192:195], v[20:23]
	v_mfma_f32_16x16x32_bf16 v[8:11], v[216:219], v[192:195], v[8:11]
	v_mfma_f32_16x16x32_bf16 v[4:7], v[208:211], v[200:203], v[4:7]
	v_mfma_f32_16x16x32_bf16 v[0:3], v[216:219], v[200:203], v[0:3]
	v_mfma_f32_16x16x32_bf16 v[54:57], v[212:215], v[180:183], v[54:57]
	v_mfma_f32_16x16x32_bf16 v[40:43], v[234:237], v[180:183], v[40:43]
	v_mfma_f32_16x16x32_bf16 v[36:39], v[212:215], v[188:191], v[36:39]
	v_mfma_f32_16x16x32_bf16 v[24:27], v[234:237], v[188:191], v[24:27]
	v_mfma_f32_16x16x32_bf16 v[20:23], v[212:215], v[196:199], v[20:23]
	v_mfma_f32_16x16x32_bf16 v[8:11], v[234:237], v[196:199], v[8:11]
	v_mfma_f32_16x16x32_bf16 v[4:7], v[212:215], v[204:207], v[4:7]
	v_mfma_f32_16x16x32_bf16 v[0:3], v[234:237], v[204:207], v[0:3]
	s_barrier
	s_cbranch_scc0 .LBB0_268

; #define PG8_STAGE(bufoff, gbase, voff) do { _Pragma("unroll") for (int _i = 0; _i < 2; ++_i) \
;         __builtin_amdgcn_global_load_lds((const unsigned*)((const char*)(gbase) + (voff)[_i]), (PG8_LAS unsigned*)(lds + (bufoff) + ldsw + _i * 8192), 16, 0, 0); } while (0)
; #define PG8_LDA(dst, b, h) do { _Pragma("unroll") for (int m = 0; m < 4; ++m) _Pragma("unroll") for (int k = 0; k < 2; ++k) dst[m][k] = *(const PG8_LAS bf16x8*)(lds + PG8_SA(b, h) + aoff + m * 2048 + k * 1024); } while (0)
; #define PG8_LDB(dst, b, h) do { _Pragma("unroll") for (int n = 0; n < 2; ++n) _Pragma("unroll") for (int k = 0; k < 2; ++k) dst[n][k] = *(const PG8_LAS bf16x8*)(lds + PG8_SB(b, h) + boff + n * 2048 + k * 1024); } while (0)
; #define PG8_WAIT_L(n) asm volatile("s_waitcnt lgkmcnt(" #n ")" ::: "memory")
; #define PG8_BAR __builtin_amdgcn_s_barrier()
; #define PG8_SCHED __builtin_amdgcn_sched_barrier(0)
; template <class Epi, class Sched>
; __device__ __forceinline__ void gemm_phase(PG8_LAS unsigned char* lds, const Gemm g, const Sched& S, const Epi& E) {
;     ...
;         const bool has_next = S.next(ui + 1, nxt);
;         const char* nA = has_next ? (const char*)g.A + (size_t)nxt.pm * tstepA + (size_t)nxt.kc * cstep : cA; const char* nB = has_next ? (const char*)g.Bt + (size_t)nxt.pn * tstep + (size_t)nxt.kc * cstep : cB;
;         for (int t = 0; t < nt; t += 2) {
;             const bool last = (t == nt - 2);
;             const char* a1 = cA + (size_t)(t + 1) * kstep;
;             const char* a2 = last ? nA : cA + (size_t)(t + 2) * kstep; const char* b2 = last ? nB : cB + (size_t)(t + 2) * kstep;
;             const char* a3 = a2 + kstep; const char* b3 = b2 + kstep;
;             if (last && has_next) S.a_ready(nxt);
;             PG8_LDB(B0, 0, 0); PG8_SCHED; PG8_LDA(At, 0, 0); PG8_STAGE(PG8_SA(1, 1), a1 + hstep, voffA);
;             PG8_WAIT_L(8); PG8_BAR; PG8_WAIT_L(0); PG8_MMA(0, 0, At, B0); PG8_BAR; PG8_SCHED;
;             PG8_LDB(B1, 0, 1); PG8_STAGE(PG8_SB(0, 0), b2, voffB);
;             PG8_BAR; PG8_WAIT_L(0); PG8_MMA(0, 1, At, B1); PG8_BAR;
;             PG8_LDA(At, 0, 1); PG8_STAGE(PG8_SA(0, 0), a2, voffA);
;             PG8_BAR; PG8_WAIT_L(0); PG8_MMA(1, 0, At, B0); PG8_BAR; PG8_SCHED;
.LBB0_287:
	s_add_u32 s20, s20, 0x80
	s_addc_u32 s21, s21, 0
	s_add_u32 s3, s22, 0x100
	s_addc_u32 s40, s23, 0
	s_mov_b32 s22, 0
	s_add_i32 s41, s22, 2
	s_add_u32 s24, s20, 0x80
	s_addc_u32 s23, s21, 0
	s_add_i32 s63, 0, 0x10000
	v_add_u32_e32 v155, s63, v152
	ds_read_b128 v[156:159], v155
	ds_read_b128 v[160:163], v155 offset:1024
	ds_read_b128 v[164:167], v155 offset:2048
	ds_read_b128 v[168:171], v155 offset:3072
	s_cmp_eq_u32 s55, s22
	s_cselect_b32 s22, s12, s24
	s_cselect_b32 s23, s13, s23
	s_cselect_b32 s25, s17, s40
	s_cselect_b32 s24, s16, s3
	v_lshl_add_u64 v[172:173], s[20:21], 0, v[148:149]
	s_add_i32 m0, s43, 0xc000
	ds_read_b128 v[176:179], v154
	ds_read_b128 v[180:183], v154 offset:1024
	ds_read_b128 v[184:187], v154 offset:2048
	ds_read_b128 v[188:191], v154 offset:3072
	ds_read_b128 v[192:195], v154 offset:4096
	ds_read_b128 v[196:199], v154 offset:5120
	ds_read_b128 v[200:203], v154 offset:6144
	ds_read_b128 v[204:207], v154 offset:7168
	global_load_lds_dwordx4 v[172:173], off
	v_lshl_add_u64 v[172:173], s[20:21], 0, v[150:151]
	s_add_i32 m0, s43, 0xe000
	s_nop 0
	global_load_lds_dwordx4 v[172:173], off
	s_waitcnt lgkmcnt(8)
	s_barrier
	s_waitcnt lgkmcnt(7)
	v_mfma_f32_16x16x32_bf16 v[126:129], v[156:159], v[176:179], 0
	v_mfma_f32_16x16x32_bf16 v[122:125], v[164:167], v[176:179], 0
	s_waitcnt lgkmcnt(5)
	v_mfma_f32_16x16x32_bf16 v[118:121], v[156:159], v[184:187], 0
	v_mfma_f32_16x16x32_bf16 v[114:117], v[164:167], v[184:187], 0
	s_waitcnt lgkmcnt(3)
	v_mfma_f32_16x16x32_bf16 v[110:113], v[156:159], v[192:195], 0
	v_mfma_f32_16x16x32_bf16 v[106:109], v[164:167], v[192:195], 0
	s_waitcnt lgkmcnt(1)
	v_mfma_f32_16x16x32_bf16 v[98:101], v[156:159], v[200:203], 0
	v_mfma_f32_16x16x32_bf16 v[90:93], v[164:167], v[200:203], 0
	v_mfma_f32_16x16x32_bf16 v[126:129], v[160:163], v[180:183], v[126:129]
	v_mfma_f32_16x16x32_bf16 v[122:125], v[168:171], v[180:183], v[122:125]
	v_mfma_f32_16x16x32_bf16 v[118:121], v[160:163], v[188:191], v[118:121]
	v_mfma_f32_16x16x32_bf16 v[114:117], v[168:171], v[188:191], v[114:117]
	v_mfma_f32_16x16x32_bf16 v[110:113], v[160:163], v[196:199], v[110:113]
	v_mfma_f32_16x16x32_bf16 v[106:109], v[168:171], v[196:199], v[106:109]
	s_waitcnt lgkmcnt(0)
	v_mfma_f32_16x16x32_bf16 v[98:101], v[160:163], v[204:207], v[98:101]
	v_mfma_f32_16x16x32_bf16 v[90:93], v[168:171], v[204:207], v[90:93]
	s_barrier
	s_add_i32 s64, 0, 0x14000
	s_add_i32 s63, s63, s37
	v_add_u32_e32 v155, s64, v152
	v_lshl_add_u64 v[172:173], s[24:25], 0, v[48:49]
	s_mov_b32 m0, s63
	ds_read_b128 v[208:211], v155
	ds_read_b128 v[212:215], v155 offset:1024
	ds_read_b128 v[216:219], v155 offset:2048
	ds_read_b128 v[234:237], v155 offset:3072
	global_load_lds_dwordx4 v[172:173], off
	v_lshl_add_u64 v[224:225], s[24:25], 0, v[130:131]
	s_add_i32 m0, s63, 0x2000
	s_nop 0
	global_load_lds_dwordx4 v[224:225], off
	s_barrier
	s_waitcnt lgkmcnt(3)
	v_mfma_f32_16x16x32_bf16 v[102:105], v[208:211], v[176:179], 0
	s_waitcnt lgkmcnt(1)
	v_mfma_f32_16x16x32_bf16 v[94:97], v[216:219], v[176:179], 0
	v_mfma_f32_16x16x32_bf16 v[86:89], v[208:211], v[184:187], 0
	v_mfma_f32_16x16x32_bf16 v[82:85], v[216:219], v[184:187], 0
	v_mfma_f32_16x16x32_bf16 v[78:81], v[208:211], v[192:195], 0
	v_mfma_f32_16x16x32_bf16 v[74:77], v[216:219], v[192:195], 0
	v_mfma_f32_16x16x32_bf16 v[70:73], v[208:211], v[200:203], 0
	v_mfma_f32_16x16x32_bf16 v[66:69], v[216:219], v[200:203], 0
	v_mfma_f32_16x16x32_bf16 v[102:105], v[212:215], v[180:183], v[102:105]
	s_waitcnt lgkmcnt(0)
	v_mfma_f32_16x16x32_bf16 v[94:97], v[234:237], v[180:183], v[94:97]
	v_mfma_f32_16x16x32_bf16 v[86:89], v[212:215], v[188:191], v[86:89]
	v_mfma_f32_16x16x32_bf16 v[82:85], v[234:237], v[188:191], v[82:85]
	v_mfma_f32_16x16x32_bf16 v[78:81], v[212:215], v[196:199], v[78:81]
	v_mfma_f32_16x16x32_bf16 v[74:77], v[234:237], v[196:199], v[74:77]
	v_mfma_f32_16x16x32_bf16 v[70:73], v[212:215], v[204:207], v[70:73]
	v_mfma_f32_16x16x32_bf16 v[66:69], v[234:237], v[204:207], v[66:69]
	s_mov_b32 m0, s43
	v_lshl_add_u64 v[228:229], s[22:23], 0, v[48:49]
	s_barrier
	ds_read_b128 v[176:179], v154 offset:16384
	ds_read_b128 v[180:183], v154 offset:17408
	ds_read_b128 v[184:187], v154 offset:18432
	ds_read_b128 v[188:191], v154 offset:19456
	ds_read_b128 v[192:195], v154 offset:20480
	ds_read_b128 v[196:199], v154 offset:21504
	ds_read_b128 v[200:203], v154 offset:22528
	ds_read_b128 v[204:207], v154 offset:23552
	global_load_lds_dwordx4 v[228:229], off
	v_lshl_add_u64 v[238:239], s[22:23], 0, v[130:131]
	s_mov_b32 m0, s44
	s_nop 0
	global_load_lds_dwordx4 v[238:239], off
	s_barrier
	s_waitcnt lgkmcnt(7)
	v_mfma_f32_16x16x32_bf16 v[62:65], v[156:159], v[176:179], 0
	v_mfma_f32_16x16x32_bf16 v[58:61], v[164:167], v[176:179], 0
	s_waitcnt lgkmcnt(5)
	v_mfma_f32_16x16x32_bf16 v[54:57], v[156:159], v[184:187], 0
	v_mfma_f32_16x16x32_bf16 v[50:53], v[164:167], v[184:187], 0
	s_waitcnt lgkmcnt(3)
	v_mfma_f32_16x16x32_bf16 v[44:47], v[156:159], v[192:195], 0
	v_mfma_f32_16x16x32_bf16 v[40:43], v[164:167], v[192:195], 0
	s_waitcnt lgkmcnt(1)
	v_mfma_f32_16x16x32_bf16 v[32:35], v[156:159], v[200:203], 0
	v_mfma_f32_16x16x32_bf16 v[24:27], v[164:167], v[200:203], 0
	v_mfma_f32_16x16x32_bf16 v[62:65], v[160:163], v[180:183], v[62:65]
	v_mfma_f32_16x16x32_bf16 v[58:61], v[168:171], v[180:183], v[58:61]
	v_mfma_f32_16x16x32_bf16 v[54:57], v[160:163], v[188:191], v[54:57]
	v_mfma_f32_16x16x32_bf16 v[50:53], v[168:171], v[188:191], v[50:53]
	v_mfma_f32_16x16x32_bf16 v[44:47], v[160:163], v[196:199], v[44:47]
	v_mfma_f32_16x16x32_bf16 v[40:43], v[168:171], v[196:199], v[40:43]
	s_waitcnt lgkmcnt(0)
	v_mfma_f32_16x16x32_bf16 v[32:35], v[160:163], v[204:207], v[32:35]
	v_mfma_f32_16x16x32_bf16 v[24:27], v[168:171], v[204:207], v[24:27]
	s_barrier
; #define PG8_STAGE(bufoff, gbase, voff) do { _Pragma("unroll") for (int _i = 0; _i < 2; ++_i) \
;         __builtin_amdgcn_global_load_lds((const unsigned*)((const char*)(gbase) + (voff)[_i]), (PG8_LAS unsigned*)(lds + (bufoff) + ldsw + _i * 8192), 16, 0, 0); } while (0)
; #define PG8_LDA(dst, b, h) do { _Pragma("unroll") for (int m = 0; m < 4; ++m) _Pragma("unroll") for (int k = 0; k < 2; ++k) dst[m][k] = *(const PG8_LAS bf16x8*)(lds + PG8_SA(b, h) + aoff + m * 2048 + k * 1024); } while (0)
; #define PG8_LDB(dst, b, h) do { _Pragma("unroll") for (int n = 0; n < 2; ++n) _Pragma("unroll") for (int k = 0; k < 2; ++k) dst[n][k] = *(const PG8_LAS bf16x8*)(lds + PG8_SB(b, h) + boff + n * 2048 + k * 1024); } while (0)
; #define PG8_MMA(ai, bj, At, Bt) do { __builtin_amdgcn_s_setprio(1); _Pragma("unroll") for (int m = 0; m < 4; ++m) _Pragma("unroll") for (int n = 0; n < 2; ++n) _Pragma("unroll") for (int k = 0; k < 2; ++k) \
;         acc[ai][bj][m][n] = __builtin_amdgcn_mfma_f32_16x16x32_bf16(Bt[n][k], At[m][k], acc[ai][bj][m][n], 0, 0, 0); __builtin_amdgcn_s_setprio(0); } while (0)
; #define PG8_WAIT_V(n) asm volatile("s_waitcnt vmcnt(" #n ")" ::: "memory")
; #define PG8_WAIT_L(n) asm volatile("s_waitcnt lgkmcnt(" #n ")" ::: "memory")
; #define PG8_BAR __builtin_amdgcn_s_barrier()
; #define PG8_SCHED __builtin_amdgcn_sched_barrier(0)
; template <class Epi, class Sched>
; __device__ __forceinline__ void gemm_phase(PG8_LAS unsigned char* lds, const Gemm g, const Sched& S, const Epi& E) {
;     ...
;             PG8_STAGE(PG8_SB(0, 1), b2 + hstep, voffB);
;             PG8_WAIT_V(6); PG8_BAR; PG8_MMA(1, 1, At, B1); PG8_BAR;
;             PG8_LDB(B0, 1, 0); PG8_SCHED; PG8_LDA(At, 1, 0); PG8_STAGE(PG8_SA(0, 1), a2 + hstep, voffA);
;             PG8_WAIT_L(8); PG8_BAR; PG8_WAIT_L(0); PG8_MMA(0, 0, At, B0); PG8_BAR; PG8_SCHED;
;             PG8_LDB(B1, 1, 1); PG8_STAGE(PG8_SB(1, 0), b3, voffB);
;             PG8_BAR; PG8_WAIT_L(0); PG8_MMA(0, 1, At, B1); PG8_BAR;
;             PG8_LDA(At, 1, 1); PG8_STAGE(PG8_SA(1, 0), a3, voffA);
;             PG8_BAR; PG8_WAIT_L(0); PG8_MMA(1, 0, At, B0); PG8_BAR; PG8_SCHED;
	s_add_u32 s24, s24, s10
	s_addc_u32 s25, s25, 0
	s_add_i32 s63, s64, s37
	v_lshl_add_u64 v[240:241], s[24:25], 0, v[48:49]
	s_mov_b32 m0, s63
	v_lshl_add_u64 v[242:243], s[24:25], 0, v[130:131]
	global_load_lds_dwordx4 v[240:241], off
	s_add_i32 m0, s63, 0x2000
	s_nop 0
	global_load_lds_dwordx4 v[242:243], off
	s_waitcnt vmcnt(6)
	s_barrier
	v_mfma_f32_16x16x32_bf16 v[36:39], v[208:211], v[176:179], 0
	v_mfma_f32_16x16x32_bf16 v[28:31], v[216:219], v[176:179], 0
	v_mfma_f32_16x16x32_bf16 v[20:23], v[208:211], v[184:187], 0
	v_mfma_f32_16x16x32_bf16 v[16:19], v[216:219], v[184:187], 0
	v_mfma_f32_16x16x32_bf16 v[12:15], v[208:211], v[192:195], 0
	v_mfma_f32_16x16x32_bf16 v[8:11], v[216:219], v[192:195], 0
	v_mfma_f32_16x16x32_bf16 v[4:7], v[208:211], v[200:203], 0
	v_mfma_f32_16x16x32_bf16 v[0:3], v[216:219], v[200:203], 0
	v_mfma_f32_16x16x32_bf16 v[36:39], v[212:215], v[180:183], v[36:39]
	v_mfma_f32_16x16x32_bf16 v[28:31], v[234:237], v[180:183], v[28:31]
	v_mfma_f32_16x16x32_bf16 v[20:23], v[212:215], v[188:191], v[20:23]
	v_mfma_f32_16x16x32_bf16 v[16:19], v[234:237], v[188:191], v[16:19]
	v_mfma_f32_16x16x32_bf16 v[12:15], v[212:215], v[196:199], v[12:15]
	v_mfma_f32_16x16x32_bf16 v[8:11], v[234:237], v[196:199], v[8:11]
	v_mfma_f32_16x16x32_bf16 v[4:7], v[212:215], v[204:207], v[4:7]
	v_mfma_f32_16x16x32_bf16 v[0:3], v[234:237], v[204:207], v[0:3]
	s_add_i32 s24, 0, 0x18000
	v_add_u32_e32 v155, s24, v152
	s_barrier
	ds_read_b128 v[156:159], v155
	ds_read_b128 v[160:163], v155 offset:1024
	ds_read_b128 v[164:167], v155 offset:2048
	ds_read_b128 v[168:171], v155 offset:3072
	s_add_u32 s22, s22, s10
	s_addc_u32 s23, s23, 0
	s_mov_b32 m0, s46
	v_lshl_add_u64 v[208:209], s[22:23], 0, v[48:49]
	ds_read_b128 v[176:179], v154 offset:32768
	ds_read_b128 v[180:183], v154 offset:33792
	ds_read_b128 v[184:187], v154 offset:34816
	ds_read_b128 v[188:191], v154 offset:35840
	ds_read_b128 v[192:195], v154 offset:36864
	ds_read_b128 v[196:199], v154 offset:37888
	ds_read_b128 v[200:203], v154 offset:38912
	ds_read_b128 v[204:207], v154 offset:39936
	global_load_lds_dwordx4 v[208:209], off
	v_lshl_add_u64 v[208:209], s[22:23], 0, v[130:131]
	s_mov_b32 m0, s47
	s_nop 0
	global_load_lds_dwordx4 v[208:209], off
	s_waitcnt lgkmcnt(8)
	s_barrier
	s_waitcnt lgkmcnt(7)
	v_mfma_f32_16x16x32_bf16 v[126:129], v[156:159], v[176:179], v[126:129]
	v_mfma_f32_16x16x32_bf16 v[122:125], v[164:167], v[176:179], v[122:125]
	s_waitcnt lgkmcnt(5)
	v_mfma_f32_16x16x32_bf16 v[118:121], v[156:159], v[184:187], v[118:121]
	v_mfma_f32_16x16x32_bf16 v[114:117], v[164:167], v[184:187], v[114:117]
	s_waitcnt lgkmcnt(3)
	v_mfma_f32_16x16x32_bf16 v[110:113], v[156:159], v[192:195], v[110:113]
	v_mfma_f32_16x16x32_bf16 v[106:109], v[164:167], v[192:195], v[106:109]
	s_waitcnt lgkmcnt(1)
	v_mfma_f32_16x16x32_bf16 v[98:101], v[156:159], v[200:203], v[98:101]
	v_mfma_f32_16x16x32_bf16 v[90:93], v[164:167], v[200:203], v[90:93]
	v_mfma_f32_16x16x32_bf16 v[126:129], v[160:163], v[180:183], v[126:129]
	v_mfma_f32_16x16x32_bf16 v[122:125], v[168:171], v[180:183], v[122:125]
	v_mfma_f32_16x16x32_bf16 v[118:121], v[160:163], v[188:191], v[118:121]
	v_mfma_f32_16x16x32_bf16 v[114:117], v[168:171], v[188:191], v[114:117]
	v_mfma_f32_16x16x32_bf16 v[110:113], v[160:163], v[196:199], v[110:113]
	v_mfma_f32_16x16x32_bf16 v[106:109], v[168:171], v[196:199], v[106:109]
	s_waitcnt lgkmcnt(0)
	v_mfma_f32_16x16x32_bf16 v[98:101], v[160:163], v[204:207], v[98:101]
	v_mfma_f32_16x16x32_bf16 v[90:93], v[168:171], v[204:207], v[90:93]
	s_barrier
	s_add_i32 s22, 0, 0x1c000
	s_add_i32 s23, s24, s37
	v_add_u32_e32 v155, s22, v152
	v_lshl_add_u64 v[172:173], v[172:173], 0, s[0:1]
	s_mov_b32 m0, s23
	ds_read_b128 v[208:211], v155
	ds_read_b128 v[212:215], v155 offset:1024
	ds_read_b128 v[216:219], v155 offset:2048
	ds_read_b128 v[234:237], v155 offset:3072
	global_load_lds_dwordx4 v[172:173], off
	v_lshl_add_u64 v[172:173], v[224:225], 0, s[0:1]
	s_add_i32 m0, s23, 0x2000
	s_nop 0
	global_load_lds_dwordx4 v[172:173], off
	s_barrier
	s_waitcnt lgkmcnt(3)
	v_mfma_f32_16x16x32_bf16 v[102:105], v[208:211], v[176:179], v[102:105]
	s_waitcnt lgkmcnt(1)
	v_mfma_f32_16x16x32_bf16 v[94:97], v[216:219], v[176:179], v[94:97]
	v_mfma_f32_16x16x32_bf16 v[86:89], v[208:211], v[184:187], v[86:89]
	v_mfma_f32_16x16x32_bf16 v[82:85], v[216:219], v[184:187], v[82:85]
	v_mfma_f32_16x16x32_bf16 v[78:81], v[208:211], v[192:195], v[78:81]
	v_mfma_f32_16x16x32_bf16 v[74:77], v[216:219], v[192:195], v[74:77]
	v_mfma_f32_16x16x32_bf16 v[70:73], v[208:211], v[200:203], v[70:73]
	v_mfma_f32_16x16x32_bf16 v[66:69], v[216:219], v[200:203], v[66:69]
	v_mfma_f32_16x16x32_bf16 v[102:105], v[212:215], v[180:183], v[102:105]
	s_waitcnt lgkmcnt(0)
	v_mfma_f32_16x16x32_bf16 v[94:97], v[234:237], v[180:183], v[94:97]
	v_mfma_f32_16x16x32_bf16 v[86:89], v[212:215], v[188:191], v[86:89]
	v_mfma_f32_16x16x32_bf16 v[82:85], v[234:237], v[188:191], v[82:85]
	v_mfma_f32_16x16x32_bf16 v[78:81], v[212:215], v[196:199], v[78:81]
	v_mfma_f32_16x16x32_bf16 v[74:77], v[234:237], v[196:199], v[74:77]
	v_mfma_f32_16x16x32_bf16 v[70:73], v[212:215], v[204:207], v[70:73]
	v_mfma_f32_16x16x32_bf16 v[66:69], v[234:237], v[204:207], v[66:69]
	s_mov_b32 m0, s50
	v_lshl_add_u64 v[172:173], v[228:229], 0, s[0:1]
	s_barrier
	ds_read_b128 v[176:179], v154 offset:49152
	ds_read_b128 v[180:183], v154 offset:50176
	ds_read_b128 v[184:187], v154 offset:51200
	ds_read_b128 v[188:191], v154 offset:52224
	ds_read_b128 v[192:195], v154 offset:53248
	ds_read_b128 v[196:199], v154 offset:54272
	ds_read_b128 v[200:203], v154 offset:55296
	ds_read_b128 v[204:207], v154 offset:56320
	global_load_lds_dwordx4 v[172:173], off
	v_lshl_add_u64 v[172:173], v[238:239], 0, s[0:1]
	s_mov_b32 m0, s51
	s_nop 0
	global_load_lds_dwordx4 v[172:173], off
	s_barrier
; #define PG8_STAGE(bufoff, gbase, voff) do { _Pragma("unroll") for (int _i = 0; _i < 2; ++_i) \
;         __builtin_amdgcn_global_load_lds((const unsigned*)((const char*)(gbase) + (voff)[_i]), (PG8_LAS unsigned*)(lds + (bufoff) + ldsw + _i * 8192), 16, 0, 0); } while (0)
; #define PG8_LDA(dst, b, h) do { _Pragma("unroll") for (int m = 0; m < 4; ++m) _Pragma("unroll") for (int k = 0; k < 2; ++k) dst[m][k] = *(const PG8_LAS bf16x8*)(lds + PG8_SA(b, h) + aoff + m * 2048 + k * 1024); } while (0)
; #define PG8_WAIT_V(n) asm volatile("s_waitcnt vmcnt(" #n ")" ::: "memory")
; template <class Epi, class Sched>
; __device__ __forceinline__ void gemm_phase(PG8_LAS unsigned char* lds, const Gemm g, const Sched& S, const Epi& E) {
;     ...
;         for (int t = 0; t < nt; t += 2) {
;             const bool last = (t == nt - 2);
;             const char* a1 = cA + (size_t)(t + 1) * kstep;
;             const char* a2 = last ? nA : cA + (size_t)(t + 2) * kstep; const char* b2 = last ? nB : cB + (size_t)(t + 2) * kstep;
;             const char* a3 = a2 + kstep; const char* b3 = b2 + kstep;
;             if (last && has_next) S.a_ready(nxt);
;             PG8_LDB(B0, 0, 0); PG8_SCHED; PG8_LDA(At, 0, 0); PG8_STAGE(PG8_SA(1, 1), a1 + hstep, voffA);
;             PG8_WAIT_L(8); PG8_BAR; PG8_WAIT_L(0); PG8_MMA(0, 0, At, B0); PG8_BAR; PG8_SCHED;
;             PG8_LDB(B1, 0, 1); PG8_STAGE(PG8_SB(0, 0), b2, voffB);
;             PG8_BAR; PG8_WAIT_L(0); PG8_MMA(0, 1, At, B1); PG8_BAR;
;             PG8_LDA(At, 0, 1); PG8_STAGE(PG8_SA(0, 0), a2, voffA);
;             PG8_BAR; PG8_WAIT_L(0); PG8_MMA(1, 0, At, B0); PG8_BAR; PG8_SCHED;
;             PG8_STAGE(PG8_SB(0, 1), b2 + hstep, voffB);
;             PG8_WAIT_V(6); PG8_BAR; PG8_MMA(1, 1, At, B1); PG8_BAR;
;             PG8_LDB(B0, 1, 0); PG8_SCHED; PG8_LDA(At, 1, 0); PG8_STAGE(PG8_SA(0, 1), a2 + hstep, voffA);
;             PG8_WAIT_L(8); PG8_BAR; PG8_WAIT_L(0); PG8_MMA(0, 0, At, B0); PG8_BAR; PG8_SCHED;
;             PG8_LDB(B1, 1, 1); PG8_STAGE(PG8_SB(1, 0), b3, voffB);
;             PG8_BAR; PG8_WAIT_L(0); PG8_MMA(0, 1, At, B1); PG8_BAR;
;             PG8_LDA(At, 1, 1); PG8_STAGE(PG8_SA(1, 0), a3, voffA);
;             PG8_BAR; PG8_WAIT_L(0); PG8_MMA(1, 0, At, B0); PG8_BAR; PG8_SCHED;
;             PG8_STAGE(PG8_SB(1, 1), b3 + hstep, voffB);
;             PG8_WAIT_V(6); PG8_BAR; PG8_MMA(1, 1, At, B1); PG8_BAR;
	s_waitcnt lgkmcnt(7)
	v_mfma_f32_16x16x32_bf16 v[62:65], v[156:159], v[176:179], v[62:65]
	v_mfma_f32_16x16x32_bf16 v[58:61], v[164:167], v[176:179], v[58:61]
	s_waitcnt lgkmcnt(5)
	v_mfma_f32_16x16x32_bf16 v[54:57], v[156:159], v[184:187], v[54:57]
	v_mfma_f32_16x16x32_bf16 v[50:53], v[164:167], v[184:187], v[50:53]
	s_waitcnt lgkmcnt(3)
	v_mfma_f32_16x16x32_bf16 v[44:47], v[156:159], v[192:195], v[44:47]
	v_mfma_f32_16x16x32_bf16 v[40:43], v[164:167], v[192:195], v[40:43]
	s_waitcnt lgkmcnt(1)
	v_mfma_f32_16x16x32_bf16 v[32:35], v[156:159], v[200:203], v[32:35]
	v_mfma_f32_16x16x32_bf16 v[24:27], v[164:167], v[200:203], v[24:27]
	v_mfma_f32_16x16x32_bf16 v[62:65], v[160:163], v[180:183], v[62:65]
	v_mfma_f32_16x16x32_bf16 v[58:61], v[168:171], v[180:183], v[58:61]
	v_mfma_f32_16x16x32_bf16 v[54:57], v[160:163], v[188:191], v[54:57]
	v_mfma_f32_16x16x32_bf16 v[50:53], v[168:171], v[188:191], v[50:53]
	v_mfma_f32_16x16x32_bf16 v[44:47], v[160:163], v[196:199], v[44:47]
	v_mfma_f32_16x16x32_bf16 v[40:43], v[168:171], v[196:199], v[40:43]
	s_waitcnt lgkmcnt(0)
	v_mfma_f32_16x16x32_bf16 v[32:35], v[160:163], v[204:207], v[32:35]
	v_mfma_f32_16x16x32_bf16 v[24:27], v[168:171], v[204:207], v[24:27]
	s_barrier
	s_add_i32 s22, s22, s37
	v_lshl_add_u64 v[156:157], v[240:241], 0, s[0:1]
	s_mov_b32 m0, s22
	s_nop 0
	global_load_lds_dwordx4 v[156:157], off
	v_lshl_add_u64 v[156:157], v[242:243], 0, s[0:1]
	s_add_i32 m0, s22, 0x2000
	s_nop 0
	global_load_lds_dwordx4 v[156:157], off
	s_add_u32 s20, s20, 0x100
	s_addc_u32 s21, s21, 0
	s_add_u32 s3, s3, 0x100
	s_addc_u32 s40, s40, 0
	s_cmp_ge_u32 s41, s54
	s_mov_b32 s22, s41
	s_waitcnt vmcnt(6)
	s_barrier
	v_mfma_f32_16x16x32_bf16 v[36:39], v[208:211], v[176:179], v[36:39]
	v_mfma_f32_16x16x32_bf16 v[28:31], v[216:219], v[176:179], v[28:31]
	v_mfma_f32_16x16x32_bf16 v[20:23], v[208:211], v[184:187], v[20:23]
	v_mfma_f32_16x16x32_bf16 v[16:19], v[216:219], v[184:187], v[16:19]
	v_mfma_f32_16x16x32_bf16 v[12:15], v[208:211], v[192:195], v[12:15]
	v_mfma_f32_16x16x32_bf16 v[8:11], v[216:219], v[192:195], v[8:11]
	v_mfma_f32_16x16x32_bf16 v[4:7], v[208:211], v[200:203], v[4:7]
	v_mfma_f32_16x16x32_bf16 v[0:3], v[216:219], v[200:203], v[0:3]
	v_mfma_f32_16x16x32_bf16 v[36:39], v[212:215], v[180:183], v[36:39]
	v_mfma_f32_16x16x32_bf16 v[28:31], v[234:237], v[180:183], v[28:31]
	v_mfma_f32_16x16x32_bf16 v[20:23], v[212:215], v[188:191], v[20:23]
	v_mfma_f32_16x16x32_bf16 v[16:19], v[234:237], v[188:191], v[16:19]
	v_mfma_f32_16x16x32_bf16 v[12:15], v[212:215], v[196:199], v[12:15]
	v_mfma_f32_16x16x32_bf16 v[8:11], v[234:237], v[196:199], v[8:11]
	v_mfma_f32_16x16x32_bf16 v[4:7], v[212:215], v[204:207], v[4:7]
	v_mfma_f32_16x16x32_bf16 v[0:3], v[234:237], v[204:207], v[0:3]
	s_barrier
	s_cbranch_scc1 .Lkpeel_exit_288
.LBB0_288:
	s_add_i32 s41, s22, 2
	s_add_u32 s24, s20, 0x80
	s_addc_u32 s23, s21, 0
	s_add_i32 s63, 0, 0x10000
	v_add_u32_e32 v155, s63, v152
	ds_read_b128 v[156:159], v155
	ds_read_b128 v[160:163], v155 offset:1024
	ds_read_b128 v[164:167], v155 offset:2048
	ds_read_b128 v[168:171], v155 offset:3072
	s_cmp_eq_u32 s55, s22
	s_cselect_b32 s22, s12, s24
	s_cselect_b32 s23, s13, s23
	s_cselect_b32 s25, s17, s40
	s_cselect_b32 s24, s16, s3
	v_lshl_add_u64 v[172:173], s[20:21], 0, v[148:149]
	s_add_i32 m0, s43, 0xc000
	ds_read_b128 v[176:179], v154
	ds_read_b128 v[180:183], v154 offset:1024
	ds_read_b128 v[184:187], v154 offset:2048
	ds_read_b128 v[188:191], v154 offset:3072
	ds_read_b128 v[192:195], v154 offset:4096
	ds_read_b128 v[196:199], v154 offset:5120
	ds_read_b128 v[200:203], v154 offset:6144
	ds_read_b128 v[204:207], v154 offset:7168
	global_load_lds_dwordx4 v[172:173], off
	v_lshl_add_u64 v[172:173], s[20:21], 0, v[150:151]
	s_add_i32 m0, s43, 0xe000
	s_nop 0
	global_load_lds_dwordx4 v[172:173], off
	s_waitcnt lgkmcnt(8)
	s_barrier
	s_waitcnt lgkmcnt(7)
	v_mfma_f32_16x16x32_bf16 v[126:129], v[156:159], v[176:179], v[126:129]
	v_mfma_f32_16x16x32_bf16 v[122:125], v[164:167], v[176:179], v[122:125]
	s_waitcnt lgkmcnt(5)
	v_mfma_f32_16x16x32_bf16 v[118:121], v[156:159], v[184:187], v[118:121]
	v_mfma_f32_16x16x32_bf16 v[114:117], v[164:167], v[184:187], v[114:117]
	s_waitcnt lgkmcnt(3)
	v_mfma_f32_16x16x32_bf16 v[110:113], v[156:159], v[192:195], v[110:113]
	v_mfma_f32_16x16x32_bf16 v[106:109], v[164:167], v[192:195], v[106:109]
	s_waitcnt lgkmcnt(1)
	v_mfma_f32_16x16x32_bf16 v[98:101], v[156:159], v[200:203], v[98:101]
	v_mfma_f32_16x16x32_bf16 v[90:93], v[164:167], v[200:203], v[90:93]
	v_mfma_f32_16x16x32_bf16 v[126:129], v[160:163], v[180:183], v[126:129]
	v_mfma_f32_16x16x32_bf16 v[122:125], v[168:171], v[180:183], v[122:125]
	v_mfma_f32_16x16x32_bf16 v[118:121], v[160:163], v[188:191], v[118:121]
	v_mfma_f32_16x16x32_bf16 v[114:117], v[168:171], v[188:191], v[114:117]
	v_mfma_f32_16x16x32_bf16 v[110:113], v[160:163], v[196:199], v[110:113]
	v_mfma_f32_16x16x32_bf16 v[106:109], v[168:171], v[196:199], v[106:109]
	s_waitcnt lgkmcnt(0)
	v_mfma_f32_16x16x32_bf16 v[98:101], v[160:163], v[204:207], v[98:101]
	v_mfma_f32_16x16x32_bf16 v[90:93], v[168:171], v[204:207], v[90:93]
	s_barrier
	s_add_i32 s64, 0, 0x14000
	s_add_i32 s63, s63, s37
	v_add_u32_e32 v155, s64, v152
	v_lshl_add_u64 v[172:173], s[24:25], 0, v[48:49]
	s_mov_b32 m0, s63
	ds_read_b128 v[208:211], v155
	ds_read_b128 v[212:215], v155 offset:1024
	ds_read_b128 v[216:219], v155 offset:2048
	ds_read_b128 v[234:237], v155 offset:3072
	global_load_lds_dwordx4 v[172:173], off
	v_lshl_add_u64 v[224:225], s[24:25], 0, v[130:131]
	s_add_i32 m0, s63, 0x2000
	s_nop 0
	global_load_lds_dwordx4 v[224:225], off
	s_barrier
; #define PG8_STAGE(bufoff, gbase, voff) do { _Pragma("unroll") for (int _i = 0; _i < 2; ++_i) \
;         __builtin_amdgcn_global_load_lds((const unsigned*)((const char*)(gbase) + (voff)[_i]), (PG8_LAS unsigned*)(lds + (bufoff) + ldsw + _i * 8192), 16, 0, 0); } while (0)
; #define PG8_LDA(dst, b, h) do { _Pragma("unroll") for (int m = 0; m < 4; ++m) _Pragma("unroll") for (int k = 0; k < 2; ++k) dst[m][k] = *(const PG8_LAS bf16x8*)(lds + PG8_SA(b, h) + aoff + m * 2048 + k * 1024); } while (0)
; #define PG8_LDB(dst, b, h) do { _Pragma("unroll") for (int n = 0; n < 2; ++n) _Pragma("unroll") for (int k = 0; k < 2; ++k) dst[n][k] = *(const PG8_LAS bf16x8*)(lds + PG8_SB(b, h) + boff + n * 2048 + k * 1024); } while (0)
; #define PG8_MMA(ai, bj, At, Bt) do { __builtin_amdgcn_s_setprio(1); _Pragma("unroll") for (int m = 0; m < 4; ++m) _Pragma("unroll") for (int n = 0; n < 2; ++n) _Pragma("unroll") for (int k = 0; k < 2; ++k) \
;         acc[ai][bj][m][n] = __builtin_amdgcn_mfma_f32_16x16x32_bf16(Bt[n][k], At[m][k], acc[ai][bj][m][n], 0, 0, 0); __builtin_amdgcn_s_setprio(0); } while (0)
; #define PG8_WAIT_V(n) asm volatile("s_waitcnt vmcnt(" #n ")" ::: "memory")
; #define PG8_WAIT_L(n) asm volatile("s_waitcnt lgkmcnt(" #n ")" ::: "memory")
; #define PG8_BAR __builtin_amdgcn_s_barrier()
; #define PG8_SCHED __builtin_amdgcn_sched_barrier(0)
; template <class Epi, class Sched>
; __device__ __forceinline__ void gemm_phase(PG8_LAS unsigned char* lds, const Gemm g, const Sched& S, const Epi& E) {
;     ...
;             PG8_LDB(B1, 0, 1); PG8_STAGE(PG8_SB(0, 0), b2, voffB);
;             PG8_BAR; PG8_WAIT_L(0); PG8_MMA(0, 1, At, B1); PG8_BAR;
;             PG8_LDA(At, 0, 1); PG8_STAGE(PG8_SA(0, 0), a2, voffA);
;             PG8_BAR; PG8_WAIT_L(0); PG8_MMA(1, 0, At, B0); PG8_BAR; PG8_SCHED;
;             PG8_STAGE(PG8_SB(0, 1), b2 + hstep, voffB);
;             PG8_WAIT_V(6); PG8_BAR; PG8_MMA(1, 1, At, B1); PG8_BAR;
;             PG8_LDB(B0, 1, 0); PG8_SCHED; PG8_LDA(At, 1, 0); PG8_STAGE(PG8_SA(0, 1), a2 + hstep, voffA);
;             PG8_WAIT_L(8); PG8_BAR; PG8_WAIT_L(0); PG8_MMA(0, 0, At, B0); PG8_BAR; PG8_SCHED;
	s_waitcnt lgkmcnt(3)
	v_mfma_f32_16x16x32_bf16 v[102:105], v[208:211], v[176:179], v[102:105]
	s_waitcnt lgkmcnt(1)
	v_mfma_f32_16x16x32_bf16 v[94:97], v[216:219], v[176:179], v[94:97]
	v_mfma_f32_16x16x32_bf16 v[86:89], v[208:211], v[184:187], v[86:89]
	v_mfma_f32_16x16x32_bf16 v[82:85], v[216:219], v[184:187], v[82:85]
	v_mfma_f32_16x16x32_bf16 v[78:81], v[208:211], v[192:195], v[78:81]
	v_mfma_f32_16x16x32_bf16 v[74:77], v[216:219], v[192:195], v[74:77]
	v_mfma_f32_16x16x32_bf16 v[70:73], v[208:211], v[200:203], v[70:73]
	v_mfma_f32_16x16x32_bf16 v[66:69], v[216:219], v[200:203], v[66:69]
	v_mfma_f32_16x16x32_bf16 v[102:105], v[212:215], v[180:183], v[102:105]
	s_waitcnt lgkmcnt(0)
	v_mfma_f32_16x16x32_bf16 v[94:97], v[234:237], v[180:183], v[94:97]
	v_mfma_f32_16x16x32_bf16 v[86:89], v[212:215], v[188:191], v[86:89]
	v_mfma_f32_16x16x32_bf16 v[82:85], v[234:237], v[188:191], v[82:85]
	v_mfma_f32_16x16x32_bf16 v[78:81], v[212:215], v[196:199], v[78:81]
	v_mfma_f32_16x16x32_bf16 v[74:77], v[234:237], v[196:199], v[74:77]
	v_mfma_f32_16x16x32_bf16 v[70:73], v[212:215], v[204:207], v[70:73]
	v_mfma_f32_16x16x32_bf16 v[66:69], v[234:237], v[204:207], v[66:69]
	s_mov_b32 m0, s43
	v_lshl_add_u64 v[228:229], s[22:23], 0, v[48:49]
	s_barrier
	ds_read_b128 v[176:179], v154 offset:16384
	ds_read_b128 v[180:183], v154 offset:17408
	ds_read_b128 v[184:187], v154 offset:18432
	ds_read_b128 v[188:191], v154 offset:19456
	ds_read_b128 v[192:195], v154 offset:20480
	ds_read_b128 v[196:199], v154 offset:21504
	ds_read_b128 v[200:203], v154 offset:22528
	ds_read_b128 v[204:207], v154 offset:23552
	global_load_lds_dwordx4 v[228:229], off
	v_lshl_add_u64 v[238:239], s[22:23], 0, v[130:131]
	s_mov_b32 m0, s44
	s_nop 0
	global_load_lds_dwordx4 v[238:239], off
	s_barrier
	s_waitcnt lgkmcnt(7)
	v_mfma_f32_16x16x32_bf16 v[62:65], v[156:159], v[176:179], v[62:65]
	v_mfma_f32_16x16x32_bf16 v[58:61], v[164:167], v[176:179], v[58:61]
	s_waitcnt lgkmcnt(5)
	v_mfma_f32_16x16x32_bf16 v[54:57], v[156:159], v[184:187], v[54:57]
	v_mfma_f32_16x16x32_bf16 v[50:53], v[164:167], v[184:187], v[50:53]
	s_waitcnt lgkmcnt(3)
	v_mfma_f32_16x16x32_bf16 v[44:47], v[156:159], v[192:195], v[44:47]
	v_mfma_f32_16x16x32_bf16 v[40:43], v[164:167], v[192:195], v[40:43]
	s_waitcnt lgkmcnt(1)
	v_mfma_f32_16x16x32_bf16 v[32:35], v[156:159], v[200:203], v[32:35]
	v_mfma_f32_16x16x32_bf16 v[24:27], v[164:167], v[200:203], v[24:27]
	v_mfma_f32_16x16x32_bf16 v[62:65], v[160:163], v[180:183], v[62:65]
	v_mfma_f32_16x16x32_bf16 v[58:61], v[168:171], v[180:183], v[58:61]
	v_mfma_f32_16x16x32_bf16 v[54:57], v[160:163], v[188:191], v[54:57]
	v_mfma_f32_16x16x32_bf16 v[50:53], v[168:171], v[188:191], v[50:53]
	v_mfma_f32_16x16x32_bf16 v[44:47], v[160:163], v[196:199], v[44:47]
	v_mfma_f32_16x16x32_bf16 v[40:43], v[168:171], v[196:199], v[40:43]
	s_waitcnt lgkmcnt(0)
	v_mfma_f32_16x16x32_bf16 v[32:35], v[160:163], v[204:207], v[32:35]
	v_mfma_f32_16x16x32_bf16 v[24:27], v[168:171], v[204:207], v[24:27]
	s_barrier
	s_add_u32 s24, s24, s10
	s_addc_u32 s25, s25, 0
	s_add_i32 s63, s64, s37
	v_lshl_add_u64 v[240:241], s[24:25], 0, v[48:49]
	s_mov_b32 m0, s63
	v_lshl_add_u64 v[242:243], s[24:25], 0, v[130:131]
	global_load_lds_dwordx4 v[240:241], off
	s_add_i32 m0, s63, 0x2000
	s_nop 0
	global_load_lds_dwordx4 v[242:243], off
	s_waitcnt vmcnt(6)
	s_barrier
	v_mfma_f32_16x16x32_bf16 v[36:39], v[208:211], v[176:179], v[36:39]
	v_mfma_f32_16x16x32_bf16 v[28:31], v[216:219], v[176:179], v[28:31]
	v_mfma_f32_16x16x32_bf16 v[20:23], v[208:211], v[184:187], v[20:23]
	v_mfma_f32_16x16x32_bf16 v[16:19], v[216:219], v[184:187], v[16:19]
	v_mfma_f32_16x16x32_bf16 v[12:15], v[208:211], v[192:195], v[12:15]
	v_mfma_f32_16x16x32_bf16 v[8:11], v[216:219], v[192:195], v[8:11]
	v_mfma_f32_16x16x32_bf16 v[4:7], v[208:211], v[200:203], v[4:7]
	v_mfma_f32_16x16x32_bf16 v[0:3], v[216:219], v[200:203], v[0:3]
	v_mfma_f32_16x16x32_bf16 v[36:39], v[212:215], v[180:183], v[36:39]
	v_mfma_f32_16x16x32_bf16 v[28:31], v[234:237], v[180:183], v[28:31]
	v_mfma_f32_16x16x32_bf16 v[20:23], v[212:215], v[188:191], v[20:23]
	v_mfma_f32_16x16x32_bf16 v[16:19], v[234:237], v[188:191], v[16:19]
	v_mfma_f32_16x16x32_bf16 v[12:15], v[212:215], v[196:199], v[12:15]
	v_mfma_f32_16x16x32_bf16 v[8:11], v[234:237], v[196:199], v[8:11]
	v_mfma_f32_16x16x32_bf16 v[4:7], v[212:215], v[204:207], v[4:7]
	v_mfma_f32_16x16x32_bf16 v[0:3], v[234:237], v[204:207], v[0:3]
	s_add_i32 s24, 0, 0x18000
	v_add_u32_e32 v155, s24, v152
	s_barrier
	ds_read_b128 v[156:159], v155
	ds_read_b128 v[160:163], v155 offset:1024
	ds_read_b128 v[164:167], v155 offset:2048
	ds_read_b128 v[168:171], v155 offset:3072
	s_add_u32 s22, s22, s10
	s_addc_u32 s23, s23, 0
	s_mov_b32 m0, s46
	v_lshl_add_u64 v[208:209], s[22:23], 0, v[48:49]
	ds_read_b128 v[176:179], v154 offset:32768
	ds_read_b128 v[180:183], v154 offset:33792
	ds_read_b128 v[184:187], v154 offset:34816
	ds_read_b128 v[188:191], v154 offset:35840
	ds_read_b128 v[192:195], v154 offset:36864
	ds_read_b128 v[196:199], v154 offset:37888
	ds_read_b128 v[200:203], v154 offset:38912
	ds_read_b128 v[204:207], v154 offset:39936
	global_load_lds_dwordx4 v[208:209], off
	v_lshl_add_u64 v[208:209], s[22:23], 0, v[130:131]
	s_mov_b32 m0, s47
	s_nop 0
	global_load_lds_dwordx4 v[208:209], off
	s_waitcnt lgkmcnt(8)
	s_barrier
; #define PG8_STAGE(bufoff, gbase, voff) do { _Pragma("unroll") for (int _i = 0; _i < 2; ++_i) \
;         __builtin_amdgcn_global_load_lds((const unsigned*)((const char*)(gbase) + (voff)[_i]), (PG8_LAS unsigned*)(lds + (bufoff) + ldsw + _i * 8192), 16, 0, 0); } while (0)
; #define PG8_LDA(dst, b, h) do { _Pragma("unroll") for (int m = 0; m < 4; ++m) _Pragma("unroll") for (int k = 0; k < 2; ++k) dst[m][k] = *(const PG8_LAS bf16x8*)(lds + PG8_SA(b, h) + aoff + m * 2048 + k * 1024); } while (0)
; #define PG8_LDB(dst, b, h) do { _Pragma("unroll") for (int n = 0; n < 2; ++n) _Pragma("unroll") for (int k = 0; k < 2; ++k) dst[n][k] = *(const PG8_LAS bf16x8*)(lds + PG8_SB(b, h) + boff + n * 2048 + k * 1024); } while (0)
; #define PG8_MMA(ai, bj, At, Bt) do { __builtin_amdgcn_s_setprio(1); _Pragma("unroll") for (int m = 0; m < 4; ++m) _Pragma("unroll") for (int n = 0; n < 2; ++n) _Pragma("unroll") for (int k = 0; k < 2; ++k) \
;         acc[ai][bj][m][n] = __builtin_amdgcn_mfma_f32_16x16x32_bf16(Bt[n][k], At[m][k], acc[ai][bj][m][n], 0, 0, 0); __builtin_amdgcn_s_setprio(0); } while (0)
; #define PG8_WAIT_V(n) asm volatile("s_waitcnt vmcnt(" #n ")" ::: "memory")
; #define PG8_WAIT_L(n) asm volatile("s_waitcnt lgkmcnt(" #n ")" ::: "memory")
; #define PG8_BAR __builtin_amdgcn_s_barrier()
; #define PG8_SCHED __builtin_amdgcn_sched_barrier(0)
; template <class Epi, class Sched>
; __device__ __forceinline__ void gemm_phase(PG8_LAS unsigned char* lds, const Gemm g, const Sched& S, const Epi& E) {
;     ...
;             PG8_WAIT_L(8); PG8_BAR; PG8_WAIT_L(0); PG8_MMA(0, 0, At, B0); PG8_BAR; PG8_SCHED;
;             PG8_LDB(B1, 1, 1); PG8_STAGE(PG8_SB(1, 0), b3, voffB);
;             PG8_BAR; PG8_WAIT_L(0); PG8_MMA(0, 1, At, B1); PG8_BAR;
;             PG8_LDA(At, 1, 1); PG8_STAGE(PG8_SA(1, 0), a3, voffA);
;             PG8_BAR; PG8_WAIT_L(0); PG8_MMA(1, 0, At, B0); PG8_BAR; PG8_SCHED;
;             PG8_STAGE(PG8_SB(1, 1), b3 + hstep, voffB);
;             PG8_WAIT_V(6); PG8_BAR; PG8_MMA(1, 1, At, B1); PG8_BAR;
	s_waitcnt lgkmcnt(7)
	v_mfma_f32_16x16x32_bf16 v[126:129], v[156:159], v[176:179], v[126:129]
	v_mfma_f32_16x16x32_bf16 v[122:125], v[164:167], v[176:179], v[122:125]
	s_waitcnt lgkmcnt(5)
	v_mfma_f32_16x16x32_bf16 v[118:121], v[156:159], v[184:187], v[118:121]
	v_mfma_f32_16x16x32_bf16 v[114:117], v[164:167], v[184:187], v[114:117]
	s_waitcnt lgkmcnt(3)
	v_mfma_f32_16x16x32_bf16 v[110:113], v[156:159], v[192:195], v[110:113]
	v_mfma_f32_16x16x32_bf16 v[106:109], v[164:167], v[192:195], v[106:109]
	s_waitcnt lgkmcnt(1)
	v_mfma_f32_16x16x32_bf16 v[98:101], v[156:159], v[200:203], v[98:101]
	v_mfma_f32_16x16x32_bf16 v[90:93], v[164:167], v[200:203], v[90:93]
	v_mfma_f32_16x16x32_bf16 v[126:129], v[160:163], v[180:183], v[126:129]
	v_mfma_f32_16x16x32_bf16 v[122:125], v[168:171], v[180:183], v[122:125]
	v_mfma_f32_16x16x32_bf16 v[118:121], v[160:163], v[188:191], v[118:121]
	v_mfma_f32_16x16x32_bf16 v[114:117], v[168:171], v[188:191], v[114:117]
	v_mfma_f32_16x16x32_bf16 v[110:113], v[160:163], v[196:199], v[110:113]
	v_mfma_f32_16x16x32_bf16 v[106:109], v[168:171], v[196:199], v[106:109]
	s_waitcnt lgkmcnt(0)
	v_mfma_f32_16x16x32_bf16 v[98:101], v[160:163], v[204:207], v[98:101]
	v_mfma_f32_16x16x32_bf16 v[90:93], v[168:171], v[204:207], v[90:93]
	s_barrier
	s_add_i32 s22, 0, 0x1c000
	s_add_i32 s23, s24, s37
	v_add_u32_e32 v155, s22, v152
	v_lshl_add_u64 v[172:173], v[172:173], 0, s[0:1]
	s_mov_b32 m0, s23
	ds_read_b128 v[208:211], v155
	ds_read_b128 v[212:215], v155 offset:1024
	ds_read_b128 v[216:219], v155 offset:2048
	ds_read_b128 v[234:237], v155 offset:3072
	global_load_lds_dwordx4 v[172:173], off
	v_lshl_add_u64 v[172:173], v[224:225], 0, s[0:1]
	s_add_i32 m0, s23, 0x2000
	s_nop 0
	global_load_lds_dwordx4 v[172:173], off
	s_barrier
	s_waitcnt lgkmcnt(3)
	v_mfma_f32_16x16x32_bf16 v[102:105], v[208:211], v[176:179], v[102:105]
	s_waitcnt lgkmcnt(1)
	v_mfma_f32_16x16x32_bf16 v[94:97], v[216:219], v[176:179], v[94:97]
	v_mfma_f32_16x16x32_bf16 v[86:89], v[208:211], v[184:187], v[86:89]
	v_mfma_f32_16x16x32_bf16 v[82:85], v[216:219], v[184:187], v[82:85]
	v_mfma_f32_16x16x32_bf16 v[78:81], v[208:211], v[192:195], v[78:81]
	v_mfma_f32_16x16x32_bf16 v[74:77], v[216:219], v[192:195], v[74:77]
	v_mfma_f32_16x16x32_bf16 v[70:73], v[208:211], v[200:203], v[70:73]
	v_mfma_f32_16x16x32_bf16 v[66:69], v[216:219], v[200:203], v[66:69]
	v_mfma_f32_16x16x32_bf16 v[102:105], v[212:215], v[180:183], v[102:105]
	s_waitcnt lgkmcnt(0)
	v_mfma_f32_16x16x32_bf16 v[94:97], v[234:237], v[180:183], v[94:97]
	v_mfma_f32_16x16x32_bf16 v[86:89], v[212:215], v[188:191], v[86:89]
	v_mfma_f32_16x16x32_bf16 v[82:85], v[234:237], v[188:191], v[82:85]
	v_mfma_f32_16x16x32_bf16 v[78:81], v[212:215], v[196:199], v[78:81]
	v_mfma_f32_16x16x32_bf16 v[74:77], v[234:237], v[196:199], v[74:77]
	v_mfma_f32_16x16x32_bf16 v[70:73], v[212:215], v[204:207], v[70:73]
	v_mfma_f32_16x16x32_bf16 v[66:69], v[234:237], v[204:207], v[66:69]
	s_mov_b32 m0, s50
	v_lshl_add_u64 v[172:173], v[228:229], 0, s[0:1]
	s_barrier
	ds_read_b128 v[176:179], v154 offset:49152
	ds_read_b128 v[180:183], v154 offset:50176
	ds_read_b128 v[184:187], v154 offset:51200
	ds_read_b128 v[188:191], v154 offset:52224
	ds_read_b128 v[192:195], v154 offset:53248
	ds_read_b128 v[196:199], v154 offset:54272
	ds_read_b128 v[200:203], v154 offset:55296
	ds_read_b128 v[204:207], v154 offset:56320
	global_load_lds_dwordx4 v[172:173], off
	v_lshl_add_u64 v[172:173], v[238:239], 0, s[0:1]
	s_mov_b32 m0, s51
	s_nop 0
	global_load_lds_dwordx4 v[172:173], off
	s_barrier
	s_waitcnt lgkmcnt(7)
	v_mfma_f32_16x16x32_bf16 v[62:65], v[156:159], v[176:179], v[62:65]
	v_mfma_f32_16x16x32_bf16 v[58:61], v[164:167], v[176:179], v[58:61]
	s_waitcnt lgkmcnt(5)
	v_mfma_f32_16x16x32_bf16 v[54:57], v[156:159], v[184:187], v[54:57]
	v_mfma_f32_16x16x32_bf16 v[50:53], v[164:167], v[184:187], v[50:53]
	s_waitcnt lgkmcnt(3)
	v_mfma_f32_16x16x32_bf16 v[44:47], v[156:159], v[192:195], v[44:47]
	v_mfma_f32_16x16x32_bf16 v[40:43], v[164:167], v[192:195], v[40:43]
	s_waitcnt lgkmcnt(1)
	v_mfma_f32_16x16x32_bf16 v[32:35], v[156:159], v[200:203], v[32:35]
	v_mfma_f32_16x16x32_bf16 v[24:27], v[164:167], v[200:203], v[24:27]
	v_mfma_f32_16x16x32_bf16 v[62:65], v[160:163], v[180:183], v[62:65]
	v_mfma_f32_16x16x32_bf16 v[58:61], v[168:171], v[180:183], v[58:61]
	v_mfma_f32_16x16x32_bf16 v[54:57], v[160:163], v[188:191], v[54:57]
	v_mfma_f32_16x16x32_bf16 v[50:53], v[168:171], v[188:191], v[50:53]
	v_mfma_f32_16x16x32_bf16 v[44:47], v[160:163], v[196:199], v[44:47]
	v_mfma_f32_16x16x32_bf16 v[40:43], v[168:171], v[196:199], v[40:43]
	s_waitcnt lgkmcnt(0)
	v_mfma_f32_16x16x32_bf16 v[32:35], v[160:163], v[204:207], v[32:35]
	v_mfma_f32_16x16x32_bf16 v[24:27], v[168:171], v[204:207], v[24:27]
	s_barrier
	s_add_i32 s22, s22, s37
	v_lshl_add_u64 v[156:157], v[240:241], 0, s[0:1]
	s_mov_b32 m0, s22
	s_nop 0
	global_load_lds_dwordx4 v[156:157], off
	v_lshl_add_u64 v[156:157], v[242:243], 0, s[0:1]
	s_add_i32 m0, s22, 0x2000
	s_nop 0
	global_load_lds_dwordx4 v[156:157], off
	s_add_u32 s20, s20, 0x100
	s_addc_u32 s21, s21, 0
	s_add_u32 s3, s3, 0x100
	s_addc_u32 s40, s40, 0
	s_cmp_ge_u32 s41, s54
	s_mov_b32 s22, s41
	s_waitcnt vmcnt(6)
	s_barrier
	v_mfma_f32_16x16x32_bf16 v[36:39], v[208:211], v[176:179], v[36:39]
	v_mfma_f32_16x16x32_bf16 v[28:31], v[216:219], v[176:179], v[28:31]
	v_mfma_f32_16x16x32_bf16 v[20:23], v[208:211], v[184:187], v[20:23]
	v_mfma_f32_16x16x32_bf16 v[16:19], v[216:219], v[184:187], v[16:19]
	v_mfma_f32_16x16x32_bf16 v[12:15], v[208:211], v[192:195], v[12:15]
	v_mfma_f32_16x16x32_bf16 v[8:11], v[216:219], v[192:195], v[8:11]
	v_mfma_f32_16x16x32_bf16 v[4:7], v[208:211], v[200:203], v[4:7]
	v_mfma_f32_16x16x32_bf16 v[0:3], v[216:219], v[200:203], v[0:3]
	v_mfma_f32_16x16x32_bf16 v[36:39], v[212:215], v[180:183], v[36:39]
	v_mfma_f32_16x16x32_bf16 v[28:31], v[234:237], v[180:183], v[28:31]
	v_mfma_f32_16x16x32_bf16 v[20:23], v[212:215], v[188:191], v[20:23]
	v_mfma_f32_16x16x32_bf16 v[16:19], v[234:237], v[188:191], v[16:19]
	v_mfma_f32_16x16x32_bf16 v[12:15], v[212:215], v[196:199], v[12:15]
	v_mfma_f32_16x16x32_bf16 v[8:11], v[234:237], v[196:199], v[8:11]
	v_mfma_f32_16x16x32_bf16 v[4:7], v[212:215], v[204:207], v[4:7]
	v_mfma_f32_16x16x32_bf16 v[0:3], v[234:237], v[204:207], v[0:3]
	s_barrier
	s_cbranch_scc0 .LBB0_288

; #define PG8_STAGE(bufoff, gbase, voff) do { _Pragma("unroll") for (int _i = 0; _i < 2; ++_i) \
;         __builtin_amdgcn_global_load_lds((const unsigned*)((const char*)(gbase) + (voff)[_i]), (PG8_LAS unsigned*)(lds + (bufoff) + ldsw + _i * 8192), 16, 0, 0); } while (0)
; #define PG8_LDA(dst, b, h) do { _Pragma("unroll") for (int m = 0; m < 4; ++m) _Pragma("unroll") for (int k = 0; k < 2; ++k) dst[m][k] = *(const PG8_LAS bf16x8*)(lds + PG8_SA(b, h) + aoff + m * 2048 + k * 1024); } while (0)
; #define PG8_LDB(dst, b, h) do { _Pragma("unroll") for (int n = 0; n < 2; ++n) _Pragma("unroll") for (int k = 0; k < 2; ++k) dst[n][k] = *(const PG8_LAS bf16x8*)(lds + PG8_SB(b, h) + boff + n * 2048 + k * 1024); } while (0)
; #define PG8_WAIT_L(n) asm volatile("s_waitcnt lgkmcnt(" #n ")" ::: "memory")
; #define PG8_BAR __builtin_amdgcn_s_barrier()
; #define PG8_SCHED __builtin_amdgcn_sched_barrier(0)
; template <class Epi, class Sched>
; __device__ __forceinline__ void gemm_phase(PG8_LAS unsigned char* lds, const Gemm g, const Sched& S, const Epi& E) {
;     ...
;         const bool has_next = S.next(ui + 1, nxt);
;         const char* nA = has_next ? (const char*)g.A + (size_t)nxt.pm * tstepA + (size_t)nxt.kc * cstep : cA; const char* nB = has_next ? (const char*)g.Bt + (size_t)nxt.pn * tstep + (size_t)nxt.kc * cstep : cB;
;         for (int t = 0; t < nt; t += 2) {
;             const bool last = (t == nt - 2);
;             const char* a1 = cA + (size_t)(t + 1) * kstep;
;             const char* a2 = last ? nA : cA + (size_t)(t + 2) * kstep; const char* b2 = last ? nB : cB + (size_t)(t + 2) * kstep;
;             const char* a3 = a2 + kstep; const char* b3 = b2 + kstep;
;             if (last && has_next) S.a_ready(nxt);
;             PG8_LDB(B0, 0, 0); PG8_SCHED; PG8_LDA(At, 0, 0); PG8_STAGE(PG8_SA(1, 1), a1 + hstep, voffA);
;             PG8_WAIT_L(8); PG8_BAR; PG8_WAIT_L(0); PG8_MMA(0, 0, At, B0); PG8_BAR; PG8_SCHED;
;             PG8_LDB(B1, 0, 1); PG8_STAGE(PG8_SB(0, 0), b2, voffB);
;             PG8_BAR; PG8_WAIT_L(0); PG8_MMA(0, 1, At, B1); PG8_BAR;
;             PG8_LDA(At, 0, 1); PG8_STAGE(PG8_SA(0, 0), a2, voffA);
;             PG8_BAR; PG8_WAIT_L(0); PG8_MMA(1, 0, At, B0); PG8_BAR; PG8_SCHED;
.LBB0_319:
	v_mov_b64_e32 v[0:1], s[56:57]
	s_ashr_i32 s25, s24, 31
	v_cmp_lt_i64_e32 vcc, s[26:27], v[0:1]
	s_lshl_b64 s[26:27], s[24:25], 19
	s_add_u32 s26, s8, s26
	s_addc_u32 s27, s9, s27
	s_and_b64 s[28:29], vcc, exec
	s_cselect_b32 s25, s27, s31
	s_cselect_b32 s56, s26, s30
	s_ashr_i32 s23, s22, 31
	s_lshl_b64 s[28:29], s[22:23], 19
	s_add_u32 s28, s6, s28
	s_addc_u32 s29, s7, s29
	s_and_b64 s[36:37], vcc, exec
	s_cselect_b32 s23, s29, s35
	s_cselect_b32 s57, s28, s34
	s_add_u32 s30, s30, 0x40080
	s_addc_u32 s31, s31, 0
	s_add_u32 s59, s34, 0x100
	s_addc_u32 s63, s35, 0
	s_mov_b32 s64, -2
	s_add_u32 s34, s30, 0xfffc0080
	s_addc_u32 s35, s31, -1
	s_add_i32 s65, 0, 0x10000
	v_add_u32_e32 v140, s65, v143
	ds_read_b128 v[146:149], v140
	ds_read_b128 v[150:153], v140 offset:1024
	ds_read_b128 v[154:157], v140 offset:2048
	ds_read_b128 v[158:161], v140 offset:3072
	s_cmp_eq_u32 s64, 12
	s_cselect_b32 s37, s25, s35
	s_cselect_b32 s36, s56, s34
	s_cselect_b32 s35, s23, s63
	s_cselect_b32 s34, s57, s59
	v_lshl_add_u64 v[140:141], s[30:31], 0, v[136:137]
	s_add_i32 m0, s21, 0xc000
	ds_read_b128 v[162:165], v145
	ds_read_b128 v[166:169], v145 offset:1024
	ds_read_b128 v[170:173], v145 offset:2048
	ds_read_b128 v[176:179], v145 offset:3072
	ds_read_b128 v[180:183], v145 offset:4096
	ds_read_b128 v[184:187], v145 offset:5120
	ds_read_b128 v[188:191], v145 offset:6144
	ds_read_b128 v[192:195], v145 offset:7168
	global_load_lds_dwordx4 v[140:141], off
	v_lshl_add_u64 v[140:141], s[30:31], 0, v[138:139]
	s_add_i32 m0, s21, 0xe000
	s_nop 0
	global_load_lds_dwordx4 v[140:141], off
	s_waitcnt lgkmcnt(8)
	s_barrier
	s_waitcnt lgkmcnt(7)
	v_mfma_f32_16x16x32_bf16 v[126:129], v[146:149], v[162:165], 0
	v_mfma_f32_16x16x32_bf16 v[122:125], v[154:157], v[162:165], 0
	s_waitcnt lgkmcnt(5)
	v_mfma_f32_16x16x32_bf16 v[118:121], v[146:149], v[170:173], 0
	v_mfma_f32_16x16x32_bf16 v[110:113], v[154:157], v[170:173], 0
	s_waitcnt lgkmcnt(3)
	v_mfma_f32_16x16x32_bf16 v[102:105], v[146:149], v[180:183], 0
	v_mfma_f32_16x16x32_bf16 v[94:97], v[154:157], v[180:183], 0
	s_waitcnt lgkmcnt(1)
	v_mfma_f32_16x16x32_bf16 v[86:89], v[146:149], v[188:191], 0
	v_mfma_f32_16x16x32_bf16 v[78:81], v[154:157], v[188:191], 0
	v_mfma_f32_16x16x32_bf16 v[126:129], v[150:153], v[166:169], v[126:129]
	v_mfma_f32_16x16x32_bf16 v[122:125], v[158:161], v[166:169], v[122:125]
	v_mfma_f32_16x16x32_bf16 v[118:121], v[150:153], v[176:179], v[118:121]
	v_mfma_f32_16x16x32_bf16 v[110:113], v[158:161], v[176:179], v[110:113]
	v_mfma_f32_16x16x32_bf16 v[102:105], v[150:153], v[184:187], v[102:105]
	v_mfma_f32_16x16x32_bf16 v[94:97], v[158:161], v[184:187], v[94:97]
	s_waitcnt lgkmcnt(0)
	v_mfma_f32_16x16x32_bf16 v[86:89], v[150:153], v[192:195], v[86:89]
	v_mfma_f32_16x16x32_bf16 v[78:81], v[158:161], v[192:195], v[78:81]
	s_barrier
	s_add_i32 s68, 0, 0x14000
	v_add_u32_e32 v140, s68, v143
	s_add_i32 s65, s65, s13
	ds_read_b128 v[196:199], v140
	ds_read_b128 v[200:203], v140 offset:1024
	ds_read_b128 v[204:207], v140 offset:2048
	ds_read_b128 v[208:211], v140 offset:3072
	v_lshl_add_u64 v[140:141], s[34:35], 0, v[48:49]
	s_mov_b32 m0, s65
	v_lshl_add_u64 v[212:213], s[34:35], 0, v[130:131]
	global_load_lds_dwordx4 v[140:141], off
	s_add_i32 m0, s65, 0x2000
	s_nop 0
	global_load_lds_dwordx4 v[212:213], off
	s_barrier
	s_waitcnt lgkmcnt(3)
	v_mfma_f32_16x16x32_bf16 v[114:117], v[196:199], v[162:165], 0
	s_waitcnt lgkmcnt(1)
	v_mfma_f32_16x16x32_bf16 v[106:109], v[204:207], v[162:165], 0
	v_mfma_f32_16x16x32_bf16 v[98:101], v[196:199], v[170:173], 0
	v_mfma_f32_16x16x32_bf16 v[90:93], v[204:207], v[170:173], 0
	v_mfma_f32_16x16x32_bf16 v[82:85], v[196:199], v[180:183], 0
	v_mfma_f32_16x16x32_bf16 v[74:77], v[204:207], v[180:183], 0
	v_mfma_f32_16x16x32_bf16 v[70:73], v[196:199], v[188:191], 0
	v_mfma_f32_16x16x32_bf16 v[66:69], v[204:207], v[188:191], 0
	v_mfma_f32_16x16x32_bf16 v[114:117], v[200:203], v[166:169], v[114:117]
	s_waitcnt lgkmcnt(0)
	v_mfma_f32_16x16x32_bf16 v[106:109], v[208:211], v[166:169], v[106:109]
	v_mfma_f32_16x16x32_bf16 v[98:101], v[200:203], v[176:179], v[98:101]
	v_mfma_f32_16x16x32_bf16 v[90:93], v[208:211], v[176:179], v[90:93]
	v_mfma_f32_16x16x32_bf16 v[82:85], v[200:203], v[184:187], v[82:85]
	v_mfma_f32_16x16x32_bf16 v[74:77], v[208:211], v[184:187], v[74:77]
	v_mfma_f32_16x16x32_bf16 v[70:73], v[200:203], v[192:195], v[70:73]
	v_mfma_f32_16x16x32_bf16 v[66:69], v[208:211], v[192:195], v[66:69]
	s_mov_b32 m0, s21
	v_lshl_add_u64 v[214:215], s[36:37], 0, v[134:135]
	s_barrier
	ds_read_b128 v[162:165], v145 offset:16384
	ds_read_b128 v[166:169], v145 offset:17408
	ds_read_b128 v[170:173], v145 offset:18432
	ds_read_b128 v[176:179], v145 offset:19456
	ds_read_b128 v[180:183], v145 offset:20480
	ds_read_b128 v[184:187], v145 offset:21504
	ds_read_b128 v[188:191], v145 offset:22528
	ds_read_b128 v[192:195], v145 offset:23552
	global_load_lds_dwordx4 v[214:215], off
	v_lshl_add_u64 v[216:217], s[36:37], 0, v[132:133]
	s_mov_b32 m0, s46
	s_nop 0
	global_load_lds_dwordx4 v[216:217], off
	s_barrier
; #define PG8_STAGE(bufoff, gbase, voff) do { _Pragma("unroll") for (int _i = 0; _i < 2; ++_i) \
;         __builtin_amdgcn_global_load_lds((const unsigned*)((const char*)(gbase) + (voff)[_i]), (PG8_LAS unsigned*)(lds + (bufoff) + ldsw + _i * 8192), 16, 0, 0); } while (0)
; #define PG8_LDA(dst, b, h) do { _Pragma("unroll") for (int m = 0; m < 4; ++m) _Pragma("unroll") for (int k = 0; k < 2; ++k) dst[m][k] = *(const PG8_LAS bf16x8*)(lds + PG8_SA(b, h) + aoff + m * 2048 + k * 1024); } while (0)
; #define PG8_LDB(dst, b, h) do { _Pragma("unroll") for (int n = 0; n < 2; ++n) _Pragma("unroll") for (int k = 0; k < 2; ++k) dst[n][k] = *(const PG8_LAS bf16x8*)(lds + PG8_SB(b, h) + boff + n * 2048 + k * 1024); } while (0)
; #define PG8_MMA(ai, bj, At, Bt) do { __builtin_amdgcn_s_setprio(1); _Pragma("unroll") for (int m = 0; m < 4; ++m) _Pragma("unroll") for (int n = 0; n < 2; ++n) _Pragma("unroll") for (int k = 0; k < 2; ++k) \
;         acc[ai][bj][m][n] = __builtin_amdgcn_mfma_f32_16x16x32_bf16(Bt[n][k], At[m][k], acc[ai][bj][m][n], 0, 0, 0); __builtin_amdgcn_s_setprio(0); } while (0)
; #define PG8_WAIT_V(n) asm volatile("s_waitcnt vmcnt(" #n ")" ::: "memory")
; #define PG8_WAIT_L(n) asm volatile("s_waitcnt lgkmcnt(" #n ")" ::: "memory")
; #define PG8_BAR __builtin_amdgcn_s_barrier()
; #define PG8_SCHED __builtin_amdgcn_sched_barrier(0)
; template <class Epi, class Sched>
; __device__ __forceinline__ void gemm_phase(PG8_LAS unsigned char* lds, const Gemm g, const Sched& S, const Epi& E) {
;     ...
;             PG8_BAR; PG8_WAIT_L(0); PG8_MMA(1, 0, At, B0); PG8_BAR; PG8_SCHED;
;             PG8_STAGE(PG8_SB(0, 1), b2 + hstep, voffB);
;             PG8_WAIT_V(6); PG8_BAR; PG8_MMA(1, 1, At, B1); PG8_BAR;
;             PG8_LDB(B0, 1, 0); PG8_SCHED; PG8_LDA(At, 1, 0); PG8_STAGE(PG8_SA(0, 1), a2 + hstep, voffA);
;             PG8_WAIT_L(8); PG8_BAR; PG8_WAIT_L(0); PG8_MMA(0, 0, At, B0); PG8_BAR; PG8_SCHED;
;             PG8_LDB(B1, 1, 1); PG8_STAGE(PG8_SB(1, 0), b3, voffB);
;             PG8_BAR; PG8_WAIT_L(0); PG8_MMA(0, 1, At, B1); PG8_BAR;
	s_waitcnt lgkmcnt(7)
	v_mfma_f32_16x16x32_bf16 v[62:65], v[146:149], v[162:165], 0
	v_mfma_f32_16x16x32_bf16 v[58:61], v[154:157], v[162:165], 0
	s_waitcnt lgkmcnt(5)
	v_mfma_f32_16x16x32_bf16 v[54:57], v[146:149], v[170:173], 0
	v_mfma_f32_16x16x32_bf16 v[44:47], v[154:157], v[170:173], 0
	s_waitcnt lgkmcnt(3)
	v_mfma_f32_16x16x32_bf16 v[36:39], v[146:149], v[180:183], 0
	v_mfma_f32_16x16x32_bf16 v[28:31], v[154:157], v[180:183], 0
	s_waitcnt lgkmcnt(1)
	v_mfma_f32_16x16x32_bf16 v[20:23], v[146:149], v[188:191], 0
	v_mfma_f32_16x16x32_bf16 v[12:15], v[154:157], v[188:191], 0
	v_mfma_f32_16x16x32_bf16 v[62:65], v[150:153], v[166:169], v[62:65]
	v_mfma_f32_16x16x32_bf16 v[58:61], v[158:161], v[166:169], v[58:61]
	v_mfma_f32_16x16x32_bf16 v[54:57], v[150:153], v[176:179], v[54:57]
	v_mfma_f32_16x16x32_bf16 v[44:47], v[158:161], v[176:179], v[44:47]
	v_mfma_f32_16x16x32_bf16 v[36:39], v[150:153], v[184:187], v[36:39]
	v_mfma_f32_16x16x32_bf16 v[28:31], v[158:161], v[184:187], v[28:31]
	s_waitcnt lgkmcnt(0)
	v_mfma_f32_16x16x32_bf16 v[20:23], v[150:153], v[192:195], v[20:23]
	v_mfma_f32_16x16x32_bf16 v[12:15], v[158:161], v[192:195], v[12:15]
	s_barrier
	s_add_u32 s66, s34, 0x40000
	s_addc_u32 s67, s35, 0
	s_add_i32 s65, s68, s13
	v_lshl_add_u64 v[146:147], s[66:67], 0, v[48:49]
	s_mov_b32 m0, s65
	s_nop 0
	global_load_lds_dwordx4 v[146:147], off
	v_lshl_add_u64 v[146:147], s[66:67], 0, v[130:131]
	s_add_i32 m0, s65, 0x2000
	s_nop 0
	global_load_lds_dwordx4 v[146:147], off
	s_waitcnt vmcnt(6)
	s_barrier
	v_mfma_f32_16x16x32_bf16 v[50:53], v[196:199], v[162:165], 0
	v_mfma_f32_16x16x32_bf16 v[40:43], v[204:207], v[162:165], 0
	v_mfma_f32_16x16x32_bf16 v[32:35], v[196:199], v[170:173], 0
	v_mfma_f32_16x16x32_bf16 v[24:27], v[204:207], v[170:173], 0
	v_mfma_f32_16x16x32_bf16 v[16:19], v[196:199], v[180:183], 0
	v_mfma_f32_16x16x32_bf16 v[8:11], v[204:207], v[180:183], 0
	v_mfma_f32_16x16x32_bf16 v[4:7], v[196:199], v[188:191], 0
	v_mfma_f32_16x16x32_bf16 v[0:3], v[204:207], v[188:191], 0
	v_mfma_f32_16x16x32_bf16 v[50:53], v[200:203], v[166:169], v[50:53]
	v_mfma_f32_16x16x32_bf16 v[40:43], v[208:211], v[166:169], v[40:43]
	v_mfma_f32_16x16x32_bf16 v[32:35], v[200:203], v[176:179], v[32:35]
	v_mfma_f32_16x16x32_bf16 v[24:27], v[208:211], v[176:179], v[24:27]
	v_mfma_f32_16x16x32_bf16 v[16:19], v[200:203], v[184:187], v[16:19]
	v_mfma_f32_16x16x32_bf16 v[8:11], v[208:211], v[184:187], v[8:11]
	v_mfma_f32_16x16x32_bf16 v[4:7], v[200:203], v[192:195], v[4:7]
	v_mfma_f32_16x16x32_bf16 v[0:3], v[208:211], v[192:195], v[0:3]
	s_add_i32 s65, 0, 0x18000
	v_add_u32_e32 v158, s65, v143
	s_barrier
	ds_read_b128 v[146:149], v158
	ds_read_b128 v[150:153], v158 offset:1024
	ds_read_b128 v[154:157], v158 offset:2048
	ds_read_b128 v[158:161], v158 offset:3072
	s_add_u32 s36, s36, 0x40000
	s_addc_u32 s37, s37, 0
	s_mov_b32 m0, s47
	v_lshl_add_u64 v[196:197], s[36:37], 0, v[134:135]
	ds_read_b128 v[162:165], v145 offset:32768
	ds_read_b128 v[166:169], v145 offset:33792
	ds_read_b128 v[170:173], v145 offset:34816
	ds_read_b128 v[176:179], v145 offset:35840
	ds_read_b128 v[180:183], v145 offset:36864
	ds_read_b128 v[184:187], v145 offset:37888
	ds_read_b128 v[188:191], v145 offset:38912
	ds_read_b128 v[192:195], v145 offset:39936
	global_load_lds_dwordx4 v[196:197], off
	v_lshl_add_u64 v[196:197], s[36:37], 0, v[132:133]
	s_mov_b32 m0, s48
	s_nop 0
	global_load_lds_dwordx4 v[196:197], off
	s_waitcnt lgkmcnt(8)
	s_barrier
	s_waitcnt lgkmcnt(7)
	v_mfma_f32_16x16x32_bf16 v[126:129], v[146:149], v[162:165], v[126:129]
	v_mfma_f32_16x16x32_bf16 v[122:125], v[154:157], v[162:165], v[122:125]
	s_waitcnt lgkmcnt(5)
	v_mfma_f32_16x16x32_bf16 v[118:121], v[146:149], v[170:173], v[118:121]
	v_mfma_f32_16x16x32_bf16 v[110:113], v[154:157], v[170:173], v[110:113]
	s_waitcnt lgkmcnt(3)
	v_mfma_f32_16x16x32_bf16 v[102:105], v[146:149], v[180:183], v[102:105]
	v_mfma_f32_16x16x32_bf16 v[94:97], v[154:157], v[180:183], v[94:97]
	s_waitcnt lgkmcnt(1)
	v_mfma_f32_16x16x32_bf16 v[86:89], v[146:149], v[188:191], v[86:89]
	v_mfma_f32_16x16x32_bf16 v[78:81], v[154:157], v[188:191], v[78:81]
	v_mfma_f32_16x16x32_bf16 v[126:129], v[150:153], v[166:169], v[126:129]
	v_mfma_f32_16x16x32_bf16 v[122:125], v[158:161], v[166:169], v[122:125]
	v_mfma_f32_16x16x32_bf16 v[118:121], v[150:153], v[176:179], v[118:121]
	v_mfma_f32_16x16x32_bf16 v[110:113], v[158:161], v[176:179], v[110:113]
	v_mfma_f32_16x16x32_bf16 v[102:105], v[150:153], v[184:187], v[102:105]
	v_mfma_f32_16x16x32_bf16 v[94:97], v[158:161], v[184:187], v[94:97]
	s_waitcnt lgkmcnt(0)
	v_mfma_f32_16x16x32_bf16 v[86:89], v[150:153], v[192:195], v[86:89]
	v_mfma_f32_16x16x32_bf16 v[78:81], v[158:161], v[192:195], v[78:81]
	s_barrier
	s_add_i32 s36, 0, 0x1c000
	s_add_i32 s37, s65, s13
	v_add_u32_e32 v175, s36, v143
	v_lshl_add_u64 v[140:141], v[140:141], 0, s[0:1]
	s_mov_b32 m0, s37
	ds_read_b128 v[196:199], v175
	ds_read_b128 v[200:203], v175 offset:1024
	ds_read_b128 v[204:207], v175 offset:2048
	ds_read_b128 v[208:211], v175 offset:3072
	global_load_lds_dwordx4 v[140:141], off
	v_lshl_add_u64 v[140:141], v[212:213], 0, s[0:1]
	s_add_i32 m0, s37, 0x2000
	s_nop 0
	global_load_lds_dwordx4 v[140:141], off
	s_barrier
; #define PG8_STAGE(bufoff, gbase, voff) do { _Pragma("unroll") for (int _i = 0; _i < 2; ++_i) \
;         __builtin_amdgcn_global_load_lds((const unsigned*)((const char*)(gbase) + (voff)[_i]), (PG8_LAS unsigned*)(lds + (bufoff) + ldsw + _i * 8192), 16, 0, 0); } while (0)
; #define PG8_LDA(dst, b, h) do { _Pragma("unroll") for (int m = 0; m < 4; ++m) _Pragma("unroll") for (int k = 0; k < 2; ++k) dst[m][k] = *(const PG8_LAS bf16x8*)(lds + PG8_SA(b, h) + aoff + m * 2048 + k * 1024); } while (0)
; #define PG8_MMA(ai, bj, At, Bt) do { __builtin_amdgcn_s_setprio(1); _Pragma("unroll") for (int m = 0; m < 4; ++m) _Pragma("unroll") for (int n = 0; n < 2; ++n) _Pragma("unroll") for (int k = 0; k < 2; ++k) \
;         acc[ai][bj][m][n] = __builtin_amdgcn_mfma_f32_16x16x32_bf16(Bt[n][k], At[m][k], acc[ai][bj][m][n], 0, 0, 0); __builtin_amdgcn_s_setprio(0); } while (0)
; #define PG8_WAIT_V(n) asm volatile("s_waitcnt vmcnt(" #n ")" ::: "memory")
; #define PG8_WAIT_L(n) asm volatile("s_waitcnt lgkmcnt(" #n ")" ::: "memory")
; #define PG8_BAR __builtin_amdgcn_s_barrier()
; #define PG8_SCHED __builtin_amdgcn_sched_barrier(0)
; template <class Epi, class Sched>
; __device__ __forceinline__ void gemm_phase(PG8_LAS unsigned char* lds, const Gemm g, const Sched& S, const Epi& E) {
;     ...
;             PG8_BAR; PG8_WAIT_L(0); PG8_MMA(0, 1, At, B1); PG8_BAR;
;             PG8_LDA(At, 1, 1); PG8_STAGE(PG8_SA(1, 0), a3, voffA);
;             PG8_BAR; PG8_WAIT_L(0); PG8_MMA(1, 0, At, B0); PG8_BAR; PG8_SCHED;
;             PG8_STAGE(PG8_SB(1, 1), b3 + hstep, voffB);
;             PG8_WAIT_V(6); PG8_BAR; PG8_MMA(1, 1, At, B1); PG8_BAR;
	s_waitcnt lgkmcnt(3)
	v_mfma_f32_16x16x32_bf16 v[114:117], v[196:199], v[162:165], v[114:117]
	s_waitcnt lgkmcnt(1)
	v_mfma_f32_16x16x32_bf16 v[106:109], v[204:207], v[162:165], v[106:109]
	v_mfma_f32_16x16x32_bf16 v[98:101], v[196:199], v[170:173], v[98:101]
	v_mfma_f32_16x16x32_bf16 v[90:93], v[204:207], v[170:173], v[90:93]
	v_mfma_f32_16x16x32_bf16 v[82:85], v[196:199], v[180:183], v[82:85]
	v_mfma_f32_16x16x32_bf16 v[74:77], v[204:207], v[180:183], v[74:77]
	v_mfma_f32_16x16x32_bf16 v[70:73], v[196:199], v[188:191], v[70:73]
	v_mfma_f32_16x16x32_bf16 v[66:69], v[204:207], v[188:191], v[66:69]
	v_mfma_f32_16x16x32_bf16 v[114:117], v[200:203], v[166:169], v[114:117]
	s_waitcnt lgkmcnt(0)
	v_mfma_f32_16x16x32_bf16 v[106:109], v[208:211], v[166:169], v[106:109]
	v_mfma_f32_16x16x32_bf16 v[98:101], v[200:203], v[176:179], v[98:101]
	v_mfma_f32_16x16x32_bf16 v[90:93], v[208:211], v[176:179], v[90:93]
	v_mfma_f32_16x16x32_bf16 v[82:85], v[200:203], v[184:187], v[82:85]
	v_mfma_f32_16x16x32_bf16 v[74:77], v[208:211], v[184:187], v[74:77]
	v_mfma_f32_16x16x32_bf16 v[70:73], v[200:203], v[192:195], v[70:73]
	v_mfma_f32_16x16x32_bf16 v[66:69], v[208:211], v[192:195], v[66:69]
	s_mov_b32 m0, s49
	v_lshl_add_u64 v[140:141], v[214:215], 0, s[0:1]
	s_barrier
	ds_read_b128 v[162:165], v145 offset:49152
	ds_read_b128 v[166:169], v145 offset:50176
	ds_read_b128 v[170:173], v145 offset:51200
	ds_read_b128 v[176:179], v145 offset:52224
	ds_read_b128 v[180:183], v145 offset:53248
	ds_read_b128 v[184:187], v145 offset:54272
	ds_read_b128 v[188:191], v145 offset:55296
	ds_read_b128 v[192:195], v145 offset:56320
	global_load_lds_dwordx4 v[140:141], off
	v_lshl_add_u64 v[140:141], v[216:217], 0, s[0:1]
	s_mov_b32 m0, s50
	s_nop 0
	global_load_lds_dwordx4 v[140:141], off
	s_barrier
	s_waitcnt lgkmcnt(7)
	v_mfma_f32_16x16x32_bf16 v[62:65], v[146:149], v[162:165], v[62:65]
	v_mfma_f32_16x16x32_bf16 v[58:61], v[154:157], v[162:165], v[58:61]
	s_waitcnt lgkmcnt(5)
	v_mfma_f32_16x16x32_bf16 v[54:57], v[146:149], v[170:173], v[54:57]
	v_mfma_f32_16x16x32_bf16 v[44:47], v[154:157], v[170:173], v[44:47]
	s_waitcnt lgkmcnt(3)
	v_mfma_f32_16x16x32_bf16 v[36:39], v[146:149], v[180:183], v[36:39]
	v_mfma_f32_16x16x32_bf16 v[28:31], v[154:157], v[180:183], v[28:31]
	s_waitcnt lgkmcnt(1)
	v_mfma_f32_16x16x32_bf16 v[20:23], v[146:149], v[188:191], v[20:23]
	v_mfma_f32_16x16x32_bf16 v[12:15], v[154:157], v[188:191], v[12:15]
	v_mfma_f32_16x16x32_bf16 v[62:65], v[150:153], v[166:169], v[62:65]
	v_mfma_f32_16x16x32_bf16 v[58:61], v[158:161], v[166:169], v[58:61]
	v_mfma_f32_16x16x32_bf16 v[54:57], v[150:153], v[176:179], v[54:57]
	v_mfma_f32_16x16x32_bf16 v[44:47], v[158:161], v[176:179], v[44:47]
	v_mfma_f32_16x16x32_bf16 v[36:39], v[150:153], v[184:187], v[36:39]
	v_mfma_f32_16x16x32_bf16 v[28:31], v[158:161], v[184:187], v[28:31]
	s_waitcnt lgkmcnt(0)
	v_mfma_f32_16x16x32_bf16 v[20:23], v[150:153], v[192:195], v[20:23]
	v_mfma_f32_16x16x32_bf16 v[12:15], v[158:161], v[192:195], v[12:15]
	s_barrier
	s_add_u32 s34, s34, 0x40080
	s_addc_u32 s35, s35, 0
	s_add_i32 s36, s36, s13
	v_lshl_add_u64 v[140:141], s[34:35], 0, v[48:49]
	s_mov_b32 m0, s36
	s_nop 0
	global_load_lds_dwordx4 v[140:141], off
	v_lshl_add_u64 v[140:141], s[34:35], 0, v[130:131]
	s_add_i32 m0, s36, 0x2000
	s_nop 0
	global_load_lds_dwordx4 v[140:141], off
	s_add_i32 s64, s64, 2
	s_add_u32 s30, s30, 0x100
	s_addc_u32 s31, s31, 0
	s_add_u32 s59, s59, 0x100
	s_addc_u32 s63, s63, 0
	s_cmp_gt_u32 s64, 13
	s_waitcnt vmcnt(6)
	s_barrier
	v_mfma_f32_16x16x32_bf16 v[50:53], v[196:199], v[162:165], v[50:53]
	v_mfma_f32_16x16x32_bf16 v[40:43], v[204:207], v[162:165], v[40:43]
	v_mfma_f32_16x16x32_bf16 v[32:35], v[196:199], v[170:173], v[32:35]
	v_mfma_f32_16x16x32_bf16 v[24:27], v[204:207], v[170:173], v[24:27]
	v_mfma_f32_16x16x32_bf16 v[16:19], v[196:199], v[180:183], v[16:19]
	v_mfma_f32_16x16x32_bf16 v[8:11], v[204:207], v[180:183], v[8:11]
	v_mfma_f32_16x16x32_bf16 v[4:7], v[196:199], v[188:191], v[4:7]
	v_mfma_f32_16x16x32_bf16 v[0:3], v[204:207], v[188:191], v[0:3]
	v_mfma_f32_16x16x32_bf16 v[50:53], v[200:203], v[166:169], v[50:53]
	v_mfma_f32_16x16x32_bf16 v[40:43], v[208:211], v[166:169], v[40:43]
	v_mfma_f32_16x16x32_bf16 v[32:35], v[200:203], v[176:179], v[32:35]
	v_mfma_f32_16x16x32_bf16 v[24:27], v[208:211], v[176:179], v[24:27]
	v_mfma_f32_16x16x32_bf16 v[16:19], v[200:203], v[184:187], v[16:19]
	v_mfma_f32_16x16x32_bf16 v[8:11], v[208:211], v[184:187], v[8:11]
	v_mfma_f32_16x16x32_bf16 v[4:7], v[200:203], v[192:195], v[4:7]
	v_mfma_f32_16x16x32_bf16 v[0:3], v[208:211], v[192:195], v[0:3]
	s_barrier
	s_cbranch_scc1 .Lkpeel_exit_320
; #define PG8_STAGE(bufoff, gbase, voff) do { _Pragma("unroll") for (int _i = 0; _i < 2; ++_i) \
;         __builtin_amdgcn_global_load_lds((const unsigned*)((const char*)(gbase) + (voff)[_i]), (PG8_LAS unsigned*)(lds + (bufoff) + ldsw + _i * 8192), 16, 0, 0); } while (0)
; #define PG8_LDA(dst, b, h) do { _Pragma("unroll") for (int m = 0; m < 4; ++m) _Pragma("unroll") for (int k = 0; k < 2; ++k) dst[m][k] = *(const PG8_LAS bf16x8*)(lds + PG8_SA(b, h) + aoff + m * 2048 + k * 1024); } while (0)
; #define PG8_LDB(dst, b, h) do { _Pragma("unroll") for (int n = 0; n < 2; ++n) _Pragma("unroll") for (int k = 0; k < 2; ++k) dst[n][k] = *(const PG8_LAS bf16x8*)(lds + PG8_SB(b, h) + boff + n * 2048 + k * 1024); } while (0)
; #define PG8_MMA(ai, bj, At, Bt) do { __builtin_amdgcn_s_setprio(1); _Pragma("unroll") for (int m = 0; m < 4; ++m) _Pragma("unroll") for (int n = 0; n < 2; ++n) _Pragma("unroll") for (int k = 0; k < 2; ++k) \
;         acc[ai][bj][m][n] = __builtin_amdgcn_mfma_f32_16x16x32_bf16(Bt[n][k], At[m][k], acc[ai][bj][m][n], 0, 0, 0); __builtin_amdgcn_s_setprio(0); } while (0)
; #define PG8_WAIT_L(n) asm volatile("s_waitcnt lgkmcnt(" #n ")" ::: "memory")
; #define PG8_BAR __builtin_amdgcn_s_barrier()
; #define PG8_SCHED __builtin_amdgcn_sched_barrier(0)
; template <class Epi, class Sched>
; __device__ __forceinline__ void gemm_phase(PG8_LAS unsigned char* lds, const Gemm g, const Sched& S, const Epi& E) {
;     ...
;             const char* a1 = cA + (size_t)(t + 1) * kstep;
;             const char* a2 = last ? nA : cA + (size_t)(t + 2) * kstep; const char* b2 = last ? nB : cB + (size_t)(t + 2) * kstep;
;             const char* a3 = a2 + kstep; const char* b3 = b2 + kstep;
;             if (last && has_next) S.a_ready(nxt);
;             PG8_LDB(B0, 0, 0); PG8_SCHED; PG8_LDA(At, 0, 0); PG8_STAGE(PG8_SA(1, 1), a1 + hstep, voffA);
;             PG8_WAIT_L(8); PG8_BAR; PG8_WAIT_L(0); PG8_MMA(0, 0, At, B0); PG8_BAR; PG8_SCHED;
;             PG8_LDB(B1, 0, 1); PG8_STAGE(PG8_SB(0, 0), b2, voffB);
;             PG8_BAR; PG8_WAIT_L(0); PG8_MMA(0, 1, At, B1); PG8_BAR;
;             PG8_LDA(At, 0, 1); PG8_STAGE(PG8_SA(0, 0), a2, voffA);
;             PG8_BAR; PG8_WAIT_L(0); PG8_MMA(1, 0, At, B0); PG8_BAR; PG8_SCHED;
.LBB0_320:
	s_add_u32 s34, s30, 0xfffc0080
	s_addc_u32 s35, s31, -1
	s_add_i32 s65, 0, 0x10000
	v_add_u32_e32 v140, s65, v143
	ds_read_b128 v[146:149], v140
	ds_read_b128 v[150:153], v140 offset:1024
	ds_read_b128 v[154:157], v140 offset:2048
	ds_read_b128 v[158:161], v140 offset:3072
	s_cmp_eq_u32 s64, 12
	s_cselect_b32 s37, s25, s35
	s_cselect_b32 s36, s56, s34
	s_cselect_b32 s35, s23, s63
	s_cselect_b32 s34, s57, s59
	v_lshl_add_u64 v[140:141], s[30:31], 0, v[136:137]
	s_add_i32 m0, s21, 0xc000
	ds_read_b128 v[162:165], v145
	ds_read_b128 v[166:169], v145 offset:1024
	ds_read_b128 v[170:173], v145 offset:2048
	ds_read_b128 v[176:179], v145 offset:3072
	ds_read_b128 v[180:183], v145 offset:4096
	ds_read_b128 v[184:187], v145 offset:5120
	ds_read_b128 v[188:191], v145 offset:6144
	ds_read_b128 v[192:195], v145 offset:7168
	global_load_lds_dwordx4 v[140:141], off
	v_lshl_add_u64 v[140:141], s[30:31], 0, v[138:139]
	s_add_i32 m0, s21, 0xe000
	s_nop 0
	global_load_lds_dwordx4 v[140:141], off
	s_waitcnt lgkmcnt(8)
	s_barrier
	s_waitcnt lgkmcnt(7)
	v_mfma_f32_16x16x32_bf16 v[126:129], v[146:149], v[162:165], v[126:129]
	v_mfma_f32_16x16x32_bf16 v[122:125], v[154:157], v[162:165], v[122:125]
	s_waitcnt lgkmcnt(5)
	v_mfma_f32_16x16x32_bf16 v[118:121], v[146:149], v[170:173], v[118:121]
	v_mfma_f32_16x16x32_bf16 v[110:113], v[154:157], v[170:173], v[110:113]
	s_waitcnt lgkmcnt(3)
	v_mfma_f32_16x16x32_bf16 v[102:105], v[146:149], v[180:183], v[102:105]
	v_mfma_f32_16x16x32_bf16 v[94:97], v[154:157], v[180:183], v[94:97]
	s_waitcnt lgkmcnt(1)
	v_mfma_f32_16x16x32_bf16 v[86:89], v[146:149], v[188:191], v[86:89]
	v_mfma_f32_16x16x32_bf16 v[78:81], v[154:157], v[188:191], v[78:81]
	v_mfma_f32_16x16x32_bf16 v[126:129], v[150:153], v[166:169], v[126:129]
	v_mfma_f32_16x16x32_bf16 v[122:125], v[158:161], v[166:169], v[122:125]
	v_mfma_f32_16x16x32_bf16 v[118:121], v[150:153], v[176:179], v[118:121]
	v_mfma_f32_16x16x32_bf16 v[110:113], v[158:161], v[176:179], v[110:113]
	v_mfma_f32_16x16x32_bf16 v[102:105], v[150:153], v[184:187], v[102:105]
	v_mfma_f32_16x16x32_bf16 v[94:97], v[158:161], v[184:187], v[94:97]
	s_waitcnt lgkmcnt(0)
	v_mfma_f32_16x16x32_bf16 v[86:89], v[150:153], v[192:195], v[86:89]
	v_mfma_f32_16x16x32_bf16 v[78:81], v[158:161], v[192:195], v[78:81]
	s_barrier
	s_add_i32 s68, 0, 0x14000
	v_add_u32_e32 v140, s68, v143
	s_add_i32 s65, s65, s13
	ds_read_b128 v[196:199], v140
	ds_read_b128 v[200:203], v140 offset:1024
	ds_read_b128 v[204:207], v140 offset:2048
	ds_read_b128 v[208:211], v140 offset:3072
	v_lshl_add_u64 v[140:141], s[34:35], 0, v[48:49]
	s_mov_b32 m0, s65
	v_lshl_add_u64 v[212:213], s[34:35], 0, v[130:131]
	global_load_lds_dwordx4 v[140:141], off
	s_add_i32 m0, s65, 0x2000
	s_nop 0
	global_load_lds_dwordx4 v[212:213], off
	s_barrier
	s_waitcnt lgkmcnt(3)
	v_mfma_f32_16x16x32_bf16 v[114:117], v[196:199], v[162:165], v[114:117]
	s_waitcnt lgkmcnt(1)
	v_mfma_f32_16x16x32_bf16 v[106:109], v[204:207], v[162:165], v[106:109]
	v_mfma_f32_16x16x32_bf16 v[98:101], v[196:199], v[170:173], v[98:101]
	v_mfma_f32_16x16x32_bf16 v[90:93], v[204:207], v[170:173], v[90:93]
	v_mfma_f32_16x16x32_bf16 v[82:85], v[196:199], v[180:183], v[82:85]
	v_mfma_f32_16x16x32_bf16 v[74:77], v[204:207], v[180:183], v[74:77]
	v_mfma_f32_16x16x32_bf16 v[70:73], v[196:199], v[188:191], v[70:73]
	v_mfma_f32_16x16x32_bf16 v[66:69], v[204:207], v[188:191], v[66:69]
	v_mfma_f32_16x16x32_bf16 v[114:117], v[200:203], v[166:169], v[114:117]
	s_waitcnt lgkmcnt(0)
	v_mfma_f32_16x16x32_bf16 v[106:109], v[208:211], v[166:169], v[106:109]
	v_mfma_f32_16x16x32_bf16 v[98:101], v[200:203], v[176:179], v[98:101]
	v_mfma_f32_16x16x32_bf16 v[90:93], v[208:211], v[176:179], v[90:93]
	v_mfma_f32_16x16x32_bf16 v[82:85], v[200:203], v[184:187], v[82:85]
	v_mfma_f32_16x16x32_bf16 v[74:77], v[208:211], v[184:187], v[74:77]
	v_mfma_f32_16x16x32_bf16 v[70:73], v[200:203], v[192:195], v[70:73]
	v_mfma_f32_16x16x32_bf16 v[66:69], v[208:211], v[192:195], v[66:69]
	s_mov_b32 m0, s21
	v_lshl_add_u64 v[214:215], s[36:37], 0, v[134:135]
	s_barrier
	ds_read_b128 v[162:165], v145 offset:16384
	ds_read_b128 v[166:169], v145 offset:17408
	ds_read_b128 v[170:173], v145 offset:18432
	ds_read_b128 v[176:179], v145 offset:19456
	ds_read_b128 v[180:183], v145 offset:20480
	ds_read_b128 v[184:187], v145 offset:21504
	ds_read_b128 v[188:191], v145 offset:22528
	ds_read_b128 v[192:195], v145 offset:23552
	global_load_lds_dwordx4 v[214:215], off
	v_lshl_add_u64 v[216:217], s[36:37], 0, v[132:133]
	s_mov_b32 m0, s46
	s_nop 0
	global_load_lds_dwordx4 v[216:217], off
	s_barrier
	s_waitcnt lgkmcnt(7)
	v_mfma_f32_16x16x32_bf16 v[62:65], v[146:149], v[162:165], v[62:65]
	v_mfma_f32_16x16x32_bf16 v[58:61], v[154:157], v[162:165], v[58:61]
	s_waitcnt lgkmcnt(5)
	v_mfma_f32_16x16x32_bf16 v[54:57], v[146:149], v[170:173], v[54:57]
	v_mfma_f32_16x16x32_bf16 v[44:47], v[154:157], v[170:173], v[44:47]
	s_waitcnt lgkmcnt(3)
	v_mfma_f32_16x16x32_bf16 v[36:39], v[146:149], v[180:183], v[36:39]
	v_mfma_f32_16x16x32_bf16 v[28:31], v[154:157], v[180:183], v[28:31]
	s_waitcnt lgkmcnt(1)
	v_mfma_f32_16x16x32_bf16 v[20:23], v[146:149], v[188:191], v[20:23]
	v_mfma_f32_16x16x32_bf16 v[12:15], v[154:157], v[188:191], v[12:15]
	v_mfma_f32_16x16x32_bf16 v[62:65], v[150:153], v[166:169], v[62:65]
	v_mfma_f32_16x16x32_bf16 v[58:61], v[158:161], v[166:169], v[58:61]
	v_mfma_f32_16x16x32_bf16 v[54:57], v[150:153], v[176:179], v[54:57]
	v_mfma_f32_16x16x32_bf16 v[44:47], v[158:161], v[176:179], v[44:47]
	v_mfma_f32_16x16x32_bf16 v[36:39], v[150:153], v[184:187], v[36:39]
	v_mfma_f32_16x16x32_bf16 v[28:31], v[158:161], v[184:187], v[28:31]
	s_waitcnt lgkmcnt(0)
	v_mfma_f32_16x16x32_bf16 v[20:23], v[150:153], v[192:195], v[20:23]
	v_mfma_f32_16x16x32_bf16 v[12:15], v[158:161], v[192:195], v[12:15]
	s_barrier
; #define PG8_STAGE(bufoff, gbase, voff) do { _Pragma("unroll") for (int _i = 0; _i < 2; ++_i) \
;         __builtin_amdgcn_global_load_lds((const unsigned*)((const char*)(gbase) + (voff)[_i]), (PG8_LAS unsigned*)(lds + (bufoff) + ldsw + _i * 8192), 16, 0, 0); } while (0)
; #define PG8_LDA(dst, b, h) do { _Pragma("unroll") for (int m = 0; m < 4; ++m) _Pragma("unroll") for (int k = 0; k < 2; ++k) dst[m][k] = *(const PG8_LAS bf16x8*)(lds + PG8_SA(b, h) + aoff + m * 2048 + k * 1024); } while (0)
; #define PG8_LDB(dst, b, h) do { _Pragma("unroll") for (int n = 0; n < 2; ++n) _Pragma("unroll") for (int k = 0; k < 2; ++k) dst[n][k] = *(const PG8_LAS bf16x8*)(lds + PG8_SB(b, h) + boff + n * 2048 + k * 1024); } while (0)
; #define PG8_MMA(ai, bj, At, Bt) do { __builtin_amdgcn_s_setprio(1); _Pragma("unroll") for (int m = 0; m < 4; ++m) _Pragma("unroll") for (int n = 0; n < 2; ++n) _Pragma("unroll") for (int k = 0; k < 2; ++k) \
;         acc[ai][bj][m][n] = __builtin_amdgcn_mfma_f32_16x16x32_bf16(Bt[n][k], At[m][k], acc[ai][bj][m][n], 0, 0, 0); __builtin_amdgcn_s_setprio(0); } while (0)
; #define PG8_WAIT_V(n) asm volatile("s_waitcnt vmcnt(" #n ")" ::: "memory")
; #define PG8_WAIT_L(n) asm volatile("s_waitcnt lgkmcnt(" #n ")" ::: "memory")
; #define PG8_BAR __builtin_amdgcn_s_barrier()
; #define PG8_SCHED __builtin_amdgcn_sched_barrier(0)
; template <class Epi, class Sched>
; __device__ __forceinline__ void gemm_phase(PG8_LAS unsigned char* lds, const Gemm g, const Sched& S, const Epi& E) {
;     ...
;             PG8_STAGE(PG8_SB(0, 1), b2 + hstep, voffB);
;             PG8_WAIT_V(6); PG8_BAR; PG8_MMA(1, 1, At, B1); PG8_BAR;
;             PG8_LDB(B0, 1, 0); PG8_SCHED; PG8_LDA(At, 1, 0); PG8_STAGE(PG8_SA(0, 1), a2 + hstep, voffA);
;             PG8_WAIT_L(8); PG8_BAR; PG8_WAIT_L(0); PG8_MMA(0, 0, At, B0); PG8_BAR; PG8_SCHED;
;             PG8_LDB(B1, 1, 1); PG8_STAGE(PG8_SB(1, 0), b3, voffB);
	s_add_u32 s66, s34, 0x40000
	s_addc_u32 s67, s35, 0
	s_add_i32 s65, s68, s13
	v_lshl_add_u64 v[146:147], s[66:67], 0, v[48:49]
	s_mov_b32 m0, s65
	s_nop 0
	global_load_lds_dwordx4 v[146:147], off
	v_lshl_add_u64 v[146:147], s[66:67], 0, v[130:131]
	s_add_i32 m0, s65, 0x2000
	s_nop 0
	global_load_lds_dwordx4 v[146:147], off
	s_waitcnt vmcnt(6)
	s_barrier
	v_mfma_f32_16x16x32_bf16 v[50:53], v[196:199], v[162:165], v[50:53]
	v_mfma_f32_16x16x32_bf16 v[40:43], v[204:207], v[162:165], v[40:43]
	v_mfma_f32_16x16x32_bf16 v[32:35], v[196:199], v[170:173], v[32:35]
	v_mfma_f32_16x16x32_bf16 v[24:27], v[204:207], v[170:173], v[24:27]
	v_mfma_f32_16x16x32_bf16 v[16:19], v[196:199], v[180:183], v[16:19]
	v_mfma_f32_16x16x32_bf16 v[8:11], v[204:207], v[180:183], v[8:11]
	v_mfma_f32_16x16x32_bf16 v[4:7], v[196:199], v[188:191], v[4:7]
	v_mfma_f32_16x16x32_bf16 v[0:3], v[204:207], v[188:191], v[0:3]
	v_mfma_f32_16x16x32_bf16 v[50:53], v[200:203], v[166:169], v[50:53]
	v_mfma_f32_16x16x32_bf16 v[40:43], v[208:211], v[166:169], v[40:43]
	v_mfma_f32_16x16x32_bf16 v[32:35], v[200:203], v[176:179], v[32:35]
	v_mfma_f32_16x16x32_bf16 v[24:27], v[208:211], v[176:179], v[24:27]
	v_mfma_f32_16x16x32_bf16 v[16:19], v[200:203], v[184:187], v[16:19]
	v_mfma_f32_16x16x32_bf16 v[8:11], v[208:211], v[184:187], v[8:11]
	v_mfma_f32_16x16x32_bf16 v[4:7], v[200:203], v[192:195], v[4:7]
	v_mfma_f32_16x16x32_bf16 v[0:3], v[208:211], v[192:195], v[0:3]
	s_add_i32 s65, 0, 0x18000
	v_add_u32_e32 v158, s65, v143
	s_barrier
	ds_read_b128 v[146:149], v158
	ds_read_b128 v[150:153], v158 offset:1024
	ds_read_b128 v[154:157], v158 offset:2048
	ds_read_b128 v[158:161], v158 offset:3072
	s_add_u32 s36, s36, 0x40000
	s_addc_u32 s37, s37, 0
	s_mov_b32 m0, s47
	v_lshl_add_u64 v[196:197], s[36:37], 0, v[134:135]
	ds_read_b128 v[162:165], v145 offset:32768
	ds_read_b128 v[166:169], v145 offset:33792
	ds_read_b128 v[170:173], v145 offset:34816
	ds_read_b128 v[176:179], v145 offset:35840
	ds_read_b128 v[180:183], v145 offset:36864
	ds_read_b128 v[184:187], v145 offset:37888
	ds_read_b128 v[188:191], v145 offset:38912
	ds_read_b128 v[192:195], v145 offset:39936
	global_load_lds_dwordx4 v[196:197], off
	v_lshl_add_u64 v[196:197], s[36:37], 0, v[132:133]
	s_mov_b32 m0, s48
	s_nop 0
	global_load_lds_dwordx4 v[196:197], off
	s_waitcnt lgkmcnt(8)
	s_barrier
	s_waitcnt lgkmcnt(7)
	v_mfma_f32_16x16x32_bf16 v[126:129], v[146:149], v[162:165], v[126:129]
	v_mfma_f32_16x16x32_bf16 v[122:125], v[154:157], v[162:165], v[122:125]
	s_waitcnt lgkmcnt(5)
	v_mfma_f32_16x16x32_bf16 v[118:121], v[146:149], v[170:173], v[118:121]
	v_mfma_f32_16x16x32_bf16 v[110:113], v[154:157], v[170:173], v[110:113]
	s_waitcnt lgkmcnt(3)
	v_mfma_f32_16x16x32_bf16 v[102:105], v[146:149], v[180:183], v[102:105]
	v_mfma_f32_16x16x32_bf16 v[94:97], v[154:157], v[180:183], v[94:97]
	s_waitcnt lgkmcnt(1)
	v_mfma_f32_16x16x32_bf16 v[86:89], v[146:149], v[188:191], v[86:89]
	v_mfma_f32_16x16x32_bf16 v[78:81], v[154:157], v[188:191], v[78:81]
	v_mfma_f32_16x16x32_bf16 v[126:129], v[150:153], v[166:169], v[126:129]
	v_mfma_f32_16x16x32_bf16 v[122:125], v[158:161], v[166:169], v[122:125]
	v_mfma_f32_16x16x32_bf16 v[118:121], v[150:153], v[176:179], v[118:121]
	v_mfma_f32_16x16x32_bf16 v[110:113], v[158:161], v[176:179], v[110:113]
	v_mfma_f32_16x16x32_bf16 v[102:105], v[150:153], v[184:187], v[102:105]
	v_mfma_f32_16x16x32_bf16 v[94:97], v[158:161], v[184:187], v[94:97]
	s_waitcnt lgkmcnt(0)
	v_mfma_f32_16x16x32_bf16 v[86:89], v[150:153], v[192:195], v[86:89]
	v_mfma_f32_16x16x32_bf16 v[78:81], v[158:161], v[192:195], v[78:81]
	s_barrier
	s_add_i32 s36, 0, 0x1c000
	s_add_i32 s37, s65, s13
	v_add_u32_e32 v175, s36, v143
	v_lshl_add_u64 v[140:141], v[140:141], 0, s[0:1]
	s_mov_b32 m0, s37
	ds_read_b128 v[196:199], v175
	ds_read_b128 v[200:203], v175 offset:1024
	ds_read_b128 v[204:207], v175 offset:2048
	ds_read_b128 v[208:211], v175 offset:3072
	global_load_lds_dwordx4 v[140:141], off
	v_lshl_add_u64 v[140:141], v[212:213], 0, s[0:1]
	s_add_i32 m0, s37, 0x2000
	s_nop 0
	global_load_lds_dwordx4 v[140:141], off
	s_barrier
; #define PG8_STAGE(bufoff, gbase, voff) do { _Pragma("unroll") for (int _i = 0; _i < 2; ++_i) \
;         __builtin_amdgcn_global_load_lds((const unsigned*)((const char*)(gbase) + (voff)[_i]), (PG8_LAS unsigned*)(lds + (bufoff) + ldsw + _i * 8192), 16, 0, 0); } while (0)
; #define PG8_LDA(dst, b, h) do { _Pragma("unroll") for (int m = 0; m < 4; ++m) _Pragma("unroll") for (int k = 0; k < 2; ++k) dst[m][k] = *(const PG8_LAS bf16x8*)(lds + PG8_SA(b, h) + aoff + m * 2048 + k * 1024); } while (0)
; #define PG8_MMA(ai, bj, At, Bt) do { __builtin_amdgcn_s_setprio(1); _Pragma("unroll") for (int m = 0; m < 4; ++m) _Pragma("unroll") for (int n = 0; n < 2; ++n) _Pragma("unroll") for (int k = 0; k < 2; ++k) \
;         acc[ai][bj][m][n] = __builtin_amdgcn_mfma_f32_16x16x32_bf16(Bt[n][k], At[m][k], acc[ai][bj][m][n], 0, 0, 0); __builtin_amdgcn_s_setprio(0); } while (0)
; #define PG8_WAIT_V(n) asm volatile("s_waitcnt vmcnt(" #n ")" ::: "memory")
; #define PG8_WAIT_L(n) asm volatile("s_waitcnt lgkmcnt(" #n ")" ::: "memory")
; #define PG8_BAR __builtin_amdgcn_s_barrier()
; #define PG8_SCHED __builtin_amdgcn_sched_barrier(0)
; template <class Epi, class Sched>
; __device__ __forceinline__ void gemm_phase(PG8_LAS unsigned char* lds, const Gemm g, const Sched& S, const Epi& E) {
;     ...
;             PG8_BAR; PG8_WAIT_L(0); PG8_MMA(0, 1, At, B1); PG8_BAR;
;             PG8_LDA(At, 1, 1); PG8_STAGE(PG8_SA(1, 0), a3, voffA);
;             PG8_BAR; PG8_WAIT_L(0); PG8_MMA(1, 0, At, B0); PG8_BAR; PG8_SCHED;
;             PG8_STAGE(PG8_SB(1, 1), b3 + hstep, voffB);
;             PG8_WAIT_V(6); PG8_BAR; PG8_MMA(1, 1, At, B1); PG8_BAR;
	s_waitcnt lgkmcnt(3)
	v_mfma_f32_16x16x32_bf16 v[114:117], v[196:199], v[162:165], v[114:117]
	s_waitcnt lgkmcnt(1)
	v_mfma_f32_16x16x32_bf16 v[106:109], v[204:207], v[162:165], v[106:109]
	v_mfma_f32_16x16x32_bf16 v[98:101], v[196:199], v[170:173], v[98:101]
	v_mfma_f32_16x16x32_bf16 v[90:93], v[204:207], v[170:173], v[90:93]
	v_mfma_f32_16x16x32_bf16 v[82:85], v[196:199], v[180:183], v[82:85]
	v_mfma_f32_16x16x32_bf16 v[74:77], v[204:207], v[180:183], v[74:77]
	v_mfma_f32_16x16x32_bf16 v[70:73], v[196:199], v[188:191], v[70:73]
	v_mfma_f32_16x16x32_bf16 v[66:69], v[204:207], v[188:191], v[66:69]
	v_mfma_f32_16x16x32_bf16 v[114:117], v[200:203], v[166:169], v[114:117]
	s_waitcnt lgkmcnt(0)
	v_mfma_f32_16x16x32_bf16 v[106:109], v[208:211], v[166:169], v[106:109]
	v_mfma_f32_16x16x32_bf16 v[98:101], v[200:203], v[176:179], v[98:101]
	v_mfma_f32_16x16x32_bf16 v[90:93], v[208:211], v[176:179], v[90:93]
	v_mfma_f32_16x16x32_bf16 v[82:85], v[200:203], v[184:187], v[82:85]
	v_mfma_f32_16x16x32_bf16 v[74:77], v[208:211], v[184:187], v[74:77]
	v_mfma_f32_16x16x32_bf16 v[70:73], v[200:203], v[192:195], v[70:73]
	v_mfma_f32_16x16x32_bf16 v[66:69], v[208:211], v[192:195], v[66:69]
	s_mov_b32 m0, s49
	v_lshl_add_u64 v[140:141], v[214:215], 0, s[0:1]
	s_barrier
	ds_read_b128 v[162:165], v145 offset:49152
	ds_read_b128 v[166:169], v145 offset:50176
	ds_read_b128 v[170:173], v145 offset:51200
	ds_read_b128 v[176:179], v145 offset:52224
	ds_read_b128 v[180:183], v145 offset:53248
	ds_read_b128 v[184:187], v145 offset:54272
	ds_read_b128 v[188:191], v145 offset:55296
	ds_read_b128 v[192:195], v145 offset:56320
	global_load_lds_dwordx4 v[140:141], off
	v_lshl_add_u64 v[140:141], v[216:217], 0, s[0:1]
	s_mov_b32 m0, s50
	s_nop 0
	global_load_lds_dwordx4 v[140:141], off
	s_barrier
	s_waitcnt lgkmcnt(7)
	v_mfma_f32_16x16x32_bf16 v[62:65], v[146:149], v[162:165], v[62:65]
	v_mfma_f32_16x16x32_bf16 v[58:61], v[154:157], v[162:165], v[58:61]
	s_waitcnt lgkmcnt(5)
	v_mfma_f32_16x16x32_bf16 v[54:57], v[146:149], v[170:173], v[54:57]
	v_mfma_f32_16x16x32_bf16 v[44:47], v[154:157], v[170:173], v[44:47]
	s_waitcnt lgkmcnt(3)
	v_mfma_f32_16x16x32_bf16 v[36:39], v[146:149], v[180:183], v[36:39]
	v_mfma_f32_16x16x32_bf16 v[28:31], v[154:157], v[180:183], v[28:31]
	s_waitcnt lgkmcnt(1)
	v_mfma_f32_16x16x32_bf16 v[20:23], v[146:149], v[188:191], v[20:23]
	v_mfma_f32_16x16x32_bf16 v[12:15], v[154:157], v[188:191], v[12:15]
	v_mfma_f32_16x16x32_bf16 v[62:65], v[150:153], v[166:169], v[62:65]
	v_mfma_f32_16x16x32_bf16 v[58:61], v[158:161], v[166:169], v[58:61]
	v_mfma_f32_16x16x32_bf16 v[54:57], v[150:153], v[176:179], v[54:57]
	v_mfma_f32_16x16x32_bf16 v[44:47], v[158:161], v[176:179], v[44:47]
	v_mfma_f32_16x16x32_bf16 v[36:39], v[150:153], v[184:187], v[36:39]
	v_mfma_f32_16x16x32_bf16 v[28:31], v[158:161], v[184:187], v[28:31]
	s_waitcnt lgkmcnt(0)
	v_mfma_f32_16x16x32_bf16 v[20:23], v[150:153], v[192:195], v[20:23]
	v_mfma_f32_16x16x32_bf16 v[12:15], v[158:161], v[192:195], v[12:15]
	s_barrier
	s_add_u32 s34, s34, 0x40080
	s_addc_u32 s35, s35, 0
	s_add_i32 s36, s36, s13
	v_lshl_add_u64 v[140:141], s[34:35], 0, v[48:49]
	s_mov_b32 m0, s36
	s_nop 0
	global_load_lds_dwordx4 v[140:141], off
	v_lshl_add_u64 v[140:141], s[34:35], 0, v[130:131]
	s_add_i32 m0, s36, 0x2000
	s_nop 0
	global_load_lds_dwordx4 v[140:141], off
	s_add_i32 s64, s64, 2
	s_add_u32 s30, s30, 0x100
	s_addc_u32 s31, s31, 0
	s_add_u32 s59, s59, 0x100
	s_addc_u32 s63, s63, 0
	s_cmp_gt_u32 s64, 13
	s_waitcnt vmcnt(6)
	s_barrier
	v_mfma_f32_16x16x32_bf16 v[50:53], v[196:199], v[162:165], v[50:53]
	v_mfma_f32_16x16x32_bf16 v[40:43], v[204:207], v[162:165], v[40:43]
	v_mfma_f32_16x16x32_bf16 v[32:35], v[196:199], v[170:173], v[32:35]
	v_mfma_f32_16x16x32_bf16 v[24:27], v[204:207], v[170:173], v[24:27]
	v_mfma_f32_16x16x32_bf16 v[16:19], v[196:199], v[180:183], v[16:19]
	v_mfma_f32_16x16x32_bf16 v[8:11], v[204:207], v[180:183], v[8:11]
	v_mfma_f32_16x16x32_bf16 v[4:7], v[196:199], v[188:191], v[4:7]
	v_mfma_f32_16x16x32_bf16 v[0:3], v[204:207], v[188:191], v[0:3]
	v_mfma_f32_16x16x32_bf16 v[50:53], v[200:203], v[166:169], v[50:53]
	v_mfma_f32_16x16x32_bf16 v[40:43], v[208:211], v[166:169], v[40:43]
	v_mfma_f32_16x16x32_bf16 v[32:35], v[200:203], v[176:179], v[32:35]
	v_mfma_f32_16x16x32_bf16 v[24:27], v[208:211], v[176:179], v[24:27]
	v_mfma_f32_16x16x32_bf16 v[16:19], v[200:203], v[184:187], v[16:19]
	v_mfma_f32_16x16x32_bf16 v[8:11], v[208:211], v[184:187], v[8:11]
	v_mfma_f32_16x16x32_bf16 v[4:7], v[200:203], v[192:195], v[4:7]
	v_mfma_f32_16x16x32_bf16 v[0:3], v[208:211], v[192:195], v[0:3]
	s_barrier
	s_cbranch_scc0 .LBB0_320

; #define PG8_STAGE(bufoff, gbase, voff) do { _Pragma("unroll") for (int _i = 0; _i < 2; ++_i) \
;         __builtin_amdgcn_global_load_lds((const unsigned*)((const char*)(gbase) + (voff)[_i]), (PG8_LAS unsigned*)(lds + (bufoff) + ldsw + _i * 8192), 16, 0, 0); } while (0)
; #define PG8_LDA(dst, b, h) do { _Pragma("unroll") for (int m = 0; m < 4; ++m) _Pragma("unroll") for (int k = 0; k < 2; ++k) dst[m][k] = *(const PG8_LAS bf16x8*)(lds + PG8_SA(b, h) + aoff + m * 2048 + k * 1024); } while (0)
; #define PG8_LDB(dst, b, h) do { _Pragma("unroll") for (int n = 0; n < 2; ++n) _Pragma("unroll") for (int k = 0; k < 2; ++k) dst[n][k] = *(const PG8_LAS bf16x8*)(lds + PG8_SB(b, h) + boff + n * 2048 + k * 1024); } while (0)
; #define PG8_WAIT_L(n) asm volatile("s_waitcnt lgkmcnt(" #n ")" ::: "memory")
; #define PG8_BAR __builtin_amdgcn_s_barrier()
; #define PG8_SCHED __builtin_amdgcn_sched_barrier(0)
; template <class Epi, class Sched>
; __device__ __forceinline__ void gemm_phase(PG8_LAS unsigned char* lds, const Gemm g, const Sched& S, const Epi& E) {
;     ...
;         const bool has_next = S.next(ui + 1, nxt);
;         const char* nA = has_next ? (const char*)g.A + (size_t)nxt.pm * tstepA + (size_t)nxt.kc * cstep : cA; const char* nB = has_next ? (const char*)g.Bt + (size_t)nxt.pn * tstep + (size_t)nxt.kc * cstep : cB;
;         for (int t = 0; t < nt; t += 2) {
;             const bool last = (t == nt - 2);
;             const char* a1 = cA + (size_t)(t + 1) * kstep;
;             const char* a2 = last ? nA : cA + (size_t)(t + 2) * kstep; const char* b2 = last ? nB : cB + (size_t)(t + 2) * kstep;
;             const char* a3 = a2 + kstep; const char* b3 = b2 + kstep;
;             if (last && has_next) S.a_ready(nxt);
;             PG8_LDB(B0, 0, 0); PG8_SCHED; PG8_LDA(At, 0, 0); PG8_STAGE(PG8_SA(1, 1), a1 + hstep, voffA);
;             PG8_WAIT_L(8); PG8_BAR; PG8_WAIT_L(0); PG8_MMA(0, 0, At, B0); PG8_BAR; PG8_SCHED;
;             PG8_LDB(B1, 0, 1); PG8_STAGE(PG8_SB(0, 0), b2, voffB);
;             PG8_BAR; PG8_WAIT_L(0); PG8_MMA(0, 1, At, B1); PG8_BAR;
;             PG8_LDA(At, 0, 1); PG8_STAGE(PG8_SA(0, 0), a2, voffA);
;             PG8_BAR; PG8_WAIT_L(0); PG8_MMA(1, 0, At, B0); PG8_BAR; PG8_SCHED;
.LBB0_334:
	v_mov_b64_e32 v[0:1], 0x440
	s_ashr_i32 s23, s22, 31
	v_cmp_lt_i64_e32 vcc, s[16:17], v[0:1]
	s_lshl_b64 s[16:17], s[22:23], 19
	s_add_u32 s24, s28, s16
	s_addc_u32 s25, s29, s17
	s_and_b64 s[16:17], vcc, exec
	s_cselect_b32 s23, s25, s7
	s_cselect_b32 s50, s24, s6
	s_ashr_i32 s21, s20, 31
	s_lshl_b64 s[16:17], s[20:21], 19
	s_add_u32 s26, s30, s16
	s_addc_u32 s27, s31, s17
	s_and_b64 s[16:17], vcc, exec
	s_cselect_b32 s21, s27, s13
	s_cselect_b32 s51, s26, s12
	s_add_u32 s6, s6, 0x40080
	s_addc_u32 s7, s7, 0
	s_add_u32 s54, s12, 0x100
	s_addc_u32 s55, s13, 0
	s_mov_b32 s56, -2
	s_add_u32 s12, s6, 0xfffc0080
	s_addc_u32 s13, s7, -1
	s_add_i32 s57, 0, 0x10000
	v_add_u32_e32 v48, s57, v166
	ds_read_b128 v[144:147], v48
	ds_read_b128 v[148:151], v48 offset:1024
	ds_read_b128 v[152:155], v48 offset:2048
	ds_read_b128 v[156:159], v48 offset:3072
	s_cmp_eq_u32 s56, 12
	s_cselect_b32 s17, s23, s13
	s_cselect_b32 s16, s50, s12
	s_cselect_b32 s13, s21, s55
	s_cselect_b32 s12, s51, s54
	v_lshl_add_u64 v[164:165], s[6:7], 0, v[140:141]
	s_add_i32 m0, s3, 0xc000
	ds_read_b128 v[160:163], v167
	ds_read_b128 v[168:171], v167 offset:1024
	ds_read_b128 v[176:179], v167 offset:2048
	ds_read_b128 v[180:183], v167 offset:3072
	ds_read_b128 v[184:187], v167 offset:4096
	ds_read_b128 v[188:191], v167 offset:5120
	ds_read_b128 v[192:195], v167 offset:6144
	ds_read_b128 v[196:199], v167 offset:7168
	global_load_lds_dwordx4 v[164:165], off
	v_lshl_add_u64 v[164:165], s[6:7], 0, v[142:143]
	s_add_i32 m0, s3, 0xe000
	s_nop 0
	global_load_lds_dwordx4 v[164:165], off
	s_waitcnt lgkmcnt(8)
	s_barrier
	s_waitcnt lgkmcnt(7)
	v_mfma_f32_16x16x32_bf16 v[126:129], v[144:147], v[160:163], 0
	v_mfma_f32_16x16x32_bf16 v[122:125], v[152:155], v[160:163], 0
	s_waitcnt lgkmcnt(5)
	v_mfma_f32_16x16x32_bf16 v[110:113], v[144:147], v[176:179], 0
	v_mfma_f32_16x16x32_bf16 v[106:109], v[152:155], v[176:179], 0
	s_waitcnt lgkmcnt(3)
	v_mfma_f32_16x16x32_bf16 v[94:97], v[144:147], v[184:187], 0
	v_mfma_f32_16x16x32_bf16 v[90:93], v[152:155], v[184:187], 0
	s_waitcnt lgkmcnt(1)
	v_mfma_f32_16x16x32_bf16 v[78:81], v[144:147], v[192:195], 0
	v_mfma_f32_16x16x32_bf16 v[74:77], v[152:155], v[192:195], 0
	v_mfma_f32_16x16x32_bf16 v[126:129], v[148:151], v[168:171], v[126:129]
	v_mfma_f32_16x16x32_bf16 v[122:125], v[156:159], v[168:171], v[122:125]
	v_mfma_f32_16x16x32_bf16 v[110:113], v[148:151], v[180:183], v[110:113]
	v_mfma_f32_16x16x32_bf16 v[106:109], v[156:159], v[180:183], v[106:109]
	v_mfma_f32_16x16x32_bf16 v[94:97], v[148:151], v[188:191], v[94:97]
	v_mfma_f32_16x16x32_bf16 v[90:93], v[156:159], v[188:191], v[90:93]
	s_waitcnt lgkmcnt(0)
	v_mfma_f32_16x16x32_bf16 v[78:81], v[148:151], v[196:199], v[78:81]
	v_mfma_f32_16x16x32_bf16 v[74:77], v[156:159], v[196:199], v[74:77]
	s_barrier
	s_add_i32 s59, 0, 0x14000
	s_add_i32 s57, s57, s34
	v_add_u32_e32 v48, s59, v166
	v_lshl_add_u64 v[164:165], s[12:13], 0, v[134:135]
	s_mov_b32 m0, s57
	ds_read_b128 v[200:203], v48
	ds_read_b128 v[204:207], v48 offset:1024
	ds_read_b128 v[208:211], v48 offset:2048
	ds_read_b128 v[212:215], v48 offset:3072
	global_load_lds_dwordx4 v[164:165], off
	v_lshl_add_u64 v[172:173], s[12:13], 0, v[130:131]
	s_add_i32 m0, s57, 0x2000
	s_nop 0
	global_load_lds_dwordx4 v[172:173], off
	s_barrier
	s_waitcnt lgkmcnt(3)
	v_mfma_f32_16x16x32_bf16 v[118:121], v[200:203], v[160:163], 0
	s_waitcnt lgkmcnt(1)
	v_mfma_f32_16x16x32_bf16 v[114:117], v[208:211], v[160:163], 0
	v_mfma_f32_16x16x32_bf16 v[102:105], v[200:203], v[176:179], 0
	v_mfma_f32_16x16x32_bf16 v[98:101], v[208:211], v[176:179], 0
	v_mfma_f32_16x16x32_bf16 v[86:89], v[200:203], v[184:187], 0
	v_mfma_f32_16x16x32_bf16 v[82:85], v[208:211], v[184:187], 0
	v_mfma_f32_16x16x32_bf16 v[70:73], v[200:203], v[192:195], 0
	v_mfma_f32_16x16x32_bf16 v[66:69], v[208:211], v[192:195], 0
	v_mfma_f32_16x16x32_bf16 v[118:121], v[204:207], v[168:171], v[118:121]
	s_waitcnt lgkmcnt(0)
	v_mfma_f32_16x16x32_bf16 v[114:117], v[212:215], v[168:171], v[114:117]
	v_mfma_f32_16x16x32_bf16 v[102:105], v[204:207], v[180:183], v[102:105]
	v_mfma_f32_16x16x32_bf16 v[98:101], v[212:215], v[180:183], v[98:101]
	v_mfma_f32_16x16x32_bf16 v[86:89], v[204:207], v[188:191], v[86:89]
	v_mfma_f32_16x16x32_bf16 v[82:85], v[212:215], v[188:191], v[82:85]
	v_mfma_f32_16x16x32_bf16 v[70:73], v[204:207], v[196:199], v[70:73]
	v_mfma_f32_16x16x32_bf16 v[66:69], v[212:215], v[196:199], v[66:69]
	s_mov_b32 m0, s3
	v_lshl_add_u64 v[216:217], s[16:17], 0, v[136:137]
	s_barrier
	ds_read_b128 v[160:163], v167 offset:16384
	ds_read_b128 v[168:171], v167 offset:17408
	ds_read_b128 v[176:179], v167 offset:18432
	ds_read_b128 v[180:183], v167 offset:19456
	ds_read_b128 v[184:187], v167 offset:20480
	ds_read_b128 v[188:191], v167 offset:21504
	ds_read_b128 v[192:195], v167 offset:22528
	ds_read_b128 v[196:199], v167 offset:23552
	global_load_lds_dwordx4 v[216:217], off
	v_lshl_add_u64 v[218:219], s[16:17], 0, v[132:133]
	s_mov_b32 m0, s36
	s_nop 0
	global_load_lds_dwordx4 v[218:219], off
	s_barrier
	s_waitcnt lgkmcnt(7)
	v_mfma_f32_16x16x32_bf16 v[62:65], v[144:147], v[160:163], 0
	v_mfma_f32_16x16x32_bf16 v[58:61], v[152:155], v[160:163], 0
	s_waitcnt lgkmcnt(5)
	v_mfma_f32_16x16x32_bf16 v[44:47], v[144:147], v[176:179], 0
	v_mfma_f32_16x16x32_bf16 v[40:43], v[152:155], v[176:179], 0
	s_waitcnt lgkmcnt(3)
	v_mfma_f32_16x16x32_bf16 v[28:31], v[144:147], v[184:187], 0
	v_mfma_f32_16x16x32_bf16 v[24:27], v[152:155], v[184:187], 0
	s_waitcnt lgkmcnt(1)
	v_mfma_f32_16x16x32_bf16 v[12:15], v[144:147], v[192:195], 0
	v_mfma_f32_16x16x32_bf16 v[8:11], v[152:155], v[192:195], 0
	v_mfma_f32_16x16x32_bf16 v[62:65], v[148:151], v[168:171], v[62:65]
	v_mfma_f32_16x16x32_bf16 v[58:61], v[156:159], v[168:171], v[58:61]
	v_mfma_f32_16x16x32_bf16 v[44:47], v[148:151], v[180:183], v[44:47]
	v_mfma_f32_16x16x32_bf16 v[40:43], v[156:159], v[180:183], v[40:43]
	v_mfma_f32_16x16x32_bf16 v[28:31], v[148:151], v[188:191], v[28:31]
	v_mfma_f32_16x16x32_bf16 v[24:27], v[156:159], v[188:191], v[24:27]
	s_waitcnt lgkmcnt(0)
	v_mfma_f32_16x16x32_bf16 v[12:15], v[148:151], v[196:199], v[12:15]
	v_mfma_f32_16x16x32_bf16 v[8:11], v[156:159], v[196:199], v[8:11]
	s_barrier
; #define PG8_STAGE(bufoff, gbase, voff) do { _Pragma("unroll") for (int _i = 0; _i < 2; ++_i) \
;         __builtin_amdgcn_global_load_lds((const unsigned*)((const char*)(gbase) + (voff)[_i]), (PG8_LAS unsigned*)(lds + (bufoff) + ldsw + _i * 8192), 16, 0, 0); } while (0)
; #define PG8_LDA(dst, b, h) do { _Pragma("unroll") for (int m = 0; m < 4; ++m) _Pragma("unroll") for (int k = 0; k < 2; ++k) dst[m][k] = *(const PG8_LAS bf16x8*)(lds + PG8_SA(b, h) + aoff + m * 2048 + k * 1024); } while (0)
; #define PG8_LDB(dst, b, h) do { _Pragma("unroll") for (int n = 0; n < 2; ++n) _Pragma("unroll") for (int k = 0; k < 2; ++k) dst[n][k] = *(const PG8_LAS bf16x8*)(lds + PG8_SB(b, h) + boff + n * 2048 + k * 1024); } while (0)
; #define PG8_MMA(ai, bj, At, Bt) do { __builtin_amdgcn_s_setprio(1); _Pragma("unroll") for (int m = 0; m < 4; ++m) _Pragma("unroll") for (int n = 0; n < 2; ++n) _Pragma("unroll") for (int k = 0; k < 2; ++k) \
;         acc[ai][bj][m][n] = __builtin_amdgcn_mfma_f32_16x16x32_bf16(Bt[n][k], At[m][k], acc[ai][bj][m][n], 0, 0, 0); __builtin_amdgcn_s_setprio(0); } while (0)
; #define PG8_WAIT_V(n) asm volatile("s_waitcnt vmcnt(" #n ")" ::: "memory")
; #define PG8_WAIT_L(n) asm volatile("s_waitcnt lgkmcnt(" #n ")" ::: "memory")
; #define PG8_BAR __builtin_amdgcn_s_barrier()
; #define PG8_SCHED __builtin_amdgcn_sched_barrier(0)
; template <class Epi, class Sched>
; __device__ __forceinline__ void gemm_phase(PG8_LAS unsigned char* lds, const Gemm g, const Sched& S, const Epi& E) {
;     ...
;             PG8_STAGE(PG8_SB(0, 1), b2 + hstep, voffB);
;             PG8_WAIT_V(6); PG8_BAR; PG8_MMA(1, 1, At, B1); PG8_BAR;
;             PG8_LDB(B0, 1, 0); PG8_SCHED; PG8_LDA(At, 1, 0); PG8_STAGE(PG8_SA(0, 1), a2 + hstep, voffA);
;             PG8_WAIT_L(8); PG8_BAR; PG8_WAIT_L(0); PG8_MMA(0, 0, At, B0); PG8_BAR; PG8_SCHED;
;             PG8_LDB(B1, 1, 1); PG8_STAGE(PG8_SB(1, 0), b3, voffB);
;             PG8_BAR; PG8_WAIT_L(0); PG8_MMA(0, 1, At, B1); PG8_BAR;
;             PG8_LDA(At, 1, 1); PG8_STAGE(PG8_SA(1, 0), a3, voffA);
;             PG8_BAR; PG8_WAIT_L(0); PG8_MMA(1, 0, At, B0); PG8_BAR; PG8_SCHED;
	s_add_u32 s64, s12, 0x40000
	s_addc_u32 s65, s13, 0
	s_add_i32 s57, s59, s34
	v_lshl_add_u64 v[144:145], s[64:65], 0, v[134:135]
	s_mov_b32 m0, s57
	s_nop 0
	global_load_lds_dwordx4 v[144:145], off
	v_lshl_add_u64 v[144:145], s[64:65], 0, v[130:131]
	s_add_i32 m0, s57, 0x2000
	s_nop 0
	global_load_lds_dwordx4 v[144:145], off
	s_waitcnt vmcnt(6)
	s_barrier
	v_mfma_f32_16x16x32_bf16 v[54:57], v[200:203], v[160:163], 0
	v_mfma_f32_16x16x32_bf16 v[50:53], v[208:211], v[160:163], 0
	v_mfma_f32_16x16x32_bf16 v[36:39], v[200:203], v[176:179], 0
	v_mfma_f32_16x16x32_bf16 v[32:35], v[208:211], v[176:179], 0
	v_mfma_f32_16x16x32_bf16 v[20:23], v[200:203], v[184:187], 0
	v_mfma_f32_16x16x32_bf16 v[16:19], v[208:211], v[184:187], 0
	v_mfma_f32_16x16x32_bf16 v[4:7], v[200:203], v[192:195], 0
	v_mfma_f32_16x16x32_bf16 v[0:3], v[208:211], v[192:195], 0
	v_mfma_f32_16x16x32_bf16 v[54:57], v[204:207], v[168:171], v[54:57]
	v_mfma_f32_16x16x32_bf16 v[50:53], v[212:215], v[168:171], v[50:53]
	v_mfma_f32_16x16x32_bf16 v[36:39], v[204:207], v[180:183], v[36:39]
	v_mfma_f32_16x16x32_bf16 v[32:35], v[212:215], v[180:183], v[32:35]
	v_mfma_f32_16x16x32_bf16 v[20:23], v[204:207], v[188:191], v[20:23]
	v_mfma_f32_16x16x32_bf16 v[16:19], v[212:215], v[188:191], v[16:19]
	v_mfma_f32_16x16x32_bf16 v[4:7], v[204:207], v[196:199], v[4:7]
	v_mfma_f32_16x16x32_bf16 v[0:3], v[212:215], v[196:199], v[0:3]
	s_add_i32 s57, 0, 0x18000
	v_add_u32_e32 v48, s57, v166
	s_barrier
	ds_read_b128 v[144:147], v48
	ds_read_b128 v[148:151], v48 offset:1024
	ds_read_b128 v[152:155], v48 offset:2048
	ds_read_b128 v[156:159], v48 offset:3072
	s_add_u32 s16, s16, 0x40000
	s_addc_u32 s17, s17, 0
	s_mov_b32 m0, s37
	v_lshl_add_u64 v[200:201], s[16:17], 0, v[136:137]
	ds_read_b128 v[160:163], v167 offset:32768
	ds_read_b128 v[168:171], v167 offset:33792
	ds_read_b128 v[176:179], v167 offset:34816
	ds_read_b128 v[180:183], v167 offset:35840
	ds_read_b128 v[184:187], v167 offset:36864
	ds_read_b128 v[188:191], v167 offset:37888
	ds_read_b128 v[192:195], v167 offset:38912
	ds_read_b128 v[196:199], v167 offset:39936
	global_load_lds_dwordx4 v[200:201], off
	v_lshl_add_u64 v[200:201], s[16:17], 0, v[132:133]
	s_mov_b32 m0, s38
	s_nop 0
	global_load_lds_dwordx4 v[200:201], off
	s_waitcnt lgkmcnt(8)
	s_barrier
	s_waitcnt lgkmcnt(7)
	v_mfma_f32_16x16x32_bf16 v[126:129], v[144:147], v[160:163], v[126:129]
	v_mfma_f32_16x16x32_bf16 v[122:125], v[152:155], v[160:163], v[122:125]
	s_waitcnt lgkmcnt(5)
	v_mfma_f32_16x16x32_bf16 v[110:113], v[144:147], v[176:179], v[110:113]
	v_mfma_f32_16x16x32_bf16 v[106:109], v[152:155], v[176:179], v[106:109]
	s_waitcnt lgkmcnt(3)
	v_mfma_f32_16x16x32_bf16 v[94:97], v[144:147], v[184:187], v[94:97]
	v_mfma_f32_16x16x32_bf16 v[90:93], v[152:155], v[184:187], v[90:93]
	s_waitcnt lgkmcnt(1)
	v_mfma_f32_16x16x32_bf16 v[78:81], v[144:147], v[192:195], v[78:81]
	v_mfma_f32_16x16x32_bf16 v[74:77], v[152:155], v[192:195], v[74:77]
	v_mfma_f32_16x16x32_bf16 v[126:129], v[148:151], v[168:171], v[126:129]
	v_mfma_f32_16x16x32_bf16 v[122:125], v[156:159], v[168:171], v[122:125]
	v_mfma_f32_16x16x32_bf16 v[110:113], v[148:151], v[180:183], v[110:113]
	v_mfma_f32_16x16x32_bf16 v[106:109], v[156:159], v[180:183], v[106:109]
	v_mfma_f32_16x16x32_bf16 v[94:97], v[148:151], v[188:191], v[94:97]
	v_mfma_f32_16x16x32_bf16 v[90:93], v[156:159], v[188:191], v[90:93]
	s_waitcnt lgkmcnt(0)
	v_mfma_f32_16x16x32_bf16 v[78:81], v[148:151], v[196:199], v[78:81]
	v_mfma_f32_16x16x32_bf16 v[74:77], v[156:159], v[196:199], v[74:77]
	s_barrier
	s_add_i32 s16, 0, 0x1c000
	s_add_i32 s17, s57, s34
	v_add_u32_e32 v48, s16, v166
	v_lshl_add_u64 v[164:165], v[164:165], 0, s[0:1]
	s_mov_b32 m0, s17
	ds_read_b128 v[200:203], v48
	ds_read_b128 v[204:207], v48 offset:1024
	ds_read_b128 v[208:211], v48 offset:2048
	ds_read_b128 v[212:215], v48 offset:3072
	global_load_lds_dwordx4 v[164:165], off
	v_lshl_add_u64 v[164:165], v[172:173], 0, s[0:1]
	s_add_i32 m0, s17, 0x2000
	s_nop 0
	global_load_lds_dwordx4 v[164:165], off
	s_barrier
	s_waitcnt lgkmcnt(3)
	v_mfma_f32_16x16x32_bf16 v[118:121], v[200:203], v[160:163], v[118:121]
	s_waitcnt lgkmcnt(1)
	v_mfma_f32_16x16x32_bf16 v[114:117], v[208:211], v[160:163], v[114:117]
	v_mfma_f32_16x16x32_bf16 v[102:105], v[200:203], v[176:179], v[102:105]
	v_mfma_f32_16x16x32_bf16 v[98:101], v[208:211], v[176:179], v[98:101]
	v_mfma_f32_16x16x32_bf16 v[86:89], v[200:203], v[184:187], v[86:89]
	v_mfma_f32_16x16x32_bf16 v[82:85], v[208:211], v[184:187], v[82:85]
	v_mfma_f32_16x16x32_bf16 v[70:73], v[200:203], v[192:195], v[70:73]
	v_mfma_f32_16x16x32_bf16 v[66:69], v[208:211], v[192:195], v[66:69]
	v_mfma_f32_16x16x32_bf16 v[118:121], v[204:207], v[168:171], v[118:121]
	s_waitcnt lgkmcnt(0)
	v_mfma_f32_16x16x32_bf16 v[114:117], v[212:215], v[168:171], v[114:117]
	v_mfma_f32_16x16x32_bf16 v[102:105], v[204:207], v[180:183], v[102:105]
	v_mfma_f32_16x16x32_bf16 v[98:101], v[212:215], v[180:183], v[98:101]
	v_mfma_f32_16x16x32_bf16 v[86:89], v[204:207], v[188:191], v[86:89]
	v_mfma_f32_16x16x32_bf16 v[82:85], v[212:215], v[188:191], v[82:85]
	v_mfma_f32_16x16x32_bf16 v[70:73], v[204:207], v[196:199], v[70:73]
	v_mfma_f32_16x16x32_bf16 v[66:69], v[212:215], v[196:199], v[66:69]
	s_mov_b32 m0, s39
	v_lshl_add_u64 v[164:165], v[216:217], 0, s[0:1]
	s_barrier
	ds_read_b128 v[160:163], v167 offset:49152
	ds_read_b128 v[168:171], v167 offset:50176
	ds_read_b128 v[176:179], v167 offset:51200
	ds_read_b128 v[180:183], v167 offset:52224
	ds_read_b128 v[184:187], v167 offset:53248
	ds_read_b128 v[188:191], v167 offset:54272
	ds_read_b128 v[192:195], v167 offset:55296
	ds_read_b128 v[196:199], v167 offset:56320
	global_load_lds_dwordx4 v[164:165], off
	v_lshl_add_u64 v[164:165], v[218:219], 0, s[0:1]
	s_mov_b32 m0, s42
	s_nop 0
	global_load_lds_dwordx4 v[164:165], off
	s_barrier
; #define PG8_STAGE(bufoff, gbase, voff) do { _Pragma("unroll") for (int _i = 0; _i < 2; ++_i) \
;         __builtin_amdgcn_global_load_lds((const unsigned*)((const char*)(gbase) + (voff)[_i]), (PG8_LAS unsigned*)(lds + (bufoff) + ldsw + _i * 8192), 16, 0, 0); } while (0)
; #define PG8_LDA(dst, b, h) do { _Pragma("unroll") for (int m = 0; m < 4; ++m) _Pragma("unroll") for (int k = 0; k < 2; ++k) dst[m][k] = *(const PG8_LAS bf16x8*)(lds + PG8_SA(b, h) + aoff + m * 2048 + k * 1024); } while (0)
; #define PG8_LDB(dst, b, h) do { _Pragma("unroll") for (int n = 0; n < 2; ++n) _Pragma("unroll") for (int k = 0; k < 2; ++k) dst[n][k] = *(const PG8_LAS bf16x8*)(lds + PG8_SB(b, h) + boff + n * 2048 + k * 1024); } while (0)
; #define PG8_MMA(ai, bj, At, Bt) do { __builtin_amdgcn_s_setprio(1); _Pragma("unroll") for (int m = 0; m < 4; ++m) _Pragma("unroll") for (int n = 0; n < 2; ++n) _Pragma("unroll") for (int k = 0; k < 2; ++k) \
;         acc[ai][bj][m][n] = __builtin_amdgcn_mfma_f32_16x16x32_bf16(Bt[n][k], At[m][k], acc[ai][bj][m][n], 0, 0, 0); __builtin_amdgcn_s_setprio(0); } while (0)
; #define PG8_WAIT_V(n) asm volatile("s_waitcnt vmcnt(" #n ")" ::: "memory")
; #define PG8_WAIT_L(n) asm volatile("s_waitcnt lgkmcnt(" #n ")" ::: "memory")
; #define PG8_BAR __builtin_amdgcn_s_barrier()
; #define PG8_SCHED __builtin_amdgcn_sched_barrier(0)
; template <class Epi, class Sched>
; __device__ __forceinline__ void gemm_phase(PG8_LAS unsigned char* lds, const Gemm g, const Sched& S, const Epi& E) {
;     ...
;             const char* a1 = cA + (size_t)(t + 1) * kstep;
;             const char* a2 = last ? nA : cA + (size_t)(t + 2) * kstep; const char* b2 = last ? nB : cB + (size_t)(t + 2) * kstep;
;             const char* a3 = a2 + kstep; const char* b3 = b2 + kstep;
;             if (last && has_next) S.a_ready(nxt);
;             PG8_LDB(B0, 0, 0); PG8_SCHED; PG8_LDA(At, 0, 0); PG8_STAGE(PG8_SA(1, 1), a1 + hstep, voffA);
;             PG8_WAIT_L(8); PG8_BAR; PG8_WAIT_L(0); PG8_MMA(0, 0, At, B0); PG8_BAR; PG8_SCHED;
;     ...
;             PG8_BAR; PG8_WAIT_L(0); PG8_MMA(1, 0, At, B0); PG8_BAR; PG8_SCHED;
;             PG8_STAGE(PG8_SB(1, 1), b3 + hstep, voffB);
;             PG8_WAIT_V(6); PG8_BAR; PG8_MMA(1, 1, At, B1); PG8_BAR;
	s_waitcnt lgkmcnt(7)
	v_mfma_f32_16x16x32_bf16 v[62:65], v[144:147], v[160:163], v[62:65]
	v_mfma_f32_16x16x32_bf16 v[58:61], v[152:155], v[160:163], v[58:61]
	s_waitcnt lgkmcnt(5)
	v_mfma_f32_16x16x32_bf16 v[44:47], v[144:147], v[176:179], v[44:47]
	v_mfma_f32_16x16x32_bf16 v[40:43], v[152:155], v[176:179], v[40:43]
	s_waitcnt lgkmcnt(3)
	v_mfma_f32_16x16x32_bf16 v[28:31], v[144:147], v[184:187], v[28:31]
	v_mfma_f32_16x16x32_bf16 v[24:27], v[152:155], v[184:187], v[24:27]
	s_waitcnt lgkmcnt(1)
	v_mfma_f32_16x16x32_bf16 v[12:15], v[144:147], v[192:195], v[12:15]
	v_mfma_f32_16x16x32_bf16 v[8:11], v[152:155], v[192:195], v[8:11]
	v_mfma_f32_16x16x32_bf16 v[62:65], v[148:151], v[168:171], v[62:65]
	v_mfma_f32_16x16x32_bf16 v[58:61], v[156:159], v[168:171], v[58:61]
	v_mfma_f32_16x16x32_bf16 v[44:47], v[148:151], v[180:183], v[44:47]
	v_mfma_f32_16x16x32_bf16 v[40:43], v[156:159], v[180:183], v[40:43]
	v_mfma_f32_16x16x32_bf16 v[28:31], v[148:151], v[188:191], v[28:31]
	v_mfma_f32_16x16x32_bf16 v[24:27], v[156:159], v[188:191], v[24:27]
	s_waitcnt lgkmcnt(0)
	v_mfma_f32_16x16x32_bf16 v[12:15], v[148:151], v[196:199], v[12:15]
	v_mfma_f32_16x16x32_bf16 v[8:11], v[156:159], v[196:199], v[8:11]
	s_barrier
	s_add_u32 s12, s12, 0x40080
	s_addc_u32 s13, s13, 0
	s_add_i32 s16, s16, s34
	v_lshl_add_u64 v[144:145], s[12:13], 0, v[134:135]
	s_mov_b32 m0, s16
	s_nop 0
	global_load_lds_dwordx4 v[144:145], off
	v_lshl_add_u64 v[144:145], s[12:13], 0, v[130:131]
	s_add_i32 m0, s16, 0x2000
	s_nop 0
	global_load_lds_dwordx4 v[144:145], off
	s_add_i32 s56, s56, 2
	s_add_u32 s6, s6, 0x100
	s_addc_u32 s7, s7, 0
	s_add_u32 s54, s54, 0x100
	s_addc_u32 s55, s55, 0
	s_cmp_gt_u32 s56, 13
	s_waitcnt vmcnt(6)
	s_barrier
	v_mfma_f32_16x16x32_bf16 v[54:57], v[200:203], v[160:163], v[54:57]
	v_mfma_f32_16x16x32_bf16 v[50:53], v[208:211], v[160:163], v[50:53]
	v_mfma_f32_16x16x32_bf16 v[36:39], v[200:203], v[176:179], v[36:39]
	v_mfma_f32_16x16x32_bf16 v[32:35], v[208:211], v[176:179], v[32:35]
	v_mfma_f32_16x16x32_bf16 v[20:23], v[200:203], v[184:187], v[20:23]
	v_mfma_f32_16x16x32_bf16 v[16:19], v[208:211], v[184:187], v[16:19]
	v_mfma_f32_16x16x32_bf16 v[4:7], v[200:203], v[192:195], v[4:7]
	v_mfma_f32_16x16x32_bf16 v[0:3], v[208:211], v[192:195], v[0:3]
	v_mfma_f32_16x16x32_bf16 v[54:57], v[204:207], v[168:171], v[54:57]
	v_mfma_f32_16x16x32_bf16 v[50:53], v[212:215], v[168:171], v[50:53]
	v_mfma_f32_16x16x32_bf16 v[36:39], v[204:207], v[180:183], v[36:39]
	v_mfma_f32_16x16x32_bf16 v[32:35], v[212:215], v[180:183], v[32:35]
	v_mfma_f32_16x16x32_bf16 v[20:23], v[204:207], v[188:191], v[20:23]
	v_mfma_f32_16x16x32_bf16 v[16:19], v[212:215], v[188:191], v[16:19]
	v_mfma_f32_16x16x32_bf16 v[4:7], v[204:207], v[196:199], v[4:7]
	v_mfma_f32_16x16x32_bf16 v[0:3], v[212:215], v[196:199], v[0:3]
	s_barrier
	s_cbranch_scc1 .Lkpeel_exit_335
.LBB0_335:
	s_add_u32 s12, s6, 0xfffc0080
	s_addc_u32 s13, s7, -1
	s_add_i32 s57, 0, 0x10000
	v_add_u32_e32 v48, s57, v166
	ds_read_b128 v[144:147], v48
	ds_read_b128 v[148:151], v48 offset:1024
	ds_read_b128 v[152:155], v48 offset:2048
	ds_read_b128 v[156:159], v48 offset:3072
	s_cmp_eq_u32 s56, 12
	s_cselect_b32 s17, s23, s13
	s_cselect_b32 s16, s50, s12
	s_cselect_b32 s13, s21, s55
	s_cselect_b32 s12, s51, s54
	v_lshl_add_u64 v[164:165], s[6:7], 0, v[140:141]
	s_add_i32 m0, s3, 0xc000
	ds_read_b128 v[160:163], v167
	ds_read_b128 v[168:171], v167 offset:1024
	ds_read_b128 v[176:179], v167 offset:2048
	ds_read_b128 v[180:183], v167 offset:3072
	ds_read_b128 v[184:187], v167 offset:4096
	ds_read_b128 v[188:191], v167 offset:5120
	ds_read_b128 v[192:195], v167 offset:6144
	ds_read_b128 v[196:199], v167 offset:7168
	global_load_lds_dwordx4 v[164:165], off
	v_lshl_add_u64 v[164:165], s[6:7], 0, v[142:143]
	s_add_i32 m0, s3, 0xe000
	s_nop 0
	global_load_lds_dwordx4 v[164:165], off
	s_waitcnt lgkmcnt(8)
	s_barrier
	s_waitcnt lgkmcnt(7)
	v_mfma_f32_16x16x32_bf16 v[126:129], v[144:147], v[160:163], v[126:129]
	v_mfma_f32_16x16x32_bf16 v[122:125], v[152:155], v[160:163], v[122:125]
	s_waitcnt lgkmcnt(5)
	v_mfma_f32_16x16x32_bf16 v[110:113], v[144:147], v[176:179], v[110:113]
	v_mfma_f32_16x16x32_bf16 v[106:109], v[152:155], v[176:179], v[106:109]
	s_waitcnt lgkmcnt(3)
	v_mfma_f32_16x16x32_bf16 v[94:97], v[144:147], v[184:187], v[94:97]
	v_mfma_f32_16x16x32_bf16 v[90:93], v[152:155], v[184:187], v[90:93]
	s_waitcnt lgkmcnt(1)
	v_mfma_f32_16x16x32_bf16 v[78:81], v[144:147], v[192:195], v[78:81]
	v_mfma_f32_16x16x32_bf16 v[74:77], v[152:155], v[192:195], v[74:77]
	v_mfma_f32_16x16x32_bf16 v[126:129], v[148:151], v[168:171], v[126:129]
	v_mfma_f32_16x16x32_bf16 v[122:125], v[156:159], v[168:171], v[122:125]
	v_mfma_f32_16x16x32_bf16 v[110:113], v[148:151], v[180:183], v[110:113]
	v_mfma_f32_16x16x32_bf16 v[106:109], v[156:159], v[180:183], v[106:109]
	v_mfma_f32_16x16x32_bf16 v[94:97], v[148:151], v[188:191], v[94:97]
	v_mfma_f32_16x16x32_bf16 v[90:93], v[156:159], v[188:191], v[90:93]
	s_waitcnt lgkmcnt(0)
	v_mfma_f32_16x16x32_bf16 v[78:81], v[148:151], v[196:199], v[78:81]
	v_mfma_f32_16x16x32_bf16 v[74:77], v[156:159], v[196:199], v[74:77]
	s_barrier
	s_add_i32 s59, 0, 0x14000
	s_add_i32 s57, s57, s34
	v_add_u32_e32 v48, s59, v166
	v_lshl_add_u64 v[164:165], s[12:13], 0, v[134:135]
	s_mov_b32 m0, s57
	ds_read_b128 v[200:203], v48
	ds_read_b128 v[204:207], v48 offset:1024
	ds_read_b128 v[208:211], v48 offset:2048
	ds_read_b128 v[212:215], v48 offset:3072
	global_load_lds_dwordx4 v[164:165], off
	v_lshl_add_u64 v[172:173], s[12:13], 0, v[130:131]
	s_add_i32 m0, s57, 0x2000
	s_nop 0
	global_load_lds_dwordx4 v[172:173], off
	s_barrier
; #define PG8_STAGE(bufoff, gbase, voff) do { _Pragma("unroll") for (int _i = 0; _i < 2; ++_i) \
;         __builtin_amdgcn_global_load_lds((const unsigned*)((const char*)(gbase) + (voff)[_i]), (PG8_LAS unsigned*)(lds + (bufoff) + ldsw + _i * 8192), 16, 0, 0); } while (0)
; #define PG8_LDA(dst, b, h) do { _Pragma("unroll") for (int m = 0; m < 4; ++m) _Pragma("unroll") for (int k = 0; k < 2; ++k) dst[m][k] = *(const PG8_LAS bf16x8*)(lds + PG8_SA(b, h) + aoff + m * 2048 + k * 1024); } while (0)
; #define PG8_LDB(dst, b, h) do { _Pragma("unroll") for (int n = 0; n < 2; ++n) _Pragma("unroll") for (int k = 0; k < 2; ++k) dst[n][k] = *(const PG8_LAS bf16x8*)(lds + PG8_SB(b, h) + boff + n * 2048 + k * 1024); } while (0)
; #define PG8_MMA(ai, bj, At, Bt) do { __builtin_amdgcn_s_setprio(1); _Pragma("unroll") for (int m = 0; m < 4; ++m) _Pragma("unroll") for (int n = 0; n < 2; ++n) _Pragma("unroll") for (int k = 0; k < 2; ++k) \
;         acc[ai][bj][m][n] = __builtin_amdgcn_mfma_f32_16x16x32_bf16(Bt[n][k], At[m][k], acc[ai][bj][m][n], 0, 0, 0); __builtin_amdgcn_s_setprio(0); } while (0)
; #define PG8_WAIT_V(n) asm volatile("s_waitcnt vmcnt(" #n ")" ::: "memory")
; #define PG8_WAIT_L(n) asm volatile("s_waitcnt lgkmcnt(" #n ")" ::: "memory")
; #define PG8_BAR __builtin_amdgcn_s_barrier()
; #define PG8_SCHED __builtin_amdgcn_sched_barrier(0)
; template <class Epi, class Sched>
; __device__ __forceinline__ void gemm_phase(PG8_LAS unsigned char* lds, const Gemm g, const Sched& S, const Epi& E) {
;     ...
;             PG8_LDB(B1, 0, 1); PG8_STAGE(PG8_SB(0, 0), b2, voffB);
;             PG8_BAR; PG8_WAIT_L(0); PG8_MMA(0, 1, At, B1); PG8_BAR;
;             PG8_LDA(At, 0, 1); PG8_STAGE(PG8_SA(0, 0), a2, voffA);
;             PG8_BAR; PG8_WAIT_L(0); PG8_MMA(1, 0, At, B0); PG8_BAR; PG8_SCHED;
;             PG8_STAGE(PG8_SB(0, 1), b2 + hstep, voffB);
;             PG8_WAIT_V(6); PG8_BAR; PG8_MMA(1, 1, At, B1); PG8_BAR;
;             PG8_LDB(B0, 1, 0); PG8_SCHED; PG8_LDA(At, 1, 0); PG8_STAGE(PG8_SA(0, 1), a2 + hstep, voffA);
;             PG8_WAIT_L(8); PG8_BAR; PG8_WAIT_L(0); PG8_MMA(0, 0, At, B0); PG8_BAR; PG8_SCHED;
	s_waitcnt lgkmcnt(3)
	v_mfma_f32_16x16x32_bf16 v[118:121], v[200:203], v[160:163], v[118:121]
	s_waitcnt lgkmcnt(1)
	v_mfma_f32_16x16x32_bf16 v[114:117], v[208:211], v[160:163], v[114:117]
	v_mfma_f32_16x16x32_bf16 v[102:105], v[200:203], v[176:179], v[102:105]
	v_mfma_f32_16x16x32_bf16 v[98:101], v[208:211], v[176:179], v[98:101]
	v_mfma_f32_16x16x32_bf16 v[86:89], v[200:203], v[184:187], v[86:89]
	v_mfma_f32_16x16x32_bf16 v[82:85], v[208:211], v[184:187], v[82:85]
	v_mfma_f32_16x16x32_bf16 v[70:73], v[200:203], v[192:195], v[70:73]
	v_mfma_f32_16x16x32_bf16 v[66:69], v[208:211], v[192:195], v[66:69]
	v_mfma_f32_16x16x32_bf16 v[118:121], v[204:207], v[168:171], v[118:121]
	s_waitcnt lgkmcnt(0)
	v_mfma_f32_16x16x32_bf16 v[114:117], v[212:215], v[168:171], v[114:117]
	v_mfma_f32_16x16x32_bf16 v[102:105], v[204:207], v[180:183], v[102:105]
	v_mfma_f32_16x16x32_bf16 v[98:101], v[212:215], v[180:183], v[98:101]
	v_mfma_f32_16x16x32_bf16 v[86:89], v[204:207], v[188:191], v[86:89]
	v_mfma_f32_16x16x32_bf16 v[82:85], v[212:215], v[188:191], v[82:85]
	v_mfma_f32_16x16x32_bf16 v[70:73], v[204:207], v[196:199], v[70:73]
	v_mfma_f32_16x16x32_bf16 v[66:69], v[212:215], v[196:199], v[66:69]
	s_mov_b32 m0, s3
	v_lshl_add_u64 v[216:217], s[16:17], 0, v[136:137]
	s_barrier
	ds_read_b128 v[160:163], v167 offset:16384
	ds_read_b128 v[168:171], v167 offset:17408
	ds_read_b128 v[176:179], v167 offset:18432
	ds_read_b128 v[180:183], v167 offset:19456
	ds_read_b128 v[184:187], v167 offset:20480
	ds_read_b128 v[188:191], v167 offset:21504
	ds_read_b128 v[192:195], v167 offset:22528
	ds_read_b128 v[196:199], v167 offset:23552
	global_load_lds_dwordx4 v[216:217], off
	v_lshl_add_u64 v[218:219], s[16:17], 0, v[132:133]
	s_mov_b32 m0, s36
	s_nop 0
	global_load_lds_dwordx4 v[218:219], off
	s_barrier
	s_waitcnt lgkmcnt(7)
	v_mfma_f32_16x16x32_bf16 v[62:65], v[144:147], v[160:163], v[62:65]
	v_mfma_f32_16x16x32_bf16 v[58:61], v[152:155], v[160:163], v[58:61]
	s_waitcnt lgkmcnt(5)
	v_mfma_f32_16x16x32_bf16 v[44:47], v[144:147], v[176:179], v[44:47]
	v_mfma_f32_16x16x32_bf16 v[40:43], v[152:155], v[176:179], v[40:43]
	s_waitcnt lgkmcnt(3)
	v_mfma_f32_16x16x32_bf16 v[28:31], v[144:147], v[184:187], v[28:31]
	v_mfma_f32_16x16x32_bf16 v[24:27], v[152:155], v[184:187], v[24:27]
	s_waitcnt lgkmcnt(1)
	v_mfma_f32_16x16x32_bf16 v[12:15], v[144:147], v[192:195], v[12:15]
	v_mfma_f32_16x16x32_bf16 v[8:11], v[152:155], v[192:195], v[8:11]
	v_mfma_f32_16x16x32_bf16 v[62:65], v[148:151], v[168:171], v[62:65]
	v_mfma_f32_16x16x32_bf16 v[58:61], v[156:159], v[168:171], v[58:61]
	v_mfma_f32_16x16x32_bf16 v[44:47], v[148:151], v[180:183], v[44:47]
	v_mfma_f32_16x16x32_bf16 v[40:43], v[156:159], v[180:183], v[40:43]
	v_mfma_f32_16x16x32_bf16 v[28:31], v[148:151], v[188:191], v[28:31]
	v_mfma_f32_16x16x32_bf16 v[24:27], v[156:159], v[188:191], v[24:27]
	s_waitcnt lgkmcnt(0)
	v_mfma_f32_16x16x32_bf16 v[12:15], v[148:151], v[196:199], v[12:15]
	v_mfma_f32_16x16x32_bf16 v[8:11], v[156:159], v[196:199], v[8:11]
	s_barrier
	s_add_u32 s64, s12, 0x40000
	s_addc_u32 s65, s13, 0
	s_add_i32 s57, s59, s34
	v_lshl_add_u64 v[144:145], s[64:65], 0, v[134:135]
	s_mov_b32 m0, s57
	s_nop 0
	global_load_lds_dwordx4 v[144:145], off
	v_lshl_add_u64 v[144:145], s[64:65], 0, v[130:131]
	s_add_i32 m0, s57, 0x2000
	s_nop 0
	global_load_lds_dwordx4 v[144:145], off
	s_waitcnt vmcnt(6)
	s_barrier
	v_mfma_f32_16x16x32_bf16 v[54:57], v[200:203], v[160:163], v[54:57]
	v_mfma_f32_16x16x32_bf16 v[50:53], v[208:211], v[160:163], v[50:53]
	v_mfma_f32_16x16x32_bf16 v[36:39], v[200:203], v[176:179], v[36:39]
	v_mfma_f32_16x16x32_bf16 v[32:35], v[208:211], v[176:179], v[32:35]
	v_mfma_f32_16x16x32_bf16 v[20:23], v[200:203], v[184:187], v[20:23]
	v_mfma_f32_16x16x32_bf16 v[16:19], v[208:211], v[184:187], v[16:19]
	v_mfma_f32_16x16x32_bf16 v[4:7], v[200:203], v[192:195], v[4:7]
	v_mfma_f32_16x16x32_bf16 v[0:3], v[208:211], v[192:195], v[0:3]
	v_mfma_f32_16x16x32_bf16 v[54:57], v[204:207], v[168:171], v[54:57]
	v_mfma_f32_16x16x32_bf16 v[50:53], v[212:215], v[168:171], v[50:53]
	v_mfma_f32_16x16x32_bf16 v[36:39], v[204:207], v[180:183], v[36:39]
	v_mfma_f32_16x16x32_bf16 v[32:35], v[212:215], v[180:183], v[32:35]
	v_mfma_f32_16x16x32_bf16 v[20:23], v[204:207], v[188:191], v[20:23]
	v_mfma_f32_16x16x32_bf16 v[16:19], v[212:215], v[188:191], v[16:19]
	v_mfma_f32_16x16x32_bf16 v[4:7], v[204:207], v[196:199], v[4:7]
	v_mfma_f32_16x16x32_bf16 v[0:3], v[212:215], v[196:199], v[0:3]
	s_add_i32 s57, 0, 0x18000
	v_add_u32_e32 v48, s57, v166
	s_barrier
	ds_read_b128 v[144:147], v48
	ds_read_b128 v[148:151], v48 offset:1024
	ds_read_b128 v[152:155], v48 offset:2048
	ds_read_b128 v[156:159], v48 offset:3072
	s_add_u32 s16, s16, 0x40000
	s_addc_u32 s17, s17, 0
	s_mov_b32 m0, s37
	v_lshl_add_u64 v[200:201], s[16:17], 0, v[136:137]
	ds_read_b128 v[160:163], v167 offset:32768
	ds_read_b128 v[168:171], v167 offset:33792
	ds_read_b128 v[176:179], v167 offset:34816
	ds_read_b128 v[180:183], v167 offset:35840
	ds_read_b128 v[184:187], v167 offset:36864
	ds_read_b128 v[188:191], v167 offset:37888
	ds_read_b128 v[192:195], v167 offset:38912
	ds_read_b128 v[196:199], v167 offset:39936
	global_load_lds_dwordx4 v[200:201], off
	v_lshl_add_u64 v[200:201], s[16:17], 0, v[132:133]
	s_mov_b32 m0, s38
	s_nop 0
	global_load_lds_dwordx4 v[200:201], off
	s_waitcnt lgkmcnt(8)
	s_barrier
; #define PG8_STAGE(bufoff, gbase, voff) do { _Pragma("unroll") for (int _i = 0; _i < 2; ++_i) \
;         __builtin_amdgcn_global_load_lds((const unsigned*)((const char*)(gbase) + (voff)[_i]), (PG8_LAS unsigned*)(lds + (bufoff) + ldsw + _i * 8192), 16, 0, 0); } while (0)
; #define PG8_LDA(dst, b, h) do { _Pragma("unroll") for (int m = 0; m < 4; ++m) _Pragma("unroll") for (int k = 0; k < 2; ++k) dst[m][k] = *(const PG8_LAS bf16x8*)(lds + PG8_SA(b, h) + aoff + m * 2048 + k * 1024); } while (0)
; #define PG8_LDB(dst, b, h) do { _Pragma("unroll") for (int n = 0; n < 2; ++n) _Pragma("unroll") for (int k = 0; k < 2; ++k) dst[n][k] = *(const PG8_LAS bf16x8*)(lds + PG8_SB(b, h) + boff + n * 2048 + k * 1024); } while (0)
; #define PG8_MMA(ai, bj, At, Bt) do { __builtin_amdgcn_s_setprio(1); _Pragma("unroll") for (int m = 0; m < 4; ++m) _Pragma("unroll") for (int n = 0; n < 2; ++n) _Pragma("unroll") for (int k = 0; k < 2; ++k) \
;         acc[ai][bj][m][n] = __builtin_amdgcn_mfma_f32_16x16x32_bf16(Bt[n][k], At[m][k], acc[ai][bj][m][n], 0, 0, 0); __builtin_amdgcn_s_setprio(0); } while (0)
; #define PG8_WAIT_V(n) asm volatile("s_waitcnt vmcnt(" #n ")" ::: "memory")
; #define PG8_WAIT_L(n) asm volatile("s_waitcnt lgkmcnt(" #n ")" ::: "memory")
; #define PG8_BAR __builtin_amdgcn_s_barrier()
; #define PG8_SCHED __builtin_amdgcn_sched_barrier(0)
; template <class Epi, class Sched>
; __device__ __forceinline__ void gemm_phase(PG8_LAS unsigned char* lds, const Gemm g, const Sched& S, const Epi& E) {
;     ...
;             PG8_WAIT_L(8); PG8_BAR; PG8_WAIT_L(0); PG8_MMA(0, 0, At, B0); PG8_BAR; PG8_SCHED;
;             PG8_LDB(B1, 1, 1); PG8_STAGE(PG8_SB(1, 0), b3, voffB);
;             PG8_BAR; PG8_WAIT_L(0); PG8_MMA(0, 1, At, B1); PG8_BAR;
;             PG8_LDA(At, 1, 1); PG8_STAGE(PG8_SA(1, 0), a3, voffA);
;             PG8_BAR; PG8_WAIT_L(0); PG8_MMA(1, 0, At, B0); PG8_BAR; PG8_SCHED;
;             PG8_STAGE(PG8_SB(1, 1), b3 + hstep, voffB);
;             PG8_WAIT_V(6); PG8_BAR; PG8_MMA(1, 1, At, B1); PG8_BAR;
	s_waitcnt lgkmcnt(7)
	v_mfma_f32_16x16x32_bf16 v[126:129], v[144:147], v[160:163], v[126:129]
	v_mfma_f32_16x16x32_bf16 v[122:125], v[152:155], v[160:163], v[122:125]
	s_waitcnt lgkmcnt(5)
	v_mfma_f32_16x16x32_bf16 v[110:113], v[144:147], v[176:179], v[110:113]
	v_mfma_f32_16x16x32_bf16 v[106:109], v[152:155], v[176:179], v[106:109]
	s_waitcnt lgkmcnt(3)
	v_mfma_f32_16x16x32_bf16 v[94:97], v[144:147], v[184:187], v[94:97]
	v_mfma_f32_16x16x32_bf16 v[90:93], v[152:155], v[184:187], v[90:93]
	s_waitcnt lgkmcnt(1)
	v_mfma_f32_16x16x32_bf16 v[78:81], v[144:147], v[192:195], v[78:81]
	v_mfma_f32_16x16x32_bf16 v[74:77], v[152:155], v[192:195], v[74:77]
	v_mfma_f32_16x16x32_bf16 v[126:129], v[148:151], v[168:171], v[126:129]
	v_mfma_f32_16x16x32_bf16 v[122:125], v[156:159], v[168:171], v[122:125]
	v_mfma_f32_16x16x32_bf16 v[110:113], v[148:151], v[180:183], v[110:113]
	v_mfma_f32_16x16x32_bf16 v[106:109], v[156:159], v[180:183], v[106:109]
	v_mfma_f32_16x16x32_bf16 v[94:97], v[148:151], v[188:191], v[94:97]
	v_mfma_f32_16x16x32_bf16 v[90:93], v[156:159], v[188:191], v[90:93]
	s_waitcnt lgkmcnt(0)
	v_mfma_f32_16x16x32_bf16 v[78:81], v[148:151], v[196:199], v[78:81]
	v_mfma_f32_16x16x32_bf16 v[74:77], v[156:159], v[196:199], v[74:77]
	s_barrier
	s_add_i32 s16, 0, 0x1c000
	s_add_i32 s17, s57, s34
	v_add_u32_e32 v48, s16, v166
	v_lshl_add_u64 v[164:165], v[164:165], 0, s[0:1]
	s_mov_b32 m0, s17
	ds_read_b128 v[200:203], v48
	ds_read_b128 v[204:207], v48 offset:1024
	ds_read_b128 v[208:211], v48 offset:2048
	ds_read_b128 v[212:215], v48 offset:3072
	global_load_lds_dwordx4 v[164:165], off
	v_lshl_add_u64 v[164:165], v[172:173], 0, s[0:1]
	s_add_i32 m0, s17, 0x2000
	s_nop 0
	global_load_lds_dwordx4 v[164:165], off
	s_barrier
	s_waitcnt lgkmcnt(3)
	v_mfma_f32_16x16x32_bf16 v[118:121], v[200:203], v[160:163], v[118:121]
	s_waitcnt lgkmcnt(1)
	v_mfma_f32_16x16x32_bf16 v[114:117], v[208:211], v[160:163], v[114:117]
	v_mfma_f32_16x16x32_bf16 v[102:105], v[200:203], v[176:179], v[102:105]
	v_mfma_f32_16x16x32_bf16 v[98:101], v[208:211], v[176:179], v[98:101]
	v_mfma_f32_16x16x32_bf16 v[86:89], v[200:203], v[184:187], v[86:89]
	v_mfma_f32_16x16x32_bf16 v[82:85], v[208:211], v[184:187], v[82:85]
	v_mfma_f32_16x16x32_bf16 v[70:73], v[200:203], v[192:195], v[70:73]
	v_mfma_f32_16x16x32_bf16 v[66:69], v[208:211], v[192:195], v[66:69]
	v_mfma_f32_16x16x32_bf16 v[118:121], v[204:207], v[168:171], v[118:121]
	s_waitcnt lgkmcnt(0)
	v_mfma_f32_16x16x32_bf16 v[114:117], v[212:215], v[168:171], v[114:117]
	v_mfma_f32_16x16x32_bf16 v[102:105], v[204:207], v[180:183], v[102:105]
	v_mfma_f32_16x16x32_bf16 v[98:101], v[212:215], v[180:183], v[98:101]
	v_mfma_f32_16x16x32_bf16 v[86:89], v[204:207], v[188:191], v[86:89]
	v_mfma_f32_16x16x32_bf16 v[82:85], v[212:215], v[188:191], v[82:85]
	v_mfma_f32_16x16x32_bf16 v[70:73], v[204:207], v[196:199], v[70:73]
	v_mfma_f32_16x16x32_bf16 v[66:69], v[212:215], v[196:199], v[66:69]
	s_mov_b32 m0, s39
	v_lshl_add_u64 v[164:165], v[216:217], 0, s[0:1]
	s_barrier
	ds_read_b128 v[160:163], v167 offset:49152
	ds_read_b128 v[168:171], v167 offset:50176
	ds_read_b128 v[176:179], v167 offset:51200
	ds_read_b128 v[180:183], v167 offset:52224
	ds_read_b128 v[184:187], v167 offset:53248
	ds_read_b128 v[188:191], v167 offset:54272
	ds_read_b128 v[192:195], v167 offset:55296
	ds_read_b128 v[196:199], v167 offset:56320
	global_load_lds_dwordx4 v[164:165], off
	v_lshl_add_u64 v[164:165], v[218:219], 0, s[0:1]
	s_mov_b32 m0, s42
	s_nop 0
	global_load_lds_dwordx4 v[164:165], off
	s_barrier
	s_waitcnt lgkmcnt(7)
	v_mfma_f32_16x16x32_bf16 v[62:65], v[144:147], v[160:163], v[62:65]
	v_mfma_f32_16x16x32_bf16 v[58:61], v[152:155], v[160:163], v[58:61]
	s_waitcnt lgkmcnt(5)
	v_mfma_f32_16x16x32_bf16 v[44:47], v[144:147], v[176:179], v[44:47]
	v_mfma_f32_16x16x32_bf16 v[40:43], v[152:155], v[176:179], v[40:43]
	s_waitcnt lgkmcnt(3)
	v_mfma_f32_16x16x32_bf16 v[28:31], v[144:147], v[184:187], v[28:31]
	v_mfma_f32_16x16x32_bf16 v[24:27], v[152:155], v[184:187], v[24:27]
	s_waitcnt lgkmcnt(1)
	v_mfma_f32_16x16x32_bf16 v[12:15], v[144:147], v[192:195], v[12:15]
	v_mfma_f32_16x16x32_bf16 v[8:11], v[152:155], v[192:195], v[8:11]
	v_mfma_f32_16x16x32_bf16 v[62:65], v[148:151], v[168:171], v[62:65]
	v_mfma_f32_16x16x32_bf16 v[58:61], v[156:159], v[168:171], v[58:61]
	v_mfma_f32_16x16x32_bf16 v[44:47], v[148:151], v[180:183], v[44:47]
	v_mfma_f32_16x16x32_bf16 v[40:43], v[156:159], v[180:183], v[40:43]
	v_mfma_f32_16x16x32_bf16 v[28:31], v[148:151], v[188:191], v[28:31]
	v_mfma_f32_16x16x32_bf16 v[24:27], v[156:159], v[188:191], v[24:27]
	s_waitcnt lgkmcnt(0)
	v_mfma_f32_16x16x32_bf16 v[12:15], v[148:151], v[196:199], v[12:15]
	v_mfma_f32_16x16x32_bf16 v[8:11], v[156:159], v[196:199], v[8:11]
	s_barrier
	s_add_u32 s12, s12, 0x40080
	s_addc_u32 s13, s13, 0
	s_add_i32 s16, s16, s34
	v_lshl_add_u64 v[144:145], s[12:13], 0, v[134:135]
	s_mov_b32 m0, s16
	s_nop 0
	global_load_lds_dwordx4 v[144:145], off
	v_lshl_add_u64 v[144:145], s[12:13], 0, v[130:131]
	s_add_i32 m0, s16, 0x2000
	s_nop 0
	global_load_lds_dwordx4 v[144:145], off
	s_add_i32 s56, s56, 2
	s_add_u32 s6, s6, 0x100
	s_addc_u32 s7, s7, 0
	s_add_u32 s54, s54, 0x100
	s_addc_u32 s55, s55, 0
	s_cmp_gt_u32 s56, 13
	s_waitcnt vmcnt(6)
	s_barrier
	v_mfma_f32_16x16x32_bf16 v[54:57], v[200:203], v[160:163], v[54:57]
	v_mfma_f32_16x16x32_bf16 v[50:53], v[208:211], v[160:163], v[50:53]
	v_mfma_f32_16x16x32_bf16 v[36:39], v[200:203], v[176:179], v[36:39]
	v_mfma_f32_16x16x32_bf16 v[32:35], v[208:211], v[176:179], v[32:35]
	v_mfma_f32_16x16x32_bf16 v[20:23], v[200:203], v[184:187], v[20:23]
	v_mfma_f32_16x16x32_bf16 v[16:19], v[208:211], v[184:187], v[16:19]
	v_mfma_f32_16x16x32_bf16 v[4:7], v[200:203], v[192:195], v[4:7]
	v_mfma_f32_16x16x32_bf16 v[0:3], v[208:211], v[192:195], v[0:3]
	v_mfma_f32_16x16x32_bf16 v[54:57], v[204:207], v[168:171], v[54:57]
	v_mfma_f32_16x16x32_bf16 v[50:53], v[212:215], v[168:171], v[50:53]
	v_mfma_f32_16x16x32_bf16 v[36:39], v[204:207], v[180:183], v[36:39]
	v_mfma_f32_16x16x32_bf16 v[32:35], v[212:215], v[180:183], v[32:35]
	v_mfma_f32_16x16x32_bf16 v[20:23], v[204:207], v[188:191], v[20:23]
	v_mfma_f32_16x16x32_bf16 v[16:19], v[212:215], v[188:191], v[16:19]
	v_mfma_f32_16x16x32_bf16 v[4:7], v[204:207], v[196:199], v[4:7]
	v_mfma_f32_16x16x32_bf16 v[0:3], v[212:215], v[196:199], v[0:3]
	s_barrier
	s_cbranch_scc0 .LBB0_335

; #define PG8_STAGE(bufoff, gbase, voff) do { _Pragma("unroll") for (int _i = 0; _i < 2; ++_i) \
;         __builtin_amdgcn_global_load_lds((const unsigned*)((const char*)(gbase) + (voff)[_i]), (PG8_LAS unsigned*)(lds + (bufoff) + ldsw + _i * 8192), 16, 0, 0); } while (0)
; #define PG8_LDA(dst, b, h) do { _Pragma("unroll") for (int m = 0; m < 4; ++m) _Pragma("unroll") for (int k = 0; k < 2; ++k) dst[m][k] = *(const PG8_LAS bf16x8*)(lds + PG8_SA(b, h) + aoff + m * 2048 + k * 1024); } while (0)
; #define PG8_LDB(dst, b, h) do { _Pragma("unroll") for (int n = 0; n < 2; ++n) _Pragma("unroll") for (int k = 0; k < 2; ++k) dst[n][k] = *(const PG8_LAS bf16x8*)(lds + PG8_SB(b, h) + boff + n * 2048 + k * 1024); } while (0)
; #define PG8_WAIT_L(n) asm volatile("s_waitcnt lgkmcnt(" #n ")" ::: "memory")
; #define PG8_BAR __builtin_amdgcn_s_barrier()
; #define PG8_SCHED __builtin_amdgcn_sched_barrier(0)
; template <class Epi, class Sched>
; __device__ __forceinline__ void gemm_phase(PG8_LAS unsigned char* lds, const Gemm g, const Sched& S, const Epi& E) {
;     ...
;         const bool has_next = S.next(ui + 1, nxt);
;         const char* nA = has_next ? (const char*)g.A + (size_t)nxt.pm * tstepA + (size_t)nxt.kc * cstep : cA; const char* nB = has_next ? (const char*)g.Bt + (size_t)nxt.pn * tstep + (size_t)nxt.kc * cstep : cB;
;         for (int t = 0; t < nt; t += 2) {
;             const bool last = (t == nt - 2);
;             const char* a1 = cA + (size_t)(t + 1) * kstep;
;             const char* a2 = last ? nA : cA + (size_t)(t + 2) * kstep; const char* b2 = last ? nB : cB + (size_t)(t + 2) * kstep;
;             const char* a3 = a2 + kstep; const char* b3 = b2 + kstep;
;             if (last && has_next) S.a_ready(nxt);
;             PG8_LDB(B0, 0, 0); PG8_SCHED; PG8_LDA(At, 0, 0); PG8_STAGE(PG8_SA(1, 1), a1 + hstep, voffA);
;             PG8_WAIT_L(8); PG8_BAR; PG8_WAIT_L(0); PG8_MMA(0, 0, At, B0); PG8_BAR; PG8_SCHED;
;             PG8_LDB(B1, 0, 1); PG8_STAGE(PG8_SB(0, 0), b2, voffB);
;             PG8_BAR; PG8_WAIT_L(0); PG8_MMA(0, 1, At, B1); PG8_BAR;
;             PG8_LDA(At, 0, 1); PG8_STAGE(PG8_SA(0, 0), a2, voffA);
;             PG8_BAR; PG8_WAIT_L(0); PG8_MMA(1, 0, At, B0); PG8_BAR; PG8_SCHED;
.LBB0_387:
	s_ashr_i32 s39, s38, 31
	s_lshl_b64 s[16:17], s[38:39], 19
	v_readlane_b32 s3, v254, 53
	s_add_u32 s94, s3, s16
	v_readlane_b32 s3, v254, 54
	s_addc_u32 s95, s3, s17
	s_and_b64 s[16:17], s[62:63], exec
	s_cselect_b32 s3, s95, s13
	s_cselect_b32 s26, s94, s12
	s_add_u32 s6, s6, 0x40080
	s_addc_u32 s7, s7, 0
	s_add_u32 s27, s12, 0x100
	s_addc_u32 s29, s13, 0
	s_mov_b32 s30, -2
	s_add_u32 s12, s6, 0xfffc0080
	s_addc_u32 s13, s7, -1
	s_add_i32 s22, 0, 0x10000
	v_add_u32_e32 v48, s22, v250
	ds_read_b128 v[130:133], v48
	ds_read_b128 v[134:137], v48 offset:1024
	ds_read_b128 v[138:141], v48 offset:2048
	ds_read_b128 v[142:145], v48 offset:3072
	s_cmp_eq_u32 s30, 12
	s_cselect_b32 s17, s9, s13
	s_cselect_b32 s16, s8, s12
	s_cselect_b32 s13, s3, s29
	s_cselect_b32 s12, s26, s27
	v_lshl_add_u64 v[192:193], s[6:7], 0, v[184:185]
	s_add_i32 m0, s37, 0xc000
	ds_read_b128 v[146:149], v242
	ds_read_b128 v[150:153], v242 offset:1024
	ds_read_b128 v[154:157], v242 offset:2048
	ds_read_b128 v[158:161], v242 offset:3072
	ds_read_b128 v[162:165], v242 offset:4096
	ds_read_b128 v[166:169], v242 offset:5120
	ds_read_b128 v[170:173], v242 offset:6144
	ds_read_b128 v[188:191], v242 offset:7168
	global_load_lds_dwordx4 v[192:193], off
	v_lshl_add_u64 v[192:193], s[6:7], 0, v[186:187]
	s_add_i32 m0, s37, 0xe000
	s_nop 0
	global_load_lds_dwordx4 v[192:193], off
	s_waitcnt lgkmcnt(8)
	s_barrier
	s_waitcnt lgkmcnt(7)
	v_mfma_f32_16x16x32_bf16 v[126:129], v[130:133], v[146:149], 0
	v_mfma_f32_16x16x32_bf16 v[62:65], v[138:141], v[146:149], 0
	s_waitcnt lgkmcnt(5)
	v_mfma_f32_16x16x32_bf16 v[118:121], v[130:133], v[154:157], 0
	v_mfma_f32_16x16x32_bf16 v[54:57], v[138:141], v[154:157], 0
	s_waitcnt lgkmcnt(3)
	v_mfma_f32_16x16x32_bf16 v[110:113], v[130:133], v[162:165], 0
	v_mfma_f32_16x16x32_bf16 v[44:47], v[138:141], v[162:165], 0
	s_waitcnt lgkmcnt(1)
	v_mfma_f32_16x16x32_bf16 v[102:105], v[130:133], v[170:173], 0
	v_mfma_f32_16x16x32_bf16 v[36:39], v[138:141], v[170:173], 0
	v_mfma_f32_16x16x32_bf16 v[126:129], v[134:137], v[150:153], v[126:129]
	v_mfma_f32_16x16x32_bf16 v[62:65], v[142:145], v[150:153], v[62:65]
	v_mfma_f32_16x16x32_bf16 v[118:121], v[134:137], v[158:161], v[118:121]
	v_mfma_f32_16x16x32_bf16 v[54:57], v[142:145], v[158:161], v[54:57]
	v_mfma_f32_16x16x32_bf16 v[110:113], v[134:137], v[166:169], v[110:113]
	v_mfma_f32_16x16x32_bf16 v[44:47], v[142:145], v[166:169], v[44:47]
	s_waitcnt lgkmcnt(0)
	v_mfma_f32_16x16x32_bf16 v[102:105], v[134:137], v[188:191], v[102:105]
	v_mfma_f32_16x16x32_bf16 v[36:39], v[142:145], v[188:191], v[36:39]
	s_barrier
	s_add_i32 s31, 0, 0x14000
	s_add_i32 s22, s22, s36
	v_add_u32_e32 v48, s31, v250
	v_lshl_add_u64 v[208:209], s[12:13], 0, v[178:179]
	s_mov_b32 m0, s22
	ds_read_b128 v[192:195], v48
	ds_read_b128 v[196:199], v48 offset:1024
	ds_read_b128 v[200:203], v48 offset:2048
	ds_read_b128 v[204:207], v48 offset:3072
	global_load_lds_dwordx4 v[208:209], off
	v_lshl_add_u64 v[210:211], s[12:13], 0, v[182:183]
	s_add_i32 m0, s22, 0x2000
	s_nop 0
	global_load_lds_dwordx4 v[210:211], off
	s_barrier
	s_waitcnt lgkmcnt(3)
	v_mfma_f32_16x16x32_bf16 v[122:125], v[192:195], v[146:149], 0
	s_waitcnt lgkmcnt(1)
	v_mfma_f32_16x16x32_bf16 v[58:61], v[200:203], v[146:149], 0
	v_mfma_f32_16x16x32_bf16 v[114:117], v[192:195], v[154:157], 0
	v_mfma_f32_16x16x32_bf16 v[50:53], v[200:203], v[154:157], 0
	v_mfma_f32_16x16x32_bf16 v[106:109], v[192:195], v[162:165], 0
	v_mfma_f32_16x16x32_bf16 v[40:43], v[200:203], v[162:165], 0
	v_mfma_f32_16x16x32_bf16 v[98:101], v[192:195], v[170:173], 0
	v_mfma_f32_16x16x32_bf16 v[32:35], v[200:203], v[170:173], 0
	v_mfma_f32_16x16x32_bf16 v[122:125], v[196:199], v[150:153], v[122:125]
	s_waitcnt lgkmcnt(0)
	v_mfma_f32_16x16x32_bf16 v[58:61], v[204:207], v[150:153], v[58:61]
	v_mfma_f32_16x16x32_bf16 v[114:117], v[196:199], v[158:161], v[114:117]
	v_mfma_f32_16x16x32_bf16 v[50:53], v[204:207], v[158:161], v[50:53]
	v_mfma_f32_16x16x32_bf16 v[106:109], v[196:199], v[166:169], v[106:109]
	v_mfma_f32_16x16x32_bf16 v[40:43], v[204:207], v[166:169], v[40:43]
	v_mfma_f32_16x16x32_bf16 v[98:101], v[196:199], v[188:191], v[98:101]
	v_mfma_f32_16x16x32_bf16 v[32:35], v[204:207], v[188:191], v[32:35]
	s_mov_b32 m0, s37
	v_lshl_add_u64 v[212:213], s[16:17], 0, v[176:177]
	s_barrier
	ds_read_b128 v[146:149], v242 offset:16384
	ds_read_b128 v[150:153], v242 offset:17408
	ds_read_b128 v[154:157], v242 offset:18432
	ds_read_b128 v[158:161], v242 offset:19456
	ds_read_b128 v[162:165], v242 offset:20480
	ds_read_b128 v[166:169], v242 offset:21504
	ds_read_b128 v[170:173], v242 offset:22528
	ds_read_b128 v[188:191], v242 offset:23552
	global_load_lds_dwordx4 v[212:213], off
	v_lshl_add_u64 v[214:215], s[16:17], 0, v[180:181]
	s_mov_b32 m0, s10
	s_nop 0
	global_load_lds_dwordx4 v[214:215], off
	s_barrier
	s_waitcnt lgkmcnt(7)
	v_mfma_f32_16x16x32_bf16 v[94:97], v[130:133], v[146:149], 0
	v_mfma_f32_16x16x32_bf16 v[28:31], v[138:141], v[146:149], 0
	s_waitcnt lgkmcnt(5)
	v_mfma_f32_16x16x32_bf16 v[86:89], v[130:133], v[154:157], 0
	v_mfma_f32_16x16x32_bf16 v[20:23], v[138:141], v[154:157], 0
	s_waitcnt lgkmcnt(3)
	v_mfma_f32_16x16x32_bf16 v[78:81], v[130:133], v[162:165], 0
	v_mfma_f32_16x16x32_bf16 v[12:15], v[138:141], v[162:165], 0
	s_waitcnt lgkmcnt(1)
	v_mfma_f32_16x16x32_bf16 v[70:73], v[130:133], v[170:173], 0
	v_mfma_f32_16x16x32_bf16 v[4:7], v[138:141], v[170:173], 0
	v_mfma_f32_16x16x32_bf16 v[94:97], v[134:137], v[150:153], v[94:97]
	v_mfma_f32_16x16x32_bf16 v[28:31], v[142:145], v[150:153], v[28:31]
	v_mfma_f32_16x16x32_bf16 v[86:89], v[134:137], v[158:161], v[86:89]
	v_mfma_f32_16x16x32_bf16 v[20:23], v[142:145], v[158:161], v[20:23]
	v_mfma_f32_16x16x32_bf16 v[78:81], v[134:137], v[166:169], v[78:81]
	v_mfma_f32_16x16x32_bf16 v[12:15], v[142:145], v[166:169], v[12:15]
	s_waitcnt lgkmcnt(0)
	v_mfma_f32_16x16x32_bf16 v[70:73], v[134:137], v[188:191], v[70:73]
	v_mfma_f32_16x16x32_bf16 v[4:7], v[142:145], v[188:191], v[4:7]
	s_barrier
; #define PG8_STAGE(bufoff, gbase, voff) do { _Pragma("unroll") for (int _i = 0; _i < 2; ++_i) \
;         __builtin_amdgcn_global_load_lds((const unsigned*)((const char*)(gbase) + (voff)[_i]), (PG8_LAS unsigned*)(lds + (bufoff) + ldsw + _i * 8192), 16, 0, 0); } while (0)
; #define PG8_LDA(dst, b, h) do { _Pragma("unroll") for (int m = 0; m < 4; ++m) _Pragma("unroll") for (int k = 0; k < 2; ++k) dst[m][k] = *(const PG8_LAS bf16x8*)(lds + PG8_SA(b, h) + aoff + m * 2048 + k * 1024); } while (0)
; #define PG8_LDB(dst, b, h) do { _Pragma("unroll") for (int n = 0; n < 2; ++n) _Pragma("unroll") for (int k = 0; k < 2; ++k) dst[n][k] = *(const PG8_LAS bf16x8*)(lds + PG8_SB(b, h) + boff + n * 2048 + k * 1024); } while (0)
; #define PG8_MMA(ai, bj, At, Bt) do { __builtin_amdgcn_s_setprio(1); _Pragma("unroll") for (int m = 0; m < 4; ++m) _Pragma("unroll") for (int n = 0; n < 2; ++n) _Pragma("unroll") for (int k = 0; k < 2; ++k) \
;         acc[ai][bj][m][n] = __builtin_amdgcn_mfma_f32_16x16x32_bf16(Bt[n][k], At[m][k], acc[ai][bj][m][n], 0, 0, 0); __builtin_amdgcn_s_setprio(0); } while (0)
; #define PG8_WAIT_V(n) asm volatile("s_waitcnt vmcnt(" #n ")" ::: "memory")
; #define PG8_WAIT_L(n) asm volatile("s_waitcnt lgkmcnt(" #n ")" ::: "memory")
; #define PG8_BAR __builtin_amdgcn_s_barrier()
; #define PG8_SCHED __builtin_amdgcn_sched_barrier(0)
; template <class Epi, class Sched>
; __device__ __forceinline__ void gemm_phase(PG8_LAS unsigned char* lds, const Gemm g, const Sched& S, const Epi& E) {
;     ...
;             PG8_STAGE(PG8_SB(0, 1), b2 + hstep, voffB);
;             PG8_WAIT_V(6); PG8_BAR; PG8_MMA(1, 1, At, B1); PG8_BAR;
;             PG8_LDB(B0, 1, 0); PG8_SCHED; PG8_LDA(At, 1, 0); PG8_STAGE(PG8_SA(0, 1), a2 + hstep, voffA);
;             PG8_WAIT_L(8); PG8_BAR; PG8_WAIT_L(0); PG8_MMA(0, 0, At, B0); PG8_BAR; PG8_SCHED;
;             PG8_LDB(B1, 1, 1); PG8_STAGE(PG8_SB(1, 0), b3, voffB);
;             PG8_BAR; PG8_WAIT_L(0); PG8_MMA(0, 1, At, B1); PG8_BAR;
;             PG8_LDA(At, 1, 1); PG8_STAGE(PG8_SA(1, 0), a3, voffA);
;             PG8_BAR; PG8_WAIT_L(0); PG8_MMA(1, 0, At, B0); PG8_BAR; PG8_SCHED;
	s_add_u32 s22, s12, 0x40000
	s_addc_u32 s23, s13, 0
	s_add_i32 s31, s31, s36
	v_lshl_add_u64 v[130:131], s[22:23], 0, v[178:179]
	s_mov_b32 m0, s31
	s_nop 0
	global_load_lds_dwordx4 v[130:131], off
	v_lshl_add_u64 v[130:131], s[22:23], 0, v[182:183]
	s_add_i32 m0, s31, 0x2000
	s_nop 0
	global_load_lds_dwordx4 v[130:131], off
	s_waitcnt vmcnt(6)
	s_barrier
	v_mfma_f32_16x16x32_bf16 v[90:93], v[192:195], v[146:149], 0
	v_mfma_f32_16x16x32_bf16 v[24:27], v[200:203], v[146:149], 0
	v_mfma_f32_16x16x32_bf16 v[82:85], v[192:195], v[154:157], 0
	v_mfma_f32_16x16x32_bf16 v[16:19], v[200:203], v[154:157], 0
	v_mfma_f32_16x16x32_bf16 v[74:77], v[192:195], v[162:165], 0
	v_mfma_f32_16x16x32_bf16 v[8:11], v[200:203], v[162:165], 0
	v_mfma_f32_16x16x32_bf16 v[66:69], v[192:195], v[170:173], 0
	v_mfma_f32_16x16x32_bf16 v[0:3], v[200:203], v[170:173], 0
	v_mfma_f32_16x16x32_bf16 v[90:93], v[196:199], v[150:153], v[90:93]
	v_mfma_f32_16x16x32_bf16 v[24:27], v[204:207], v[150:153], v[24:27]
	v_mfma_f32_16x16x32_bf16 v[82:85], v[196:199], v[158:161], v[82:85]
	v_mfma_f32_16x16x32_bf16 v[16:19], v[204:207], v[158:161], v[16:19]
	v_mfma_f32_16x16x32_bf16 v[74:77], v[196:199], v[166:169], v[74:77]
	v_mfma_f32_16x16x32_bf16 v[8:11], v[204:207], v[166:169], v[8:11]
	v_mfma_f32_16x16x32_bf16 v[66:69], v[196:199], v[188:191], v[66:69]
	v_mfma_f32_16x16x32_bf16 v[0:3], v[204:207], v[188:191], v[0:3]
	s_add_i32 s22, 0, 0x18000
	v_add_u32_e32 v48, s22, v250
	s_barrier
	ds_read_b128 v[130:133], v48
	ds_read_b128 v[134:137], v48 offset:1024
	ds_read_b128 v[138:141], v48 offset:2048
	ds_read_b128 v[142:145], v48 offset:3072
	s_add_u32 s16, s16, 0x40000
	s_addc_u32 s17, s17, 0
	s_mov_b32 m0, s11
	v_lshl_add_u64 v[192:193], s[16:17], 0, v[176:177]
	ds_read_b128 v[146:149], v242 offset:32768
	ds_read_b128 v[150:153], v242 offset:33792
	ds_read_b128 v[154:157], v242 offset:34816
	ds_read_b128 v[158:161], v242 offset:35840
	ds_read_b128 v[162:165], v242 offset:36864
	ds_read_b128 v[166:169], v242 offset:37888
	ds_read_b128 v[170:173], v242 offset:38912
	ds_read_b128 v[188:191], v242 offset:39936
	global_load_lds_dwordx4 v[192:193], off
	v_lshl_add_u64 v[192:193], s[16:17], 0, v[180:181]
	s_mov_b32 m0, s24
	s_nop 0
	global_load_lds_dwordx4 v[192:193], off
	s_waitcnt lgkmcnt(8)
	s_barrier
	s_waitcnt lgkmcnt(7)
	v_mfma_f32_16x16x32_bf16 v[126:129], v[130:133], v[146:149], v[126:129]
	v_mfma_f32_16x16x32_bf16 v[62:65], v[138:141], v[146:149], v[62:65]
	s_waitcnt lgkmcnt(5)
	v_mfma_f32_16x16x32_bf16 v[118:121], v[130:133], v[154:157], v[118:121]
	v_mfma_f32_16x16x32_bf16 v[54:57], v[138:141], v[154:157], v[54:57]
	s_waitcnt lgkmcnt(3)
	v_mfma_f32_16x16x32_bf16 v[110:113], v[130:133], v[162:165], v[110:113]
	v_mfma_f32_16x16x32_bf16 v[44:47], v[138:141], v[162:165], v[44:47]
	s_waitcnt lgkmcnt(1)
	v_mfma_f32_16x16x32_bf16 v[102:105], v[130:133], v[170:173], v[102:105]
	v_mfma_f32_16x16x32_bf16 v[36:39], v[138:141], v[170:173], v[36:39]
	v_mfma_f32_16x16x32_bf16 v[126:129], v[134:137], v[150:153], v[126:129]
	v_mfma_f32_16x16x32_bf16 v[62:65], v[142:145], v[150:153], v[62:65]
	v_mfma_f32_16x16x32_bf16 v[118:121], v[134:137], v[158:161], v[118:121]
	v_mfma_f32_16x16x32_bf16 v[54:57], v[142:145], v[158:161], v[54:57]
	v_mfma_f32_16x16x32_bf16 v[110:113], v[134:137], v[166:169], v[110:113]
	v_mfma_f32_16x16x32_bf16 v[44:47], v[142:145], v[166:169], v[44:47]
	s_waitcnt lgkmcnt(0)
	v_mfma_f32_16x16x32_bf16 v[102:105], v[134:137], v[188:191], v[102:105]
	v_mfma_f32_16x16x32_bf16 v[36:39], v[142:145], v[188:191], v[36:39]
	s_barrier
	s_add_i32 s16, 0, 0x1c000
	s_add_i32 s17, s22, s36
	v_add_u32_e32 v48, s16, v250
	v_lshl_add_u64 v[208:209], v[208:209], 0, s[0:1]
	s_mov_b32 m0, s17
	ds_read_b128 v[192:195], v48
	ds_read_b128 v[196:199], v48 offset:1024
	ds_read_b128 v[200:203], v48 offset:2048
	ds_read_b128 v[204:207], v48 offset:3072
	global_load_lds_dwordx4 v[208:209], off
	v_lshl_add_u64 v[208:209], v[210:211], 0, s[0:1]
	s_add_i32 m0, s17, 0x2000
	s_nop 0
	global_load_lds_dwordx4 v[208:209], off
	s_barrier
	s_waitcnt lgkmcnt(3)
	v_mfma_f32_16x16x32_bf16 v[122:125], v[192:195], v[146:149], v[122:125]
	s_waitcnt lgkmcnt(1)
	v_mfma_f32_16x16x32_bf16 v[58:61], v[200:203], v[146:149], v[58:61]
	v_mfma_f32_16x16x32_bf16 v[114:117], v[192:195], v[154:157], v[114:117]
	v_mfma_f32_16x16x32_bf16 v[50:53], v[200:203], v[154:157], v[50:53]
	v_mfma_f32_16x16x32_bf16 v[106:109], v[192:195], v[162:165], v[106:109]
	v_mfma_f32_16x16x32_bf16 v[40:43], v[200:203], v[162:165], v[40:43]
	v_mfma_f32_16x16x32_bf16 v[98:101], v[192:195], v[170:173], v[98:101]
	v_mfma_f32_16x16x32_bf16 v[32:35], v[200:203], v[170:173], v[32:35]
	v_mfma_f32_16x16x32_bf16 v[122:125], v[196:199], v[150:153], v[122:125]
	s_waitcnt lgkmcnt(0)
	v_mfma_f32_16x16x32_bf16 v[58:61], v[204:207], v[150:153], v[58:61]
	v_mfma_f32_16x16x32_bf16 v[114:117], v[196:199], v[158:161], v[114:117]
	v_mfma_f32_16x16x32_bf16 v[50:53], v[204:207], v[158:161], v[50:53]
	v_mfma_f32_16x16x32_bf16 v[106:109], v[196:199], v[166:169], v[106:109]
	v_mfma_f32_16x16x32_bf16 v[40:43], v[204:207], v[166:169], v[40:43]
	v_mfma_f32_16x16x32_bf16 v[98:101], v[196:199], v[188:191], v[98:101]
	v_mfma_f32_16x16x32_bf16 v[32:35], v[204:207], v[188:191], v[32:35]
	s_mov_b32 m0, s25
	v_lshl_add_u64 v[208:209], v[212:213], 0, s[0:1]
	s_barrier
	ds_read_b128 v[146:149], v242 offset:49152
	ds_read_b128 v[150:153], v242 offset:50176
	ds_read_b128 v[154:157], v242 offset:51200
	ds_read_b128 v[158:161], v242 offset:52224
	ds_read_b128 v[162:165], v242 offset:53248
	ds_read_b128 v[166:169], v242 offset:54272
	ds_read_b128 v[170:173], v242 offset:55296
	ds_read_b128 v[188:191], v242 offset:56320
	global_load_lds_dwordx4 v[208:209], off
	v_lshl_add_u64 v[208:209], v[214:215], 0, s[0:1]
	s_mov_b32 m0, s18
	s_nop 0
	global_load_lds_dwordx4 v[208:209], off
	s_barrier
; #define PG8_STAGE(bufoff, gbase, voff) do { _Pragma("unroll") for (int _i = 0; _i < 2; ++_i) \
;         __builtin_amdgcn_global_load_lds((const unsigned*)((const char*)(gbase) + (voff)[_i]), (PG8_LAS unsigned*)(lds + (bufoff) + ldsw + _i * 8192), 16, 0, 0); } while (0)
; #define PG8_LDA(dst, b, h) do { _Pragma("unroll") for (int m = 0; m < 4; ++m) _Pragma("unroll") for (int k = 0; k < 2; ++k) dst[m][k] = *(const PG8_LAS bf16x8*)(lds + PG8_SA(b, h) + aoff + m * 2048 + k * 1024); } while (0)
; #define PG8_LDB(dst, b, h) do { _Pragma("unroll") for (int n = 0; n < 2; ++n) _Pragma("unroll") for (int k = 0; k < 2; ++k) dst[n][k] = *(const PG8_LAS bf16x8*)(lds + PG8_SB(b, h) + boff + n * 2048 + k * 1024); } while (0)
; #define PG8_MMA(ai, bj, At, Bt) do { __builtin_amdgcn_s_setprio(1); _Pragma("unroll") for (int m = 0; m < 4; ++m) _Pragma("unroll") for (int n = 0; n < 2; ++n) _Pragma("unroll") for (int k = 0; k < 2; ++k) \
;         acc[ai][bj][m][n] = __builtin_amdgcn_mfma_f32_16x16x32_bf16(Bt[n][k], At[m][k], acc[ai][bj][m][n], 0, 0, 0); __builtin_amdgcn_s_setprio(0); } while (0)
; #define PG8_WAIT_V(n) asm volatile("s_waitcnt vmcnt(" #n ")" ::: "memory")
; #define PG8_WAIT_L(n) asm volatile("s_waitcnt lgkmcnt(" #n ")" ::: "memory")
; #define PG8_BAR __builtin_amdgcn_s_barrier()
; #define PG8_SCHED __builtin_amdgcn_sched_barrier(0)
; template <class Epi, class Sched>
; __device__ __forceinline__ void gemm_phase(PG8_LAS unsigned char* lds, const Gemm g, const Sched& S, const Epi& E) {
;     ...
;             const char* a1 = cA + (size_t)(t + 1) * kstep;
;             const char* a2 = last ? nA : cA + (size_t)(t + 2) * kstep; const char* b2 = last ? nB : cB + (size_t)(t + 2) * kstep;
;             const char* a3 = a2 + kstep; const char* b3 = b2 + kstep;
;             if (last && has_next) S.a_ready(nxt);
;             PG8_LDB(B0, 0, 0); PG8_SCHED; PG8_LDA(At, 0, 0); PG8_STAGE(PG8_SA(1, 1), a1 + hstep, voffA);
;             PG8_WAIT_L(8); PG8_BAR; PG8_WAIT_L(0); PG8_MMA(0, 0, At, B0); PG8_BAR; PG8_SCHED;
;     ...
;             PG8_BAR; PG8_WAIT_L(0); PG8_MMA(1, 0, At, B0); PG8_BAR; PG8_SCHED;
;             PG8_STAGE(PG8_SB(1, 1), b3 + hstep, voffB);
;             PG8_WAIT_V(6); PG8_BAR; PG8_MMA(1, 1, At, B1); PG8_BAR;
	s_waitcnt lgkmcnt(7)
	v_mfma_f32_16x16x32_bf16 v[94:97], v[130:133], v[146:149], v[94:97]
	v_mfma_f32_16x16x32_bf16 v[28:31], v[138:141], v[146:149], v[28:31]
	s_waitcnt lgkmcnt(5)
	v_mfma_f32_16x16x32_bf16 v[86:89], v[130:133], v[154:157], v[86:89]
	v_mfma_f32_16x16x32_bf16 v[20:23], v[138:141], v[154:157], v[20:23]
	s_waitcnt lgkmcnt(3)
	v_mfma_f32_16x16x32_bf16 v[78:81], v[130:133], v[162:165], v[78:81]
	v_mfma_f32_16x16x32_bf16 v[12:15], v[138:141], v[162:165], v[12:15]
	s_waitcnt lgkmcnt(1)
	v_mfma_f32_16x16x32_bf16 v[70:73], v[130:133], v[170:173], v[70:73]
	v_mfma_f32_16x16x32_bf16 v[4:7], v[138:141], v[170:173], v[4:7]
	v_mfma_f32_16x16x32_bf16 v[94:97], v[134:137], v[150:153], v[94:97]
	v_mfma_f32_16x16x32_bf16 v[28:31], v[142:145], v[150:153], v[28:31]
	v_mfma_f32_16x16x32_bf16 v[86:89], v[134:137], v[158:161], v[86:89]
	v_mfma_f32_16x16x32_bf16 v[20:23], v[142:145], v[158:161], v[20:23]
	v_mfma_f32_16x16x32_bf16 v[78:81], v[134:137], v[166:169], v[78:81]
	v_mfma_f32_16x16x32_bf16 v[12:15], v[142:145], v[166:169], v[12:15]
	s_waitcnt lgkmcnt(0)
	v_mfma_f32_16x16x32_bf16 v[70:73], v[134:137], v[188:191], v[70:73]
	v_mfma_f32_16x16x32_bf16 v[4:7], v[142:145], v[188:191], v[4:7]
	s_barrier
	s_add_u32 s12, s12, 0x40080
	s_addc_u32 s13, s13, 0
	s_add_i32 s16, s16, s36
	v_lshl_add_u64 v[130:131], s[12:13], 0, v[178:179]
	s_mov_b32 m0, s16
	s_nop 0
	global_load_lds_dwordx4 v[130:131], off
	v_lshl_add_u64 v[130:131], s[12:13], 0, v[182:183]
	s_add_i32 m0, s16, 0x2000
	s_nop 0
	global_load_lds_dwordx4 v[130:131], off
	s_add_i32 s30, s30, 2
	s_add_u32 s6, s6, 0x100
	s_addc_u32 s7, s7, 0
	s_add_u32 s27, s27, 0x100
	s_addc_u32 s29, s29, 0
	s_cmp_gt_u32 s30, 13
	s_waitcnt vmcnt(6)
	s_barrier
	v_mfma_f32_16x16x32_bf16 v[90:93], v[192:195], v[146:149], v[90:93]
	v_mfma_f32_16x16x32_bf16 v[24:27], v[200:203], v[146:149], v[24:27]
	v_mfma_f32_16x16x32_bf16 v[82:85], v[192:195], v[154:157], v[82:85]
	v_mfma_f32_16x16x32_bf16 v[16:19], v[200:203], v[154:157], v[16:19]
	v_mfma_f32_16x16x32_bf16 v[74:77], v[192:195], v[162:165], v[74:77]
	v_mfma_f32_16x16x32_bf16 v[8:11], v[200:203], v[162:165], v[8:11]
	v_mfma_f32_16x16x32_bf16 v[66:69], v[192:195], v[170:173], v[66:69]
	v_mfma_f32_16x16x32_bf16 v[0:3], v[200:203], v[170:173], v[0:3]
	v_mfma_f32_16x16x32_bf16 v[90:93], v[196:199], v[150:153], v[90:93]
	v_mfma_f32_16x16x32_bf16 v[24:27], v[204:207], v[150:153], v[24:27]
	v_mfma_f32_16x16x32_bf16 v[82:85], v[196:199], v[158:161], v[82:85]
	v_mfma_f32_16x16x32_bf16 v[16:19], v[204:207], v[158:161], v[16:19]
	v_mfma_f32_16x16x32_bf16 v[74:77], v[196:199], v[166:169], v[74:77]
	v_mfma_f32_16x16x32_bf16 v[8:11], v[204:207], v[166:169], v[8:11]
	v_mfma_f32_16x16x32_bf16 v[66:69], v[196:199], v[188:191], v[66:69]
	v_mfma_f32_16x16x32_bf16 v[0:3], v[204:207], v[188:191], v[0:3]
	s_barrier
	s_cbranch_scc1 .Lkpeel_exit_388
.LBB0_388:
	s_add_u32 s12, s6, 0xfffc0080
	s_addc_u32 s13, s7, -1
	s_add_i32 s22, 0, 0x10000
	v_add_u32_e32 v48, s22, v250
	ds_read_b128 v[130:133], v48
	ds_read_b128 v[134:137], v48 offset:1024
	ds_read_b128 v[138:141], v48 offset:2048
	ds_read_b128 v[142:145], v48 offset:3072
	s_cmp_eq_u32 s30, 12
	s_cselect_b32 s17, s9, s13
	s_cselect_b32 s16, s8, s12
	s_cselect_b32 s13, s3, s29
	s_cselect_b32 s12, s26, s27
	v_lshl_add_u64 v[192:193], s[6:7], 0, v[184:185]
	s_add_i32 m0, s37, 0xc000
	ds_read_b128 v[146:149], v242
	ds_read_b128 v[150:153], v242 offset:1024
	ds_read_b128 v[154:157], v242 offset:2048
	ds_read_b128 v[158:161], v242 offset:3072
	ds_read_b128 v[162:165], v242 offset:4096
	ds_read_b128 v[166:169], v242 offset:5120
	ds_read_b128 v[170:173], v242 offset:6144
	ds_read_b128 v[188:191], v242 offset:7168
	global_load_lds_dwordx4 v[192:193], off
	v_lshl_add_u64 v[192:193], s[6:7], 0, v[186:187]
	s_add_i32 m0, s37, 0xe000
	s_nop 0
	global_load_lds_dwordx4 v[192:193], off
	s_waitcnt lgkmcnt(8)
	s_barrier
	s_waitcnt lgkmcnt(7)
	v_mfma_f32_16x16x32_bf16 v[126:129], v[130:133], v[146:149], v[126:129]
	v_mfma_f32_16x16x32_bf16 v[62:65], v[138:141], v[146:149], v[62:65]
	s_waitcnt lgkmcnt(5)
	v_mfma_f32_16x16x32_bf16 v[118:121], v[130:133], v[154:157], v[118:121]
	v_mfma_f32_16x16x32_bf16 v[54:57], v[138:141], v[154:157], v[54:57]
	s_waitcnt lgkmcnt(3)
	v_mfma_f32_16x16x32_bf16 v[110:113], v[130:133], v[162:165], v[110:113]
	v_mfma_f32_16x16x32_bf16 v[44:47], v[138:141], v[162:165], v[44:47]
	s_waitcnt lgkmcnt(1)
	v_mfma_f32_16x16x32_bf16 v[102:105], v[130:133], v[170:173], v[102:105]
	v_mfma_f32_16x16x32_bf16 v[36:39], v[138:141], v[170:173], v[36:39]
	v_mfma_f32_16x16x32_bf16 v[126:129], v[134:137], v[150:153], v[126:129]
	v_mfma_f32_16x16x32_bf16 v[62:65], v[142:145], v[150:153], v[62:65]
	v_mfma_f32_16x16x32_bf16 v[118:121], v[134:137], v[158:161], v[118:121]
	v_mfma_f32_16x16x32_bf16 v[54:57], v[142:145], v[158:161], v[54:57]
	v_mfma_f32_16x16x32_bf16 v[110:113], v[134:137], v[166:169], v[110:113]
	v_mfma_f32_16x16x32_bf16 v[44:47], v[142:145], v[166:169], v[44:47]
	s_waitcnt lgkmcnt(0)
	v_mfma_f32_16x16x32_bf16 v[102:105], v[134:137], v[188:191], v[102:105]
	v_mfma_f32_16x16x32_bf16 v[36:39], v[142:145], v[188:191], v[36:39]
	s_barrier
	s_add_i32 s31, 0, 0x14000
	s_add_i32 s22, s22, s36
	v_add_u32_e32 v48, s31, v250
	v_lshl_add_u64 v[208:209], s[12:13], 0, v[178:179]
	s_mov_b32 m0, s22
	ds_read_b128 v[192:195], v48
	ds_read_b128 v[196:199], v48 offset:1024
	ds_read_b128 v[200:203], v48 offset:2048
	ds_read_b128 v[204:207], v48 offset:3072
	global_load_lds_dwordx4 v[208:209], off
	v_lshl_add_u64 v[210:211], s[12:13], 0, v[182:183]
	s_add_i32 m0, s22, 0x2000
	s_nop 0
	global_load_lds_dwordx4 v[210:211], off
	s_barrier
; #define PG8_STAGE(bufoff, gbase, voff) do { _Pragma("unroll") for (int _i = 0; _i < 2; ++_i) \
;         __builtin_amdgcn_global_load_lds((const unsigned*)((const char*)(gbase) + (voff)[_i]), (PG8_LAS unsigned*)(lds + (bufoff) + ldsw + _i * 8192), 16, 0, 0); } while (0)
; #define PG8_LDA(dst, b, h) do { _Pragma("unroll") for (int m = 0; m < 4; ++m) _Pragma("unroll") for (int k = 0; k < 2; ++k) dst[m][k] = *(const PG8_LAS bf16x8*)(lds + PG8_SA(b, h) + aoff + m * 2048 + k * 1024); } while (0)
; #define PG8_LDB(dst, b, h) do { _Pragma("unroll") for (int n = 0; n < 2; ++n) _Pragma("unroll") for (int k = 0; k < 2; ++k) dst[n][k] = *(const PG8_LAS bf16x8*)(lds + PG8_SB(b, h) + boff + n * 2048 + k * 1024); } while (0)
; #define PG8_MMA(ai, bj, At, Bt) do { __builtin_amdgcn_s_setprio(1); _Pragma("unroll") for (int m = 0; m < 4; ++m) _Pragma("unroll") for (int n = 0; n < 2; ++n) _Pragma("unroll") for (int k = 0; k < 2; ++k) \
;         acc[ai][bj][m][n] = __builtin_amdgcn_mfma_f32_16x16x32_bf16(Bt[n][k], At[m][k], acc[ai][bj][m][n], 0, 0, 0); __builtin_amdgcn_s_setprio(0); } while (0)
; #define PG8_WAIT_V(n) asm volatile("s_waitcnt vmcnt(" #n ")" ::: "memory")
; #define PG8_WAIT_L(n) asm volatile("s_waitcnt lgkmcnt(" #n ")" ::: "memory")
; #define PG8_BAR __builtin_amdgcn_s_barrier()
; #define PG8_SCHED __builtin_amdgcn_sched_barrier(0)
; template <class Epi, class Sched>
; __device__ __forceinline__ void gemm_phase(PG8_LAS unsigned char* lds, const Gemm g, const Sched& S, const Epi& E) {
;     ...
;             PG8_LDB(B1, 0, 1); PG8_STAGE(PG8_SB(0, 0), b2, voffB);
;             PG8_BAR; PG8_WAIT_L(0); PG8_MMA(0, 1, At, B1); PG8_BAR;
;             PG8_LDA(At, 0, 1); PG8_STAGE(PG8_SA(0, 0), a2, voffA);
;             PG8_BAR; PG8_WAIT_L(0); PG8_MMA(1, 0, At, B0); PG8_BAR; PG8_SCHED;
;             PG8_STAGE(PG8_SB(0, 1), b2 + hstep, voffB);
;             PG8_WAIT_V(6); PG8_BAR; PG8_MMA(1, 1, At, B1); PG8_BAR;
;             PG8_LDB(B0, 1, 0); PG8_SCHED; PG8_LDA(At, 1, 0); PG8_STAGE(PG8_SA(0, 1), a2 + hstep, voffA);
;             PG8_WAIT_L(8); PG8_BAR; PG8_WAIT_L(0); PG8_MMA(0, 0, At, B0); PG8_BAR; PG8_SCHED;
	s_waitcnt lgkmcnt(3)
	v_mfma_f32_16x16x32_bf16 v[122:125], v[192:195], v[146:149], v[122:125]
	s_waitcnt lgkmcnt(1)
	v_mfma_f32_16x16x32_bf16 v[58:61], v[200:203], v[146:149], v[58:61]
	v_mfma_f32_16x16x32_bf16 v[114:117], v[192:195], v[154:157], v[114:117]
	v_mfma_f32_16x16x32_bf16 v[50:53], v[200:203], v[154:157], v[50:53]
	v_mfma_f32_16x16x32_bf16 v[106:109], v[192:195], v[162:165], v[106:109]
	v_mfma_f32_16x16x32_bf16 v[40:43], v[200:203], v[162:165], v[40:43]
	v_mfma_f32_16x16x32_bf16 v[98:101], v[192:195], v[170:173], v[98:101]
	v_mfma_f32_16x16x32_bf16 v[32:35], v[200:203], v[170:173], v[32:35]
	v_mfma_f32_16x16x32_bf16 v[122:125], v[196:199], v[150:153], v[122:125]
	s_waitcnt lgkmcnt(0)
	v_mfma_f32_16x16x32_bf16 v[58:61], v[204:207], v[150:153], v[58:61]
	v_mfma_f32_16x16x32_bf16 v[114:117], v[196:199], v[158:161], v[114:117]
	v_mfma_f32_16x16x32_bf16 v[50:53], v[204:207], v[158:161], v[50:53]
	v_mfma_f32_16x16x32_bf16 v[106:109], v[196:199], v[166:169], v[106:109]
	v_mfma_f32_16x16x32_bf16 v[40:43], v[204:207], v[166:169], v[40:43]
	v_mfma_f32_16x16x32_bf16 v[98:101], v[196:199], v[188:191], v[98:101]
	v_mfma_f32_16x16x32_bf16 v[32:35], v[204:207], v[188:191], v[32:35]
	s_mov_b32 m0, s37
	v_lshl_add_u64 v[212:213], s[16:17], 0, v[176:177]
	s_barrier
	ds_read_b128 v[146:149], v242 offset:16384
	ds_read_b128 v[150:153], v242 offset:17408
	ds_read_b128 v[154:157], v242 offset:18432
	ds_read_b128 v[158:161], v242 offset:19456
	ds_read_b128 v[162:165], v242 offset:20480
	ds_read_b128 v[166:169], v242 offset:21504
	ds_read_b128 v[170:173], v242 offset:22528
	ds_read_b128 v[188:191], v242 offset:23552
	global_load_lds_dwordx4 v[212:213], off
	v_lshl_add_u64 v[214:215], s[16:17], 0, v[180:181]
	s_mov_b32 m0, s10
	s_nop 0
	global_load_lds_dwordx4 v[214:215], off
	s_barrier
	s_waitcnt lgkmcnt(7)
	v_mfma_f32_16x16x32_bf16 v[94:97], v[130:133], v[146:149], v[94:97]
	v_mfma_f32_16x16x32_bf16 v[28:31], v[138:141], v[146:149], v[28:31]
	s_waitcnt lgkmcnt(5)
	v_mfma_f32_16x16x32_bf16 v[86:89], v[130:133], v[154:157], v[86:89]
	v_mfma_f32_16x16x32_bf16 v[20:23], v[138:141], v[154:157], v[20:23]
	s_waitcnt lgkmcnt(3)
	v_mfma_f32_16x16x32_bf16 v[78:81], v[130:133], v[162:165], v[78:81]
	v_mfma_f32_16x16x32_bf16 v[12:15], v[138:141], v[162:165], v[12:15]
	s_waitcnt lgkmcnt(1)
	v_mfma_f32_16x16x32_bf16 v[70:73], v[130:133], v[170:173], v[70:73]
	v_mfma_f32_16x16x32_bf16 v[4:7], v[138:141], v[170:173], v[4:7]
	v_mfma_f32_16x16x32_bf16 v[94:97], v[134:137], v[150:153], v[94:97]
	v_mfma_f32_16x16x32_bf16 v[28:31], v[142:145], v[150:153], v[28:31]
	v_mfma_f32_16x16x32_bf16 v[86:89], v[134:137], v[158:161], v[86:89]
	v_mfma_f32_16x16x32_bf16 v[20:23], v[142:145], v[158:161], v[20:23]
	v_mfma_f32_16x16x32_bf16 v[78:81], v[134:137], v[166:169], v[78:81]
	v_mfma_f32_16x16x32_bf16 v[12:15], v[142:145], v[166:169], v[12:15]
	s_waitcnt lgkmcnt(0)
	v_mfma_f32_16x16x32_bf16 v[70:73], v[134:137], v[188:191], v[70:73]
	v_mfma_f32_16x16x32_bf16 v[4:7], v[142:145], v[188:191], v[4:7]
	s_barrier
	s_add_u32 s22, s12, 0x40000
	s_addc_u32 s23, s13, 0
	s_add_i32 s31, s31, s36
	v_lshl_add_u64 v[130:131], s[22:23], 0, v[178:179]
	s_mov_b32 m0, s31
	s_nop 0
	global_load_lds_dwordx4 v[130:131], off
	v_lshl_add_u64 v[130:131], s[22:23], 0, v[182:183]
	s_add_i32 m0, s31, 0x2000
	s_nop 0
	global_load_lds_dwordx4 v[130:131], off
	s_waitcnt vmcnt(6)
	s_barrier
	v_mfma_f32_16x16x32_bf16 v[90:93], v[192:195], v[146:149], v[90:93]
	v_mfma_f32_16x16x32_bf16 v[24:27], v[200:203], v[146:149], v[24:27]
	v_mfma_f32_16x16x32_bf16 v[82:85], v[192:195], v[154:157], v[82:85]
	v_mfma_f32_16x16x32_bf16 v[16:19], v[200:203], v[154:157], v[16:19]
	v_mfma_f32_16x16x32_bf16 v[74:77], v[192:195], v[162:165], v[74:77]
	v_mfma_f32_16x16x32_bf16 v[8:11], v[200:203], v[162:165], v[8:11]
	v_mfma_f32_16x16x32_bf16 v[66:69], v[192:195], v[170:173], v[66:69]
	v_mfma_f32_16x16x32_bf16 v[0:3], v[200:203], v[170:173], v[0:3]
	v_mfma_f32_16x16x32_bf16 v[90:93], v[196:199], v[150:153], v[90:93]
	v_mfma_f32_16x16x32_bf16 v[24:27], v[204:207], v[150:153], v[24:27]
	v_mfma_f32_16x16x32_bf16 v[82:85], v[196:199], v[158:161], v[82:85]
	v_mfma_f32_16x16x32_bf16 v[16:19], v[204:207], v[158:161], v[16:19]
	v_mfma_f32_16x16x32_bf16 v[74:77], v[196:199], v[166:169], v[74:77]
	v_mfma_f32_16x16x32_bf16 v[8:11], v[204:207], v[166:169], v[8:11]
	v_mfma_f32_16x16x32_bf16 v[66:69], v[196:199], v[188:191], v[66:69]
	v_mfma_f32_16x16x32_bf16 v[0:3], v[204:207], v[188:191], v[0:3]
	s_add_i32 s22, 0, 0x18000
	v_add_u32_e32 v48, s22, v250
	s_barrier
	ds_read_b128 v[130:133], v48
	ds_read_b128 v[134:137], v48 offset:1024
	ds_read_b128 v[138:141], v48 offset:2048
	ds_read_b128 v[142:145], v48 offset:3072
	s_add_u32 s16, s16, 0x40000
	s_addc_u32 s17, s17, 0
	s_mov_b32 m0, s11
	v_lshl_add_u64 v[192:193], s[16:17], 0, v[176:177]
	ds_read_b128 v[146:149], v242 offset:32768
	ds_read_b128 v[150:153], v242 offset:33792
	ds_read_b128 v[154:157], v242 offset:34816
	ds_read_b128 v[158:161], v242 offset:35840
	ds_read_b128 v[162:165], v242 offset:36864
	ds_read_b128 v[166:169], v242 offset:37888
	ds_read_b128 v[170:173], v242 offset:38912
	ds_read_b128 v[188:191], v242 offset:39936
	global_load_lds_dwordx4 v[192:193], off
	v_lshl_add_u64 v[192:193], s[16:17], 0, v[180:181]
	s_mov_b32 m0, s24
	s_nop 0
	global_load_lds_dwordx4 v[192:193], off
	s_waitcnt lgkmcnt(8)
	s_barrier
; #define PG8_STAGE(bufoff, gbase, voff) do { _Pragma("unroll") for (int _i = 0; _i < 2; ++_i) \
;         __builtin_amdgcn_global_load_lds((const unsigned*)((const char*)(gbase) + (voff)[_i]), (PG8_LAS unsigned*)(lds + (bufoff) + ldsw + _i * 8192), 16, 0, 0); } while (0)
; #define PG8_LDA(dst, b, h) do { _Pragma("unroll") for (int m = 0; m < 4; ++m) _Pragma("unroll") for (int k = 0; k < 2; ++k) dst[m][k] = *(const PG8_LAS bf16x8*)(lds + PG8_SA(b, h) + aoff + m * 2048 + k * 1024); } while (0)
; #define PG8_LDB(dst, b, h) do { _Pragma("unroll") for (int n = 0; n < 2; ++n) _Pragma("unroll") for (int k = 0; k < 2; ++k) dst[n][k] = *(const PG8_LAS bf16x8*)(lds + PG8_SB(b, h) + boff + n * 2048 + k * 1024); } while (0)
; #define PG8_MMA(ai, bj, At, Bt) do { __builtin_amdgcn_s_setprio(1); _Pragma("unroll") for (int m = 0; m < 4; ++m) _Pragma("unroll") for (int n = 0; n < 2; ++n) _Pragma("unroll") for (int k = 0; k < 2; ++k) \
;         acc[ai][bj][m][n] = __builtin_amdgcn_mfma_f32_16x16x32_bf16(Bt[n][k], At[m][k], acc[ai][bj][m][n], 0, 0, 0); __builtin_amdgcn_s_setprio(0); } while (0)
; #define PG8_WAIT_V(n) asm volatile("s_waitcnt vmcnt(" #n ")" ::: "memory")
; #define PG8_WAIT_L(n) asm volatile("s_waitcnt lgkmcnt(" #n ")" ::: "memory")
; #define PG8_BAR __builtin_amdgcn_s_barrier()
; #define PG8_SCHED __builtin_amdgcn_sched_barrier(0)
; template <class Epi, class Sched>
; __device__ __forceinline__ void gemm_phase(PG8_LAS unsigned char* lds, const Gemm g, const Sched& S, const Epi& E) {
;     ...
;             PG8_WAIT_L(8); PG8_BAR; PG8_WAIT_L(0); PG8_MMA(0, 0, At, B0); PG8_BAR; PG8_SCHED;
;             PG8_LDB(B1, 1, 1); PG8_STAGE(PG8_SB(1, 0), b3, voffB);
;             PG8_BAR; PG8_WAIT_L(0); PG8_MMA(0, 1, At, B1); PG8_BAR;
;             PG8_LDA(At, 1, 1); PG8_STAGE(PG8_SA(1, 0), a3, voffA);
;             PG8_BAR; PG8_WAIT_L(0); PG8_MMA(1, 0, At, B0); PG8_BAR; PG8_SCHED;
;             PG8_STAGE(PG8_SB(1, 1), b3 + hstep, voffB);
;             PG8_WAIT_V(6); PG8_BAR; PG8_MMA(1, 1, At, B1); PG8_BAR;
	s_waitcnt lgkmcnt(7)
	v_mfma_f32_16x16x32_bf16 v[126:129], v[130:133], v[146:149], v[126:129]
	v_mfma_f32_16x16x32_bf16 v[62:65], v[138:141], v[146:149], v[62:65]
	s_waitcnt lgkmcnt(5)
	v_mfma_f32_16x16x32_bf16 v[118:121], v[130:133], v[154:157], v[118:121]
	v_mfma_f32_16x16x32_bf16 v[54:57], v[138:141], v[154:157], v[54:57]
	s_waitcnt lgkmcnt(3)
	v_mfma_f32_16x16x32_bf16 v[110:113], v[130:133], v[162:165], v[110:113]
	v_mfma_f32_16x16x32_bf16 v[44:47], v[138:141], v[162:165], v[44:47]
	s_waitcnt lgkmcnt(1)
	v_mfma_f32_16x16x32_bf16 v[102:105], v[130:133], v[170:173], v[102:105]
	v_mfma_f32_16x16x32_bf16 v[36:39], v[138:141], v[170:173], v[36:39]
	v_mfma_f32_16x16x32_bf16 v[126:129], v[134:137], v[150:153], v[126:129]
	v_mfma_f32_16x16x32_bf16 v[62:65], v[142:145], v[150:153], v[62:65]
	v_mfma_f32_16x16x32_bf16 v[118:121], v[134:137], v[158:161], v[118:121]
	v_mfma_f32_16x16x32_bf16 v[54:57], v[142:145], v[158:161], v[54:57]
	v_mfma_f32_16x16x32_bf16 v[110:113], v[134:137], v[166:169], v[110:113]
	v_mfma_f32_16x16x32_bf16 v[44:47], v[142:145], v[166:169], v[44:47]
	s_waitcnt lgkmcnt(0)
	v_mfma_f32_16x16x32_bf16 v[102:105], v[134:137], v[188:191], v[102:105]
	v_mfma_f32_16x16x32_bf16 v[36:39], v[142:145], v[188:191], v[36:39]
	s_barrier
	s_add_i32 s16, 0, 0x1c000
	s_add_i32 s17, s22, s36
	v_add_u32_e32 v48, s16, v250
	v_lshl_add_u64 v[208:209], v[208:209], 0, s[0:1]
	s_mov_b32 m0, s17
	ds_read_b128 v[192:195], v48
	ds_read_b128 v[196:199], v48 offset:1024
	ds_read_b128 v[200:203], v48 offset:2048
	ds_read_b128 v[204:207], v48 offset:3072
	global_load_lds_dwordx4 v[208:209], off
	v_lshl_add_u64 v[208:209], v[210:211], 0, s[0:1]
	s_add_i32 m0, s17, 0x2000
	s_nop 0
	global_load_lds_dwordx4 v[208:209], off
	s_barrier
	s_waitcnt lgkmcnt(3)
	v_mfma_f32_16x16x32_bf16 v[122:125], v[192:195], v[146:149], v[122:125]
	s_waitcnt lgkmcnt(1)
	v_mfma_f32_16x16x32_bf16 v[58:61], v[200:203], v[146:149], v[58:61]
	v_mfma_f32_16x16x32_bf16 v[114:117], v[192:195], v[154:157], v[114:117]
	v_mfma_f32_16x16x32_bf16 v[50:53], v[200:203], v[154:157], v[50:53]
	v_mfma_f32_16x16x32_bf16 v[106:109], v[192:195], v[162:165], v[106:109]
	v_mfma_f32_16x16x32_bf16 v[40:43], v[200:203], v[162:165], v[40:43]
	v_mfma_f32_16x16x32_bf16 v[98:101], v[192:195], v[170:173], v[98:101]
	v_mfma_f32_16x16x32_bf16 v[32:35], v[200:203], v[170:173], v[32:35]
	v_mfma_f32_16x16x32_bf16 v[122:125], v[196:199], v[150:153], v[122:125]
	s_waitcnt lgkmcnt(0)
	v_mfma_f32_16x16x32_bf16 v[58:61], v[204:207], v[150:153], v[58:61]
	v_mfma_f32_16x16x32_bf16 v[114:117], v[196:199], v[158:161], v[114:117]
	v_mfma_f32_16x16x32_bf16 v[50:53], v[204:207], v[158:161], v[50:53]
	v_mfma_f32_16x16x32_bf16 v[106:109], v[196:199], v[166:169], v[106:109]
	v_mfma_f32_16x16x32_bf16 v[40:43], v[204:207], v[166:169], v[40:43]
	v_mfma_f32_16x16x32_bf16 v[98:101], v[196:199], v[188:191], v[98:101]
	v_mfma_f32_16x16x32_bf16 v[32:35], v[204:207], v[188:191], v[32:35]
	s_mov_b32 m0, s25
	v_lshl_add_u64 v[208:209], v[212:213], 0, s[0:1]
	s_barrier
	ds_read_b128 v[146:149], v242 offset:49152
	ds_read_b128 v[150:153], v242 offset:50176
	ds_read_b128 v[154:157], v242 offset:51200
	ds_read_b128 v[158:161], v242 offset:52224
	ds_read_b128 v[162:165], v242 offset:53248
	ds_read_b128 v[166:169], v242 offset:54272
	ds_read_b128 v[170:173], v242 offset:55296
	ds_read_b128 v[188:191], v242 offset:56320
	global_load_lds_dwordx4 v[208:209], off
	v_lshl_add_u64 v[208:209], v[214:215], 0, s[0:1]
	s_mov_b32 m0, s18
	s_nop 0
	global_load_lds_dwordx4 v[208:209], off
	s_barrier
	s_waitcnt lgkmcnt(7)
	v_mfma_f32_16x16x32_bf16 v[94:97], v[130:133], v[146:149], v[94:97]
	v_mfma_f32_16x16x32_bf16 v[28:31], v[138:141], v[146:149], v[28:31]
	s_waitcnt lgkmcnt(5)
	v_mfma_f32_16x16x32_bf16 v[86:89], v[130:133], v[154:157], v[86:89]
	v_mfma_f32_16x16x32_bf16 v[20:23], v[138:141], v[154:157], v[20:23]
	s_waitcnt lgkmcnt(3)
	v_mfma_f32_16x16x32_bf16 v[78:81], v[130:133], v[162:165], v[78:81]
	v_mfma_f32_16x16x32_bf16 v[12:15], v[138:141], v[162:165], v[12:15]
	s_waitcnt lgkmcnt(1)
	v_mfma_f32_16x16x32_bf16 v[70:73], v[130:133], v[170:173], v[70:73]
	v_mfma_f32_16x16x32_bf16 v[4:7], v[138:141], v[170:173], v[4:7]
	v_mfma_f32_16x16x32_bf16 v[94:97], v[134:137], v[150:153], v[94:97]
	v_mfma_f32_16x16x32_bf16 v[28:31], v[142:145], v[150:153], v[28:31]
	v_mfma_f32_16x16x32_bf16 v[86:89], v[134:137], v[158:161], v[86:89]
	v_mfma_f32_16x16x32_bf16 v[20:23], v[142:145], v[158:161], v[20:23]
	v_mfma_f32_16x16x32_bf16 v[78:81], v[134:137], v[166:169], v[78:81]
	v_mfma_f32_16x16x32_bf16 v[12:15], v[142:145], v[166:169], v[12:15]
	s_waitcnt lgkmcnt(0)
	v_mfma_f32_16x16x32_bf16 v[70:73], v[134:137], v[188:191], v[70:73]
	v_mfma_f32_16x16x32_bf16 v[4:7], v[142:145], v[188:191], v[4:7]
	s_barrier
	s_add_u32 s12, s12, 0x40080
	s_addc_u32 s13, s13, 0
	s_add_i32 s16, s16, s36
	v_lshl_add_u64 v[130:131], s[12:13], 0, v[178:179]
	s_mov_b32 m0, s16
	s_nop 0
	global_load_lds_dwordx4 v[130:131], off
	v_lshl_add_u64 v[130:131], s[12:13], 0, v[182:183]
	s_add_i32 m0, s16, 0x2000
	s_nop 0
	global_load_lds_dwordx4 v[130:131], off
	s_add_i32 s30, s30, 2
	s_add_u32 s6, s6, 0x100
	s_addc_u32 s7, s7, 0
	s_add_u32 s27, s27, 0x100
	s_addc_u32 s29, s29, 0
	s_cmp_gt_u32 s30, 13
	s_waitcnt vmcnt(6)
	s_barrier
	v_mfma_f32_16x16x32_bf16 v[90:93], v[192:195], v[146:149], v[90:93]
	v_mfma_f32_16x16x32_bf16 v[24:27], v[200:203], v[146:149], v[24:27]
	v_mfma_f32_16x16x32_bf16 v[82:85], v[192:195], v[154:157], v[82:85]
	v_mfma_f32_16x16x32_bf16 v[16:19], v[200:203], v[154:157], v[16:19]
	v_mfma_f32_16x16x32_bf16 v[74:77], v[192:195], v[162:165], v[74:77]
	v_mfma_f32_16x16x32_bf16 v[8:11], v[200:203], v[162:165], v[8:11]
	v_mfma_f32_16x16x32_bf16 v[66:69], v[192:195], v[170:173], v[66:69]
	v_mfma_f32_16x16x32_bf16 v[0:3], v[200:203], v[170:173], v[0:3]
	v_mfma_f32_16x16x32_bf16 v[90:93], v[196:199], v[150:153], v[90:93]
	v_mfma_f32_16x16x32_bf16 v[24:27], v[204:207], v[150:153], v[24:27]
	v_mfma_f32_16x16x32_bf16 v[82:85], v[196:199], v[158:161], v[82:85]
	v_mfma_f32_16x16x32_bf16 v[16:19], v[204:207], v[158:161], v[16:19]
	v_mfma_f32_16x16x32_bf16 v[74:77], v[196:199], v[166:169], v[74:77]
	v_mfma_f32_16x16x32_bf16 v[8:11], v[204:207], v[166:169], v[8:11]
	v_mfma_f32_16x16x32_bf16 v[66:69], v[196:199], v[188:191], v[66:69]
	v_mfma_f32_16x16x32_bf16 v[0:3], v[204:207], v[188:191], v[0:3]
	s_barrier
	s_cbranch_scc0 .LBB0_388
